# nt (streaming) output stores in all GEMM epilogues except PP
# baseline (speedup 1.0000x reference)
; __device__ __forceinline__ u32x4 pack8(const f32x4 v0, const f32x4 v1) { u32x4 w; w.x = cvt_pk_bf16(v0[0], v0[1]); w.y = cvt_pk_bf16(v0[2], v0[3]); w.z = cvt_pk_bf16(v1[0], v1[1]); w.w = cvt_pk_bf16(v1[2], v1[3]); return w; }
;     __device__ __forceinline__ bf16_t* dst(const Unit& u, int row, int bj, int wc, int fq, int col0) const {
;         if (u.pn < 2 || u.pn >= 6) return O + (size_t)row * ldc + col0 + bj * HALF;
;         const int b = row >> 11, t = row & 2047;
;         if (u.pn < 4) { const int hc = (u.pn - 2) * 4 + bj * 2 + (wc >> 1), chunk = (wc & 1) * 4 + fq;
;             return KC + (size_t)((b * 8 + hc) * 32 + (t >> 6)) * 4096 + chunk * 512 + (t & 63) * 8; }
;         const int h = (u.pn - 4) * 2 + bj, piece = wc * 4 + ((t & 63) >> 4);
;         return VC + (size_t)((b * 4 + h) * 32 + (t >> 6)) * 8192 + piece * 512 + (t & 15) * 32 + fq * 8;
;     }
;     __device__ __forceinline__ void operator()(const f32x4 (&acc)[2][2][4][2], const Unit& u, int wr, int wc, int fr, int fq) const {
;     ...
; #pragma unroll
;             for (int ai = 0; ai < 2; ++ai)
; #pragma unroll
;                 for (int m = 0; m < 4; ++m) { const int row = row0 + ai * HALF + m * 16; const float r = rs[ai * 4 + m] * sc;
; #pragma unroll
;                     for (int bj = 0; bj < 2; ++bj) *(u32x4*)dst(u, row, bj, wc, fq, col0) = pack8(acc[ai][bj][m][0] * r, acc[ai][bj][m][1] * r); }
.LBB0_160:
	v_mov_b32_e32 v165, v164
	v_lshl_add_u64 v[168:169], v[194:195], 1, v[168:169]
	global_store_dwordx4 v[168:169], v[128:131], off nt
	v_pk_mul_f32 v[168:169], v[116:117], v[164:165]
	v_pk_mul_f32 v[178:179], v[112:113], v[164:165]
	v_mov_b32_e32 v128, v164
	v_mov_b32_e32 v129, v164
	v_cndmask_b32_e64 v165, 0, 1, s[28:29]
	v_pk_mul_f32 v[130:131], v[118:119], v[128:129]
	v_cmp_ne_u32_e64 s[0:1], 1, v165
	s_andn2_b64 vcc, exec, s[28:29]
	s_mov_b64 s[28:29], -1
	v_pk_mul_f32 v[170:171], v[114:115], v[128:129]
	v_cvt_pk_bf16_f32 v128, v168, v169
	v_cvt_pk_bf16_f32 v129, v130, v131
	v_cvt_pk_bf16_f32 v130, v178, v179
	s_nop 0
	v_cvt_pk_bf16_f32 v131, v170, v171
	s_cbranch_vccnz .LBB0_166
	s_cmp_lt_u32 s8, 4
	s_cbranch_scc1 .LBB0_163
	s_lshl_b32 s28, s8, 6
	s_add_i32 s28, s28, s40
	s_addk_i32 s28, 0xff20
	s_ashr_i32 s29, s28, 31
	s_lshl_b64 s[28:29], s[28:29], 14
	s_add_u32 s28, s16, s28
	s_addc_u32 s29, s17, s29
	s_lshl_b32 s41, s31, 1
	s_add_u32 s28, s28, s41
	s_addc_u32 s29, s29, 0
	v_lshlrev_b32_e32 v194, 1, v176
	v_lshl_add_u64 v[168:169], s[28:29], 0, v[194:195]
	s_mov_b64 s[28:29], 0

; __device__ __forceinline__ u32x4 pack8(const f32x4 v0, const f32x4 v1) { u32x4 w; w.x = cvt_pk_bf16(v0[0], v0[1]); w.y = cvt_pk_bf16(v0[2], v0[3]); w.z = cvt_pk_bf16(v1[0], v1[1]); w.w = cvt_pk_bf16(v1[2], v1[3]); return w; }
;     __device__ __forceinline__ bf16_t* dst(const Unit& u, int row, int bj, int wc, int fq, int col0) const {
;         if (u.pn < 2 || u.pn >= 6) return O + (size_t)row * ldc + col0 + bj * HALF;
;         const int b = row >> 11, t = row & 2047;
;         if (u.pn < 4) { const int hc = (u.pn - 2) * 4 + bj * 2 + (wc >> 1), chunk = (wc & 1) * 4 + fq;
;             return KC + (size_t)((b * 8 + hc) * 32 + (t >> 6)) * 4096 + chunk * 512 + (t & 63) * 8; }
;         const int h = (u.pn - 4) * 2 + bj, piece = wc * 4 + ((t & 63) >> 4);
;         return VC + (size_t)((b * 4 + h) * 32 + (t >> 6)) * 8192 + piece * 512 + (t & 15) * 32 + fq * 8;
;     }
;     __device__ __forceinline__ void operator()(const f32x4 (&acc)[2][2][4][2], const Unit& u, int wr, int wc, int fr, int fq) const {
;     ...
; #pragma unroll
;             for (int ai = 0; ai < 2; ++ai)
; #pragma unroll
;                 for (int m = 0; m < 4; ++m) { const int row = row0 + ai * HALF + m * 16; const float r = rs[ai * 4 + m] * sc;
; #pragma unroll
;                     for (int bj = 0; bj < 2; ++bj) *(u32x4*)dst(u, row, bj, wc, fq, col0) = pack8(acc[ai][bj][m][0] * r, acc[ai][bj][m][1] * r); }
.LBB0_168:
	v_lshl_add_u64 v[168:169], v[194:195], 1, v[168:169]
	global_store_dwordx4 v[168:169], v[128:131], off nt
	v_mul_f32_e32 v168, v149, v174
	v_pk_mul_f32 v[170:171], v[106:107], v[168:169] op_sel_hi:[1,0]
	v_lshlrev_b32_e32 v128, 3, v160
	v_and_b32_e32 v165, 0xf8, v128
	v_pk_mul_f32 v[130:131], v[110:111], v[168:169] op_sel_hi:[1,0]
	v_pk_mul_f32 v[128:129], v[108:109], v[168:169] op_sel_hi:[1,0]
	s_and_b64 vcc, exec, s[0:1]
	s_mov_b64 s[28:29], -1
	v_pk_mul_f32 v[178:179], v[104:105], v[168:169] op_sel_hi:[1,0]
	v_cvt_pk_bf16_f32 v128, v128, v129
	v_cvt_pk_bf16_f32 v129, v130, v131
	s_nop 0
	v_cvt_pk_bf16_f32 v130, v178, v179
	v_cvt_pk_bf16_f32 v131, v170, v171
	s_cbranch_vccnz .LBB0_174
	s_cmp_lt_u32 s8, 4
	s_cbranch_scc1 .LBB0_171
	s_lshl_b32 s28, s8, 6
	s_add_i32 s28, s28, s40
	s_addk_i32 s28, 0xff00
	s_ashr_i32 s29, s28, 31
	s_lshl_b64 s[28:29], s[28:29], 14
	s_add_u32 s28, s16, s28
	s_addc_u32 s29, s17, s29
	s_lshl_b32 s41, s31, 1
	s_add_u32 s28, s28, s41
	s_addc_u32 s29, s29, 0
	v_lshlrev_b32_e32 v194, 1, v176
	v_lshl_add_u64 v[170:171], s[28:29], 0, v[194:195]
	s_mov_b64 s[28:29], 0x400
	v_lshl_add_u64 v[170:171], v[170:171], 0, s[28:29]
	s_mov_b64 s[28:29], 0

; __device__ __forceinline__ u32x4 pack8(const f32x4 v0, const f32x4 v1) { u32x4 w; w.x = cvt_pk_bf16(v0[0], v0[1]); w.y = cvt_pk_bf16(v0[2], v0[3]); w.z = cvt_pk_bf16(v1[0], v1[1]); w.w = cvt_pk_bf16(v1[2], v1[3]); return w; }
;     __device__ __forceinline__ bf16_t* dst(const Unit& u, int row, int bj, int wc, int fq, int col0) const {
;         if (u.pn < 2 || u.pn >= 6) return O + (size_t)row * ldc + col0 + bj * HALF;
;         const int b = row >> 11, t = row & 2047;
;         if (u.pn < 4) { const int hc = (u.pn - 2) * 4 + bj * 2 + (wc >> 1), chunk = (wc & 1) * 4 + fq;
;             return KC + (size_t)((b * 8 + hc) * 32 + (t >> 6)) * 4096 + chunk * 512 + (t & 63) * 8; }
;         const int h = (u.pn - 4) * 2 + bj, piece = wc * 4 + ((t & 63) >> 4);
;         return VC + (size_t)((b * 4 + h) * 32 + (t >> 6)) * 8192 + piece * 512 + (t & 15) * 32 + fq * 8;
;     }
;     __device__ __forceinline__ void operator()(const f32x4 (&acc)[2][2][4][2], const Unit& u, int wr, int wc, int fr, int fq) const {
;     ...
; #pragma unroll
;             for (int ai = 0; ai < 2; ++ai)
; #pragma unroll
;                 for (int m = 0; m < 4; ++m) { const int row = row0 + ai * HALF + m * 16; const float r = rs[ai * 4 + m] * sc;
; #pragma unroll
;                     for (int bj = 0; bj < 2; ++bj) *(u32x4*)dst(u, row, bj, wc, fq, col0) = pack8(acc[ai][bj][m][0] * r, acc[ai][bj][m][1] * r); }
.LBB0_176:
	v_lshl_add_u64 v[170:171], v[194:195], 1, v[170:171]
	v_mov_b32_e32 v169, v168
	global_store_dwordx4 v[170:171], v[128:131], off nt
	v_pk_mul_f32 v[170:171], v[100:101], v[168:169]
	s_and_b64 vcc, exec, s[0:1]
	v_mov_b32_e32 v128, v168
	v_mov_b32_e32 v129, v168
	v_pk_mul_f32 v[130:131], v[102:103], v[128:129]
	v_pk_mul_f32 v[168:169], v[96:97], v[168:169]
	s_mov_b64 s[28:29], -1
	v_pk_mul_f32 v[178:179], v[98:99], v[128:129]
	v_cvt_pk_bf16_f32 v128, v170, v171
	v_cvt_pk_bf16_f32 v129, v130, v131
	v_cvt_pk_bf16_f32 v130, v168, v169
	s_nop 0
	v_cvt_pk_bf16_f32 v131, v178, v179
	s_cbranch_vccnz .LBB0_182
	s_cmp_lt_u32 s8, 4
	s_cbranch_scc1 .LBB0_179
	s_lshl_b32 s28, s8, 6
	s_add_i32 s28, s28, s40
	s_addk_i32 s28, 0xff20
	s_ashr_i32 s29, s28, 31
	s_lshl_b64 s[28:29], s[28:29], 14
	s_add_u32 s28, s16, s28
	s_addc_u32 s29, s17, s29
	s_lshl_b32 s41, s31, 1
	s_add_u32 s28, s28, s41
	s_addc_u32 s29, s29, 0
	v_lshlrev_b32_e32 v194, 1, v176
	v_lshl_add_u64 v[168:169], s[28:29], 0, v[194:195]
	s_mov_b64 s[28:29], 0x400
	v_lshl_add_u64 v[168:169], v[168:169], 0, s[28:29]
	s_mov_b64 s[28:29], 0

; __device__ __forceinline__ u32x4 pack8(const f32x4 v0, const f32x4 v1) { u32x4 w; w.x = cvt_pk_bf16(v0[0], v0[1]); w.y = cvt_pk_bf16(v0[2], v0[3]); w.z = cvt_pk_bf16(v1[0], v1[1]); w.w = cvt_pk_bf16(v1[2], v1[3]); return w; }
;     __device__ __forceinline__ bf16_t* dst(const Unit& u, int row, int bj, int wc, int fq, int col0) const {
;         if (u.pn < 2 || u.pn >= 6) return O + (size_t)row * ldc + col0 + bj * HALF;
;         const int b = row >> 11, t = row & 2047;
;         if (u.pn < 4) { const int hc = (u.pn - 2) * 4 + bj * 2 + (wc >> 1), chunk = (wc & 1) * 4 + fq;
;             return KC + (size_t)((b * 8 + hc) * 32 + (t >> 6)) * 4096 + chunk * 512 + (t & 63) * 8; }
;         const int h = (u.pn - 4) * 2 + bj, piece = wc * 4 + ((t & 63) >> 4);
;         return VC + (size_t)((b * 4 + h) * 32 + (t >> 6)) * 8192 + piece * 512 + (t & 15) * 32 + fq * 8;
;     }
;     __device__ __forceinline__ void operator()(const f32x4 (&acc)[2][2][4][2], const Unit& u, int wr, int wc, int fr, int fq) const {
;     ...
; #pragma unroll
;             for (int ai = 0; ai < 2; ++ai)
; #pragma unroll
;                 for (int m = 0; m < 4; ++m) { const int row = row0 + ai * HALF + m * 16; const float r = rs[ai * 4 + m] * sc;
; #pragma unroll
;                     for (int bj = 0; bj < 2; ++bj) *(u32x4*)dst(u, row, bj, wc, fq, col0) = pack8(acc[ai][bj][m][0] * r, acc[ai][bj][m][1] * r); }
.LBB0_184:
	v_lshl_add_u64 v[168:169], v[194:195], 1, v[168:169]
	global_store_dwordx4 v[168:169], v[128:131], off nt
	v_mul_f32_e32 v168, v149, v167
	v_pk_mul_f32 v[170:171], v[90:91], v[168:169] op_sel_hi:[1,0]
	v_lshlrev_b32_e32 v128, 3, v158
	v_and_b32_e32 v165, 0x178, v128
	v_pk_mul_f32 v[130:131], v[94:95], v[168:169] op_sel_hi:[1,0]
	v_pk_mul_f32 v[128:129], v[92:93], v[168:169] op_sel_hi:[1,0]
	s_and_b64 vcc, exec, s[0:1]
	s_mov_b64 s[28:29], -1
	v_pk_mul_f32 v[178:179], v[88:89], v[168:169] op_sel_hi:[1,0]
	v_cvt_pk_bf16_f32 v128, v128, v129
	v_cvt_pk_bf16_f32 v129, v130, v131
	s_nop 0
	v_cvt_pk_bf16_f32 v130, v178, v179
	v_cvt_pk_bf16_f32 v131, v170, v171
	s_cbranch_vccnz .LBB0_190
	s_cmp_lt_u32 s8, 4
	s_cbranch_scc1 .LBB0_187
	s_lshl_b32 s28, s8, 6
	s_add_i32 s28, s28, s40
	s_addk_i32 s28, 0xff00
	s_ashr_i32 s29, s28, 31
	s_lshl_b64 s[28:29], s[28:29], 14
	s_add_u32 s28, s16, s28
	s_addc_u32 s29, s17, s29
	s_lshl_b32 s41, s31, 1
	s_add_u32 s28, s28, s41
	s_addc_u32 s29, s29, 0
	v_lshlrev_b32_e32 v194, 1, v176
	v_lshl_add_u64 v[170:171], s[28:29], 0, v[194:195]
	v_lshl_add_u64 v[170:171], v[170:171], 0, s[78:79]
	s_mov_b64 s[28:29], 0

; __device__ __forceinline__ u32x4 pack8(const f32x4 v0, const f32x4 v1) { u32x4 w; w.x = cvt_pk_bf16(v0[0], v0[1]); w.y = cvt_pk_bf16(v0[2], v0[3]); w.z = cvt_pk_bf16(v1[0], v1[1]); w.w = cvt_pk_bf16(v1[2], v1[3]); return w; }
;     __device__ __forceinline__ bf16_t* dst(const Unit& u, int row, int bj, int wc, int fq, int col0) const {
;         if (u.pn < 2 || u.pn >= 6) return O + (size_t)row * ldc + col0 + bj * HALF;
;         const int b = row >> 11, t = row & 2047;
;         if (u.pn < 4) { const int hc = (u.pn - 2) * 4 + bj * 2 + (wc >> 1), chunk = (wc & 1) * 4 + fq;
;             return KC + (size_t)((b * 8 + hc) * 32 + (t >> 6)) * 4096 + chunk * 512 + (t & 63) * 8; }
;         const int h = (u.pn - 4) * 2 + bj, piece = wc * 4 + ((t & 63) >> 4);
;         return VC + (size_t)((b * 4 + h) * 32 + (t >> 6)) * 8192 + piece * 512 + (t & 15) * 32 + fq * 8;
;     }
;     __device__ __forceinline__ void operator()(const f32x4 (&acc)[2][2][4][2], const Unit& u, int wr, int wc, int fr, int fq) const {
;     ...
; #pragma unroll
;             for (int ai = 0; ai < 2; ++ai)
; #pragma unroll
;                 for (int m = 0; m < 4; ++m) { const int row = row0 + ai * HALF + m * 16; const float r = rs[ai * 4 + m] * sc;
; #pragma unroll
;                     for (int bj = 0; bj < 2; ++bj) *(u32x4*)dst(u, row, bj, wc, fq, col0) = pack8(acc[ai][bj][m][0] * r, acc[ai][bj][m][1] * r); }
.LBB0_192:
	v_lshl_add_u64 v[170:171], v[194:195], 1, v[170:171]
	v_mov_b32_e32 v169, v168
	global_store_dwordx4 v[170:171], v[128:131], off nt
	v_pk_mul_f32 v[170:171], v[84:85], v[168:169]
	s_and_b64 vcc, exec, s[0:1]
	v_mov_b32_e32 v128, v168
	v_mov_b32_e32 v129, v168
	v_pk_mul_f32 v[130:131], v[86:87], v[128:129]
	v_pk_mul_f32 v[168:169], v[80:81], v[168:169]
	s_mov_b64 s[28:29], -1
	v_pk_mul_f32 v[178:179], v[82:83], v[128:129]
	v_cvt_pk_bf16_f32 v128, v170, v171
	v_cvt_pk_bf16_f32 v129, v130, v131
	v_cvt_pk_bf16_f32 v130, v168, v169
	s_nop 0
	v_cvt_pk_bf16_f32 v131, v178, v179
	s_cbranch_vccnz .LBB0_198
	s_cmp_lt_u32 s8, 4
	s_cbranch_scc1 .LBB0_195
	s_lshl_b32 s28, s8, 6
	s_add_i32 s28, s28, s40
	s_addk_i32 s28, 0xff20
	s_ashr_i32 s29, s28, 31
	s_lshl_b64 s[28:29], s[28:29], 14
	s_add_u32 s28, s16, s28
	s_addc_u32 s29, s17, s29
	s_lshl_b32 s41, s31, 1
	s_add_u32 s28, s28, s41
	s_addc_u32 s29, s29, 0
	v_lshlrev_b32_e32 v194, 1, v176
	v_lshl_add_u64 v[168:169], s[28:29], 0, v[194:195]
	v_lshl_add_u64 v[168:169], v[168:169], 0, s[78:79]
	s_mov_b64 s[28:29], 0

; __device__ __forceinline__ u32x4 pack8(const f32x4 v0, const f32x4 v1) { u32x4 w; w.x = cvt_pk_bf16(v0[0], v0[1]); w.y = cvt_pk_bf16(v0[2], v0[3]); w.z = cvt_pk_bf16(v1[0], v1[1]); w.w = cvt_pk_bf16(v1[2], v1[3]); return w; }
;     __device__ __forceinline__ bf16_t* dst(const Unit& u, int row, int bj, int wc, int fq, int col0) const {
;         if (u.pn < 2 || u.pn >= 6) return O + (size_t)row * ldc + col0 + bj * HALF;
;         const int b = row >> 11, t = row & 2047;
;         if (u.pn < 4) { const int hc = (u.pn - 2) * 4 + bj * 2 + (wc >> 1), chunk = (wc & 1) * 4 + fq;
;             return KC + (size_t)((b * 8 + hc) * 32 + (t >> 6)) * 4096 + chunk * 512 + (t & 63) * 8; }
;         const int h = (u.pn - 4) * 2 + bj, piece = wc * 4 + ((t & 63) >> 4);
;         return VC + (size_t)((b * 4 + h) * 32 + (t >> 6)) * 8192 + piece * 512 + (t & 15) * 32 + fq * 8;
;     }
;     __device__ __forceinline__ void operator()(const f32x4 (&acc)[2][2][4][2], const Unit& u, int wr, int wc, int fr, int fq) const {
;     ...
; #pragma unroll
;             for (int ai = 0; ai < 2; ++ai)
; #pragma unroll
;                 for (int m = 0; m < 4; ++m) { const int row = row0 + ai * HALF + m * 16; const float r = rs[ai * 4 + m] * sc;
; #pragma unroll
;                     for (int bj = 0; bj < 2; ++bj) *(u32x4*)dst(u, row, bj, wc, fq, col0) = pack8(acc[ai][bj][m][0] * r, acc[ai][bj][m][1] * r); }
.LBB0_200:
	v_lshl_add_u64 v[168:169], v[194:195], 1, v[168:169]
	global_store_dwordx4 v[168:169], v[128:131], off nt
	v_mul_f32_e32 v168, v149, v161
	v_pk_mul_f32 v[170:171], v[74:75], v[168:169] op_sel_hi:[1,0]
	v_lshlrev_b32_e32 v128, 3, v156
	v_and_b32_e32 v165, 0x1f8, v128
	v_pk_mul_f32 v[130:131], v[78:79], v[168:169] op_sel_hi:[1,0]
	v_pk_mul_f32 v[128:129], v[76:77], v[168:169] op_sel_hi:[1,0]
	s_and_b64 vcc, exec, s[0:1]
	s_mov_b64 s[28:29], -1
	v_pk_mul_f32 v[178:179], v[72:73], v[168:169] op_sel_hi:[1,0]
	v_cvt_pk_bf16_f32 v128, v128, v129
	v_cvt_pk_bf16_f32 v129, v130, v131
	s_nop 0
	v_cvt_pk_bf16_f32 v130, v178, v179
	v_cvt_pk_bf16_f32 v131, v170, v171
	s_cbranch_vccnz .LBB0_206
	s_cmp_lt_u32 s8, 4
	s_cbranch_scc1 .LBB0_203
	s_lshl_b32 s28, s8, 6
	s_add_i32 s28, s28, s40
	s_addk_i32 s28, 0xff00
	s_ashr_i32 s29, s28, 31
	s_lshl_b64 s[28:29], s[28:29], 14
	s_add_u32 s28, s16, s28
	s_addc_u32 s29, s17, s29
	s_lshl_b32 s41, s31, 1
	s_add_u32 s28, s28, s41
	s_addc_u32 s29, s29, 0
	v_lshlrev_b32_e32 v194, 1, v176
	v_lshl_add_u64 v[170:171], s[28:29], 0, v[194:195]
	s_mov_b64 s[28:29], 0xc00
	v_lshl_add_u64 v[170:171], v[170:171], 0, s[28:29]
	s_mov_b64 s[28:29], 0

; __device__ __forceinline__ u32x4 pack8(const f32x4 v0, const f32x4 v1) { u32x4 w; w.x = cvt_pk_bf16(v0[0], v0[1]); w.y = cvt_pk_bf16(v0[2], v0[3]); w.z = cvt_pk_bf16(v1[0], v1[1]); w.w = cvt_pk_bf16(v1[2], v1[3]); return w; }
;     __device__ __forceinline__ bf16_t* dst(const Unit& u, int row, int bj, int wc, int fq, int col0) const {
;         if (u.pn < 2 || u.pn >= 6) return O + (size_t)row * ldc + col0 + bj * HALF;
;         const int b = row >> 11, t = row & 2047;
;         if (u.pn < 4) { const int hc = (u.pn - 2) * 4 + bj * 2 + (wc >> 1), chunk = (wc & 1) * 4 + fq;
;             return KC + (size_t)((b * 8 + hc) * 32 + (t >> 6)) * 4096 + chunk * 512 + (t & 63) * 8; }
;         const int h = (u.pn - 4) * 2 + bj, piece = wc * 4 + ((t & 63) >> 4);
;         return VC + (size_t)((b * 4 + h) * 32 + (t >> 6)) * 8192 + piece * 512 + (t & 15) * 32 + fq * 8;
;     }
;     __device__ __forceinline__ void operator()(const f32x4 (&acc)[2][2][4][2], const Unit& u, int wr, int wc, int fr, int fq) const {
;     ...
; #pragma unroll
;             for (int ai = 0; ai < 2; ++ai)
; #pragma unroll
;                 for (int m = 0; m < 4; ++m) { const int row = row0 + ai * HALF + m * 16; const float r = rs[ai * 4 + m] * sc;
; #pragma unroll
;                     for (int bj = 0; bj < 2; ++bj) *(u32x4*)dst(u, row, bj, wc, fq, col0) = pack8(acc[ai][bj][m][0] * r, acc[ai][bj][m][1] * r); }
.LBB0_208:
	v_lshl_add_u64 v[170:171], v[194:195], 1, v[170:171]
	v_mov_b32_e32 v169, v168
	global_store_dwordx4 v[170:171], v[128:131], off nt
	v_pk_mul_f32 v[170:171], v[68:69], v[168:169]
	s_and_b64 vcc, exec, s[0:1]
	v_mov_b32_e32 v128, v168
	v_mov_b32_e32 v129, v168
	v_pk_mul_f32 v[130:131], v[70:71], v[128:129]
	v_pk_mul_f32 v[168:169], v[64:65], v[168:169]
	s_mov_b64 s[28:29], -1
	v_pk_mul_f32 v[178:179], v[66:67], v[128:129]
	v_cvt_pk_bf16_f32 v128, v170, v171
	v_cvt_pk_bf16_f32 v129, v130, v131
	v_cvt_pk_bf16_f32 v130, v168, v169
	s_nop 0
	v_cvt_pk_bf16_f32 v131, v178, v179
	s_cbranch_vccnz .LBB0_214
	s_cmp_lt_u32 s8, 4
	s_cbranch_scc1 .LBB0_211
	s_lshl_b32 s28, s8, 6
	s_add_i32 s28, s28, s40
	s_addk_i32 s28, 0xff20
	s_ashr_i32 s29, s28, 31
	s_lshl_b64 s[28:29], s[28:29], 14
	s_add_u32 s28, s16, s28
	s_addc_u32 s29, s17, s29
	s_lshl_b32 s40, s31, 1
	s_add_u32 s28, s28, s40
	s_addc_u32 s29, s29, 0
	v_lshlrev_b32_e32 v194, 1, v176
	v_lshl_add_u64 v[168:169], s[28:29], 0, v[194:195]
	s_mov_b64 s[28:29], 0xc00
	v_lshl_add_u64 v[168:169], v[168:169], 0, s[28:29]
	s_mov_b64 s[28:29], 0

; __device__ __forceinline__ u32x4 pack8(const f32x4 v0, const f32x4 v1) { u32x4 w; w.x = cvt_pk_bf16(v0[0], v0[1]); w.y = cvt_pk_bf16(v0[2], v0[3]); w.z = cvt_pk_bf16(v1[0], v1[1]); w.w = cvt_pk_bf16(v1[2], v1[3]); return w; }
;     __device__ __forceinline__ bf16_t* dst(const Unit& u, int row, int bj, int wc, int fq, int col0) const {
;         if (u.pn < 2 || u.pn >= 6) return O + (size_t)row * ldc + col0 + bj * HALF;
;         const int b = row >> 11, t = row & 2047;
;         if (u.pn < 4) { const int hc = (u.pn - 2) * 4 + bj * 2 + (wc >> 1), chunk = (wc & 1) * 4 + fq;
;             return KC + (size_t)((b * 8 + hc) * 32 + (t >> 6)) * 4096 + chunk * 512 + (t & 63) * 8; }
;         const int h = (u.pn - 4) * 2 + bj, piece = wc * 4 + ((t & 63) >> 4);
;         return VC + (size_t)((b * 4 + h) * 32 + (t >> 6)) * 8192 + piece * 512 + (t & 15) * 32 + fq * 8;
;     }
;     __device__ __forceinline__ void operator()(const f32x4 (&acc)[2][2][4][2], const Unit& u, int wr, int wc, int fr, int fq) const {
;     ...
; #pragma unroll
;             for (int ai = 0; ai < 2; ++ai)
; #pragma unroll
;                 for (int m = 0; m < 4; ++m) { const int row = row0 + ai * HALF + m * 16; const float r = rs[ai * 4 + m] * sc;
; #pragma unroll
;                     for (int bj = 0; bj < 2; ++bj) *(u32x4*)dst(u, row, bj, wc, fq, col0) = pack8(acc[ai][bj][m][0] * r, acc[ai][bj][m][1] * r); }
.LBB0_216:
	v_lshl_add_u64 v[168:169], v[194:195], 1, v[168:169]
	global_store_dwordx4 v[168:169], v[128:131], off nt
	v_mul_f32_e32 v168, v149, v159
	v_pk_mul_f32 v[170:171], v[58:59], v[168:169] op_sel_hi:[1,0]
	v_ashrrev_i32_e32 v128, 11, v152
	v_lshlrev_b32_e32 v165, 7, v128
	v_lshlrev_b32_e32 v177, 8, v128
	v_bfe_u32 v128, v152, 6, 5
	v_or_b32_e32 v179, v165, v128
	v_or_b32_e32 v178, v177, v128
	v_pk_mul_f32 v[130:131], v[62:63], v[168:169] op_sel_hi:[1,0]
	v_pk_mul_f32 v[128:129], v[60:61], v[168:169] op_sel_hi:[1,0]
	s_and_b64 vcc, exec, s[0:1]
	s_mov_b64 s[28:29], -1
	v_pk_mul_f32 v[180:181], v[56:57], v[168:169] op_sel_hi:[1,0]
	v_cvt_pk_bf16_f32 v128, v128, v129
	v_cvt_pk_bf16_f32 v129, v130, v131
	s_nop 0
	v_cvt_pk_bf16_f32 v130, v180, v181
	v_cvt_pk_bf16_f32 v131, v170, v171
	s_cbranch_vccnz .LBB0_222
	s_cmp_lt_u32 s8, 4
	s_cbranch_scc1 .LBB0_219
	s_lshl_b32 s28, s8, 6
	s_addk_i32 s28, 0xff00
	v_add_u32_e32 v170, s28, v179
	v_ashrrev_i32_e32 v171, 31, v170
	v_lshlrev_b64 v[170:171], 14, v[170:171]
	v_lshl_add_u64 v[170:171], s[16:17], 0, v[170:171]
	s_lshl_b32 s72, s31, 1
	v_lshl_add_u64 v[170:171], v[170:171], 0, s[72:73]
	v_lshlrev_b32_e32 v194, 1, v176
	v_lshl_add_u64 v[170:171], v[170:171], 0, v[194:195]
	s_mov_b64 s[28:29], 0

; __device__ __forceinline__ u32x4 pack8(const f32x4 v0, const f32x4 v1) { u32x4 w; w.x = cvt_pk_bf16(v0[0], v0[1]); w.y = cvt_pk_bf16(v0[2], v0[3]); w.z = cvt_pk_bf16(v1[0], v1[1]); w.w = cvt_pk_bf16(v1[2], v1[3]); return w; }
;     __device__ __forceinline__ bf16_t* dst(const Unit& u, int row, int bj, int wc, int fq, int col0) const {
;         if (u.pn < 2 || u.pn >= 6) return O + (size_t)row * ldc + col0 + bj * HALF;
;         const int b = row >> 11, t = row & 2047;
;         if (u.pn < 4) { const int hc = (u.pn - 2) * 4 + bj * 2 + (wc >> 1), chunk = (wc & 1) * 4 + fq;
;             return KC + (size_t)((b * 8 + hc) * 32 + (t >> 6)) * 4096 + chunk * 512 + (t & 63) * 8; }
;         const int h = (u.pn - 4) * 2 + bj, piece = wc * 4 + ((t & 63) >> 4);
;         return VC + (size_t)((b * 4 + h) * 32 + (t >> 6)) * 8192 + piece * 512 + (t & 15) * 32 + fq * 8;
;     }
;     __device__ __forceinline__ void operator()(const f32x4 (&acc)[2][2][4][2], const Unit& u, int wr, int wc, int fr, int fq) const {
;     ...
; #pragma unroll
;             for (int ai = 0; ai < 2; ++ai)
; #pragma unroll
;                 for (int m = 0; m < 4; ++m) { const int row = row0 + ai * HALF + m * 16; const float r = rs[ai * 4 + m] * sc;
; #pragma unroll
;                     for (int bj = 0; bj < 2; ++bj) *(u32x4*)dst(u, row, bj, wc, fq, col0) = pack8(acc[ai][bj][m][0] * r, acc[ai][bj][m][1] * r); }
.LBB0_224:
	v_lshl_add_u64 v[170:171], v[194:195], 1, v[170:171]
	v_mov_b32_e32 v169, v168
	global_store_dwordx4 v[170:171], v[128:131], off nt
	v_pk_mul_f32 v[170:171], v[52:53], v[168:169]
	s_and_b64 vcc, exec, s[0:1]
	v_mov_b32_e32 v128, v168
	v_mov_b32_e32 v129, v168
	v_pk_mul_f32 v[130:131], v[54:55], v[128:129]
	v_pk_mul_f32 v[168:169], v[48:49], v[168:169]
	s_mov_b64 s[28:29], -1
	v_pk_mul_f32 v[180:181], v[50:51], v[128:129]
	v_cvt_pk_bf16_f32 v128, v170, v171
	v_cvt_pk_bf16_f32 v129, v130, v131
	v_cvt_pk_bf16_f32 v130, v168, v169
	s_nop 0
	v_cvt_pk_bf16_f32 v131, v180, v181
	s_cbranch_vccnz .LBB0_230
	s_cmp_lt_u32 s8, 4
	s_cbranch_scc1 .LBB0_227
	s_lshl_b32 s28, s8, 6
	s_addk_i32 s28, 0xff20
	v_add_u32_e32 v168, s28, v179
	v_ashrrev_i32_e32 v169, 31, v168
	v_lshlrev_b64 v[168:169], 14, v[168:169]
	v_lshl_add_u64 v[168:169], s[16:17], 0, v[168:169]
	s_lshl_b32 s72, s31, 1
	v_lshl_add_u64 v[168:169], v[168:169], 0, s[72:73]
	v_lshlrev_b32_e32 v194, 1, v176
	v_lshl_add_u64 v[168:169], v[168:169], 0, v[194:195]
	s_mov_b64 s[28:29], 0

; __device__ __forceinline__ u32x4 pack8(const f32x4 v0, const f32x4 v1) { u32x4 w; w.x = cvt_pk_bf16(v0[0], v0[1]); w.y = cvt_pk_bf16(v0[2], v0[3]); w.z = cvt_pk_bf16(v1[0], v1[1]); w.w = cvt_pk_bf16(v1[2], v1[3]); return w; }
;     __device__ __forceinline__ bf16_t* dst(const Unit& u, int row, int bj, int wc, int fq, int col0) const {
;         if (u.pn < 2 || u.pn >= 6) return O + (size_t)row * ldc + col0 + bj * HALF;
;         const int b = row >> 11, t = row & 2047;
;         if (u.pn < 4) { const int hc = (u.pn - 2) * 4 + bj * 2 + (wc >> 1), chunk = (wc & 1) * 4 + fq;
;             return KC + (size_t)((b * 8 + hc) * 32 + (t >> 6)) * 4096 + chunk * 512 + (t & 63) * 8; }
;         const int h = (u.pn - 4) * 2 + bj, piece = wc * 4 + ((t & 63) >> 4);
;         return VC + (size_t)((b * 4 + h) * 32 + (t >> 6)) * 8192 + piece * 512 + (t & 15) * 32 + fq * 8;
;     }
;     __device__ __forceinline__ void operator()(const f32x4 (&acc)[2][2][4][2], const Unit& u, int wr, int wc, int fr, int fq) const {
;     ...
; #pragma unroll
;             for (int ai = 0; ai < 2; ++ai)
; #pragma unroll
;                 for (int m = 0; m < 4; ++m) { const int row = row0 + ai * HALF + m * 16; const float r = rs[ai * 4 + m] * sc;
; #pragma unroll
;                     for (int bj = 0; bj < 2; ++bj) *(u32x4*)dst(u, row, bj, wc, fq, col0) = pack8(acc[ai][bj][m][0] * r, acc[ai][bj][m][1] * r); }
.LBB0_232:
	v_lshl_add_u64 v[168:169], v[194:195], 1, v[168:169]
	global_store_dwordx4 v[168:169], v[128:131], off nt
	v_mul_f32_e32 v168, v149, v157
	v_pk_mul_f32 v[170:171], v[42:43], v[168:169] op_sel_hi:[1,0]
	v_bfe_u32 v128, v150, 6, 5
	v_or_b32_e32 v180, v165, v128
	v_or_b32_e32 v179, v177, v128
	v_lshlrev_b32_e32 v128, 3, v150
	v_and_b32_e32 v178, 0xf8, v128
	v_pk_mul_f32 v[130:131], v[46:47], v[168:169] op_sel_hi:[1,0]
	v_pk_mul_f32 v[128:129], v[44:45], v[168:169] op_sel_hi:[1,0]
	s_and_b64 vcc, exec, s[0:1]
	s_mov_b64 s[28:29], -1
	v_pk_mul_f32 v[182:183], v[40:41], v[168:169] op_sel_hi:[1,0]
	v_cvt_pk_bf16_f32 v128, v128, v129
	v_cvt_pk_bf16_f32 v129, v130, v131
	s_nop 0
	v_cvt_pk_bf16_f32 v130, v182, v183
	v_cvt_pk_bf16_f32 v131, v170, v171
	s_cbranch_vccnz .LBB0_238
	s_cmp_lt_u32 s8, 4
	s_cbranch_scc1 .LBB0_235
	s_lshl_b32 s28, s8, 6
	s_addk_i32 s28, 0xff00
	v_add_u32_e32 v170, s28, v180
	v_ashrrev_i32_e32 v171, 31, v170
	v_lshlrev_b64 v[170:171], 14, v[170:171]
	v_lshl_add_u64 v[170:171], s[16:17], 0, v[170:171]
	s_lshl_b32 s72, s31, 1
	v_lshl_add_u64 v[170:171], v[170:171], 0, s[72:73]
	v_lshlrev_b32_e32 v194, 1, v176
	v_lshl_add_u64 v[170:171], v[170:171], 0, v[194:195]
	s_mov_b64 s[28:29], 0x400
	v_lshl_add_u64 v[170:171], v[170:171], 0, s[28:29]
	s_mov_b64 s[28:29], 0

; __device__ __forceinline__ u32x4 pack8(const f32x4 v0, const f32x4 v1) { u32x4 w; w.x = cvt_pk_bf16(v0[0], v0[1]); w.y = cvt_pk_bf16(v0[2], v0[3]); w.z = cvt_pk_bf16(v1[0], v1[1]); w.w = cvt_pk_bf16(v1[2], v1[3]); return w; }
;     __device__ __forceinline__ bf16_t* dst(const Unit& u, int row, int bj, int wc, int fq, int col0) const {
;         if (u.pn < 2 || u.pn >= 6) return O + (size_t)row * ldc + col0 + bj * HALF;
;         const int b = row >> 11, t = row & 2047;
;         if (u.pn < 4) { const int hc = (u.pn - 2) * 4 + bj * 2 + (wc >> 1), chunk = (wc & 1) * 4 + fq;
;             return KC + (size_t)((b * 8 + hc) * 32 + (t >> 6)) * 4096 + chunk * 512 + (t & 63) * 8; }
;         const int h = (u.pn - 4) * 2 + bj, piece = wc * 4 + ((t & 63) >> 4);
;         return VC + (size_t)((b * 4 + h) * 32 + (t >> 6)) * 8192 + piece * 512 + (t & 15) * 32 + fq * 8;
;     }
;     __device__ __forceinline__ void operator()(const f32x4 (&acc)[2][2][4][2], const Unit& u, int wr, int wc, int fr, int fq) const {
;     ...
; #pragma unroll
;             for (int ai = 0; ai < 2; ++ai)
; #pragma unroll
;                 for (int m = 0; m < 4; ++m) { const int row = row0 + ai * HALF + m * 16; const float r = rs[ai * 4 + m] * sc;
; #pragma unroll
;                     for (int bj = 0; bj < 2; ++bj) *(u32x4*)dst(u, row, bj, wc, fq, col0) = pack8(acc[ai][bj][m][0] * r, acc[ai][bj][m][1] * r); }
.LBB0_240:
	v_lshl_add_u64 v[170:171], v[194:195], 1, v[170:171]
	v_mov_b32_e32 v169, v168
	global_store_dwordx4 v[170:171], v[128:131], off nt
	v_pk_mul_f32 v[170:171], v[36:37], v[168:169]
	s_and_b64 vcc, exec, s[0:1]
	v_mov_b32_e32 v128, v168
	v_mov_b32_e32 v129, v168
	v_pk_mul_f32 v[130:131], v[38:39], v[128:129]
	v_pk_mul_f32 v[168:169], v[32:33], v[168:169]
	s_mov_b64 s[28:29], -1
	v_pk_mul_f32 v[182:183], v[34:35], v[128:129]
	v_cvt_pk_bf16_f32 v128, v170, v171
	v_cvt_pk_bf16_f32 v129, v130, v131
	v_cvt_pk_bf16_f32 v130, v168, v169
	s_nop 0
	v_cvt_pk_bf16_f32 v131, v182, v183
	s_cbranch_vccnz .LBB0_246
	s_cmp_lt_u32 s8, 4
	s_cbranch_scc1 .LBB0_243
	s_lshl_b32 s28, s8, 6
	s_addk_i32 s28, 0xff20
	v_add_u32_e32 v168, s28, v180
	v_ashrrev_i32_e32 v169, 31, v168
	v_lshlrev_b64 v[168:169], 14, v[168:169]
	v_lshl_add_u64 v[168:169], s[16:17], 0, v[168:169]
	s_lshl_b32 s72, s31, 1
	v_lshl_add_u64 v[168:169], v[168:169], 0, s[72:73]
	v_lshlrev_b32_e32 v194, 1, v176
	v_lshl_add_u64 v[168:169], v[168:169], 0, v[194:195]
	s_mov_b64 s[28:29], 0x400
	v_lshl_add_u64 v[168:169], v[168:169], 0, s[28:29]
	s_mov_b64 s[28:29], 0

; __device__ __forceinline__ u32x4 pack8(const f32x4 v0, const f32x4 v1) { u32x4 w; w.x = cvt_pk_bf16(v0[0], v0[1]); w.y = cvt_pk_bf16(v0[2], v0[3]); w.z = cvt_pk_bf16(v1[0], v1[1]); w.w = cvt_pk_bf16(v1[2], v1[3]); return w; }
;     __device__ __forceinline__ bf16_t* dst(const Unit& u, int row, int bj, int wc, int fq, int col0) const {
;         if (u.pn < 2 || u.pn >= 6) return O + (size_t)row * ldc + col0 + bj * HALF;
;         const int b = row >> 11, t = row & 2047;
;         if (u.pn < 4) { const int hc = (u.pn - 2) * 4 + bj * 2 + (wc >> 1), chunk = (wc & 1) * 4 + fq;
;             return KC + (size_t)((b * 8 + hc) * 32 + (t >> 6)) * 4096 + chunk * 512 + (t & 63) * 8; }
;         const int h = (u.pn - 4) * 2 + bj, piece = wc * 4 + ((t & 63) >> 4);
;         return VC + (size_t)((b * 4 + h) * 32 + (t >> 6)) * 8192 + piece * 512 + (t & 15) * 32 + fq * 8;
;     }
;     __device__ __forceinline__ void operator()(const f32x4 (&acc)[2][2][4][2], const Unit& u, int wr, int wc, int fr, int fq) const {
;     ...
; #pragma unroll
;             for (int ai = 0; ai < 2; ++ai)
; #pragma unroll
;                 for (int m = 0; m < 4; ++m) { const int row = row0 + ai * HALF + m * 16; const float r = rs[ai * 4 + m] * sc;
; #pragma unroll
;                     for (int bj = 0; bj < 2; ++bj) *(u32x4*)dst(u, row, bj, wc, fq, col0) = pack8(acc[ai][bj][m][0] * r, acc[ai][bj][m][1] * r); }
.LBB0_248:
	v_lshl_add_u64 v[168:169], v[194:195], 1, v[168:169]
	global_store_dwordx4 v[168:169], v[128:131], off nt
	v_mul_f32_e32 v168, v149, v153
	v_pk_mul_f32 v[170:171], v[26:27], v[168:169] op_sel_hi:[1,0]
	v_bfe_u32 v128, v148, 6, 5
	v_or_b32_e32 v180, v165, v128
	v_or_b32_e32 v179, v177, v128
	v_lshlrev_b32_e32 v128, 3, v148
	v_and_b32_e32 v178, 0x178, v128
	v_pk_mul_f32 v[130:131], v[30:31], v[168:169] op_sel_hi:[1,0]
	v_pk_mul_f32 v[128:129], v[28:29], v[168:169] op_sel_hi:[1,0]
	s_and_b64 vcc, exec, s[0:1]
	s_mov_b64 s[28:29], -1
	v_pk_mul_f32 v[182:183], v[24:25], v[168:169] op_sel_hi:[1,0]
	v_cvt_pk_bf16_f32 v128, v128, v129
	v_cvt_pk_bf16_f32 v129, v130, v131
	s_nop 0
	v_cvt_pk_bf16_f32 v130, v182, v183
	v_cvt_pk_bf16_f32 v131, v170, v171
	s_cbranch_vccnz .LBB0_254
	s_cmp_lt_u32 s8, 4
	s_cbranch_scc1 .LBB0_251
	s_lshl_b32 s28, s8, 6
	s_addk_i32 s28, 0xff00
	v_add_u32_e32 v170, s28, v180
	v_ashrrev_i32_e32 v171, 31, v170
	v_lshlrev_b64 v[170:171], 14, v[170:171]
	v_lshl_add_u64 v[170:171], s[16:17], 0, v[170:171]
	s_lshl_b32 s72, s31, 1
	v_lshl_add_u64 v[170:171], v[170:171], 0, s[72:73]
	v_lshlrev_b32_e32 v194, 1, v176
	v_lshl_add_u64 v[170:171], v[170:171], 0, v[194:195]
	v_lshl_add_u64 v[170:171], v[170:171], 0, s[78:79]
	s_mov_b64 s[28:29], 0

; __device__ __forceinline__ u32x4 pack8(const f32x4 v0, const f32x4 v1) { u32x4 w; w.x = cvt_pk_bf16(v0[0], v0[1]); w.y = cvt_pk_bf16(v0[2], v0[3]); w.z = cvt_pk_bf16(v1[0], v1[1]); w.w = cvt_pk_bf16(v1[2], v1[3]); return w; }
;     __device__ __forceinline__ bf16_t* dst(const Unit& u, int row, int bj, int wc, int fq, int col0) const {
;         if (u.pn < 2 || u.pn >= 6) return O + (size_t)row * ldc + col0 + bj * HALF;
;         const int b = row >> 11, t = row & 2047;
;         if (u.pn < 4) { const int hc = (u.pn - 2) * 4 + bj * 2 + (wc >> 1), chunk = (wc & 1) * 4 + fq;
;             return KC + (size_t)((b * 8 + hc) * 32 + (t >> 6)) * 4096 + chunk * 512 + (t & 63) * 8; }
;         const int h = (u.pn - 4) * 2 + bj, piece = wc * 4 + ((t & 63) >> 4);
;         return VC + (size_t)((b * 4 + h) * 32 + (t >> 6)) * 8192 + piece * 512 + (t & 15) * 32 + fq * 8;
;     }
;     __device__ __forceinline__ void operator()(const f32x4 (&acc)[2][2][4][2], const Unit& u, int wr, int wc, int fr, int fq) const {
;     ...
; #pragma unroll
;             for (int ai = 0; ai < 2; ++ai)
; #pragma unroll
;                 for (int m = 0; m < 4; ++m) { const int row = row0 + ai * HALF + m * 16; const float r = rs[ai * 4 + m] * sc;
; #pragma unroll
;                     for (int bj = 0; bj < 2; ++bj) *(u32x4*)dst(u, row, bj, wc, fq, col0) = pack8(acc[ai][bj][m][0] * r, acc[ai][bj][m][1] * r); }
.LBB0_256:
	v_lshl_add_u64 v[170:171], v[194:195], 1, v[170:171]
	v_mov_b32_e32 v169, v168
	global_store_dwordx4 v[170:171], v[128:131], off nt
	v_pk_mul_f32 v[170:171], v[20:21], v[168:169]
	s_and_b64 vcc, exec, s[0:1]
	v_mov_b32_e32 v128, v168
	v_mov_b32_e32 v129, v168
	v_pk_mul_f32 v[130:131], v[22:23], v[128:129]
	v_pk_mul_f32 v[168:169], v[16:17], v[168:169]
	s_mov_b64 s[28:29], -1
	v_pk_mul_f32 v[182:183], v[18:19], v[128:129]
	v_cvt_pk_bf16_f32 v128, v170, v171
	v_cvt_pk_bf16_f32 v129, v130, v131
	v_cvt_pk_bf16_f32 v130, v168, v169
	s_nop 0
	v_cvt_pk_bf16_f32 v131, v182, v183
	s_cbranch_vccnz .LBB0_262
	s_cmp_lt_u32 s8, 4
	s_cbranch_scc1 .LBB0_259
	s_lshl_b32 s28, s8, 6
	s_addk_i32 s28, 0xff20
	v_add_u32_e32 v168, s28, v180
	v_ashrrev_i32_e32 v169, 31, v168
	v_lshlrev_b64 v[168:169], 14, v[168:169]
	v_lshl_add_u64 v[168:169], s[16:17], 0, v[168:169]
	s_lshl_b32 s72, s31, 1
	v_lshl_add_u64 v[168:169], v[168:169], 0, s[72:73]
	v_lshlrev_b32_e32 v194, 1, v176
	v_lshl_add_u64 v[168:169], v[168:169], 0, v[194:195]
	v_lshl_add_u64 v[168:169], v[168:169], 0, s[78:79]
	s_mov_b64 s[28:29], 0

; __device__ __forceinline__ u32x4 pack8(const f32x4 v0, const f32x4 v1) { u32x4 w; w.x = cvt_pk_bf16(v0[0], v0[1]); w.y = cvt_pk_bf16(v0[2], v0[3]); w.z = cvt_pk_bf16(v1[0], v1[1]); w.w = cvt_pk_bf16(v1[2], v1[3]); return w; }
;     __device__ __forceinline__ bf16_t* dst(const Unit& u, int row, int bj, int wc, int fq, int col0) const {
;         if (u.pn < 2 || u.pn >= 6) return O + (size_t)row * ldc + col0 + bj * HALF;
;         const int b = row >> 11, t = row & 2047;
;         if (u.pn < 4) { const int hc = (u.pn - 2) * 4 + bj * 2 + (wc >> 1), chunk = (wc & 1) * 4 + fq;
;             return KC + (size_t)((b * 8 + hc) * 32 + (t >> 6)) * 4096 + chunk * 512 + (t & 63) * 8; }
;         const int h = (u.pn - 4) * 2 + bj, piece = wc * 4 + ((t & 63) >> 4);
;         return VC + (size_t)((b * 4 + h) * 32 + (t >> 6)) * 8192 + piece * 512 + (t & 15) * 32 + fq * 8;
;     }
;     __device__ __forceinline__ void operator()(const f32x4 (&acc)[2][2][4][2], const Unit& u, int wr, int wc, int fr, int fq) const {
;     ...
; #pragma unroll
;             for (int ai = 0; ai < 2; ++ai)
; #pragma unroll
;                 for (int m = 0; m < 4; ++m) { const int row = row0 + ai * HALF + m * 16; const float r = rs[ai * 4 + m] * sc;
; #pragma unroll
;                     for (int bj = 0; bj < 2; ++bj) *(u32x4*)dst(u, row, bj, wc, fq, col0) = pack8(acc[ai][bj][m][0] * r, acc[ai][bj][m][1] * r); }
.LBB0_264:
	v_lshl_add_u64 v[168:169], v[194:195], 1, v[168:169]
	global_store_dwordx4 v[168:169], v[128:131], off nt
	v_mul_f32_e32 v168, v149, v151
	v_pk_mul_f32 v[170:171], v[10:11], v[168:169] op_sel_hi:[1,0]
	v_bfe_u32 v128, v144, 6, 5
	v_or_b32_e32 v178, v165, v128
	v_or_b32_e32 v177, v177, v128
	v_lshlrev_b32_e32 v128, 3, v144
	v_and_b32_e32 v165, 0x1f8, v128
	v_pk_mul_f32 v[130:131], v[14:15], v[168:169] op_sel_hi:[1,0]
	v_pk_mul_f32 v[128:129], v[12:13], v[168:169] op_sel_hi:[1,0]
	s_and_b64 vcc, exec, s[0:1]
	s_mov_b64 s[28:29], -1
	v_pk_mul_f32 v[180:181], v[8:9], v[168:169] op_sel_hi:[1,0]
	v_cvt_pk_bf16_f32 v128, v128, v129
	v_cvt_pk_bf16_f32 v129, v130, v131
	s_nop 0
	v_cvt_pk_bf16_f32 v130, v180, v181
	v_cvt_pk_bf16_f32 v131, v170, v171
	s_cbranch_vccnz .LBB0_270
	s_cmp_lt_u32 s8, 4
	s_cbranch_scc1 .LBB0_267
	s_lshl_b32 s28, s8, 6
	s_addk_i32 s28, 0xff00
	v_add_u32_e32 v170, s28, v178
	v_ashrrev_i32_e32 v171, 31, v170
	v_lshlrev_b64 v[170:171], 14, v[170:171]
	v_lshl_add_u64 v[170:171], s[16:17], 0, v[170:171]
	s_lshl_b32 s72, s31, 1
	v_lshl_add_u64 v[170:171], v[170:171], 0, s[72:73]
	v_lshlrev_b32_e32 v194, 1, v176
	v_lshl_add_u64 v[170:171], v[170:171], 0, v[194:195]
	s_mov_b64 s[28:29], 0xc00
	v_lshl_add_u64 v[170:171], v[170:171], 0, s[28:29]
	s_mov_b64 s[28:29], 0

; __device__ __forceinline__ u32x4 pack8(const f32x4 v0, const f32x4 v1) { u32x4 w; w.x = cvt_pk_bf16(v0[0], v0[1]); w.y = cvt_pk_bf16(v0[2], v0[3]); w.z = cvt_pk_bf16(v1[0], v1[1]); w.w = cvt_pk_bf16(v1[2], v1[3]); return w; }
;     __device__ __forceinline__ bf16_t* dst(const Unit& u, int row, int bj, int wc, int fq, int col0) const {
;         if (u.pn < 2 || u.pn >= 6) return O + (size_t)row * ldc + col0 + bj * HALF;
;         const int b = row >> 11, t = row & 2047;
;         if (u.pn < 4) { const int hc = (u.pn - 2) * 4 + bj * 2 + (wc >> 1), chunk = (wc & 1) * 4 + fq;
;             return KC + (size_t)((b * 8 + hc) * 32 + (t >> 6)) * 4096 + chunk * 512 + (t & 63) * 8; }
;         const int h = (u.pn - 4) * 2 + bj, piece = wc * 4 + ((t & 63) >> 4);
;         return VC + (size_t)((b * 4 + h) * 32 + (t >> 6)) * 8192 + piece * 512 + (t & 15) * 32 + fq * 8;
;     }
;     __device__ __forceinline__ void operator()(const f32x4 (&acc)[2][2][4][2], const Unit& u, int wr, int wc, int fr, int fq) const {
;     ...
; #pragma unroll
;             for (int ai = 0; ai < 2; ++ai)
; #pragma unroll
;                 for (int m = 0; m < 4; ++m) { const int row = row0 + ai * HALF + m * 16; const float r = rs[ai * 4 + m] * sc;
; #pragma unroll
;                     for (int bj = 0; bj < 2; ++bj) *(u32x4*)dst(u, row, bj, wc, fq, col0) = pack8(acc[ai][bj][m][0] * r, acc[ai][bj][m][1] * r); }
.LBB0_272:
	v_lshl_add_u64 v[170:171], v[194:195], 1, v[170:171]
	v_mov_b32_e32 v169, v168
	global_store_dwordx4 v[170:171], v[128:131], off nt
	v_pk_mul_f32 v[170:171], v[4:5], v[168:169]
	s_and_b64 vcc, exec, s[0:1]
	v_mov_b32_e32 v128, v168
	v_mov_b32_e32 v129, v168
	v_pk_mul_f32 v[130:131], v[6:7], v[128:129]
	v_pk_mul_f32 v[168:169], v[0:1], v[168:169]
	s_mov_b64 s[0:1], -1
	v_pk_mul_f32 v[180:181], v[2:3], v[128:129]
	v_cvt_pk_bf16_f32 v128, v170, v171
	v_cvt_pk_bf16_f32 v129, v130, v131
	v_cvt_pk_bf16_f32 v130, v168, v169
	s_nop 0
	v_cvt_pk_bf16_f32 v131, v180, v181
	s_cbranch_vccnz .LBB0_278
	s_cmp_lt_u32 s8, 4
	s_cbranch_scc1 .LBB0_275
	s_lshl_b32 s0, s8, 6
	s_addk_i32 s0, 0xff20
	v_add_u32_e32 v168, s0, v178
	v_ashrrev_i32_e32 v169, 31, v168
	v_lshlrev_b64 v[168:169], 14, v[168:169]
	v_lshl_add_u64 v[168:169], s[16:17], 0, v[168:169]
	s_lshl_b32 s72, s31, 1
	v_lshl_add_u64 v[168:169], v[168:169], 0, s[72:73]
	v_lshlrev_b32_e32 v194, 1, v176
	v_lshl_add_u64 v[168:169], v[168:169], 0, v[194:195]
	s_mov_b64 s[0:1], 0xc00
	v_lshl_add_u64 v[168:169], v[168:169], 0, s[0:1]
	s_mov_b64 s[0:1], 0

; __device__ __forceinline__ u32x4 pack8(const f32x4 v0, const f32x4 v1) { u32x4 w; w.x = cvt_pk_bf16(v0[0], v0[1]); w.y = cvt_pk_bf16(v0[2], v0[3]); w.z = cvt_pk_bf16(v1[0], v1[1]); w.w = cvt_pk_bf16(v1[2], v1[3]); return w; }
;     __device__ __forceinline__ bf16_t* dst(const Unit& u, int row, int bj, int wc, int fq, int col0) const {
;         if (u.pn < 2 || u.pn >= 6) return O + (size_t)row * ldc + col0 + bj * HALF;
;         const int b = row >> 11, t = row & 2047;
;         if (u.pn < 4) { const int hc = (u.pn - 2) * 4 + bj * 2 + (wc >> 1), chunk = (wc & 1) * 4 + fq;
;             return KC + (size_t)((b * 8 + hc) * 32 + (t >> 6)) * 4096 + chunk * 512 + (t & 63) * 8; }
;     __device__ __forceinline__ void operator()(const f32x4 (&acc)[2][2][4][2], const Unit& u, int wr, int wc, int fr, int fq) const {
;     ...
;                 for (int m = 0; m < 4; ++m) { const int row = row0 + ai * HALF + m * 16; const float r = rs[ai * 4 + m] * sc; const float pf = (float)ps[ai * 4 + m];
;                     float c[8], sn[8];
; #pragma unroll
;                     for (int e = 0; e < 8; ++e) { const float rev = __builtin_amdgcn_fractf((pf * invf[e]) * 0.15915494309189535f); c[e] = mine ? __builtin_amdgcn_cosf(rev) : 1.f; sn[e] = mine ? __builtin_amdgcn_sinf(rev) * sgn : 0.f; }
; #pragma unroll
;                     for (int bj = 0; bj < 2; ++bj) { f32x4 v0 = acc[ai][bj][m][0] * r, v1 = acc[ai][bj][m][1] * r; f32x4 p0, p1;
; #pragma unroll
;                         for (int e = 0; e < 4; ++e) { p0[e] = __shfl_xor(v0[e], 16); p1[e] = __shfl_xor(v1[e], 16); }
; #pragma unroll
;                         for (int e = 0; e < 4; ++e) { v0[e] = v0[e] * c[e] + p0[e] * sn[e]; v1[e] = v1[e] * c[4 + e] + p1[e] * sn[4 + e]; }
;                         *(u32x4*)dst(u, row, bj, wc, fq, col0) = pack8(v0, v1); } }
.LBB0_286:
	v_mov_b32_e32 v165, v164
	v_lshl_add_u64 v[124:125], v[126:127], 1, v[124:125]
	global_store_dwordx4 v[124:125], v[120:123], off nt
	v_pk_mul_f32 v[116:117], v[116:117], v[164:165]
	v_pk_mul_f32 v[112:113], v[112:113], v[164:165]
	v_mov_b32_e32 v120, v164
	v_mov_b32_e32 v121, v164
	v_pk_mul_f32 v[118:119], v[118:119], v[120:121]
	v_pk_mul_f32 v[114:115], v[114:115], v[120:121]
	ds_bpermute_b32 v120, v145, v116
	ds_bpermute_b32 v121, v145, v112
	ds_bpermute_b32 v122, v145, v117
	ds_bpermute_b32 v123, v145, v113
	ds_bpermute_b32 v124, v145, v118
	ds_bpermute_b32 v125, v145, v114
	s_waitcnt lgkmcnt(5)
	v_mul_f32_e32 v120, v175, v120
	ds_bpermute_b32 v126, v145, v119
	v_fmac_f32_e32 v120, v116, v169
	s_waitcnt lgkmcnt(5)
	v_mul_f32_e32 v116, v183, v121
	v_fmac_f32_e32 v116, v112, v180
	s_waitcnt lgkmcnt(4)
	v_mul_f32_e32 v112, v177, v122
	ds_bpermute_b32 v127, v145, v115
	v_fmac_f32_e32 v112, v117, v170
	s_waitcnt lgkmcnt(4)
	v_mul_f32_e32 v117, v185, v123
	v_fmac_f32_e32 v117, v113, v181
	s_waitcnt lgkmcnt(3)
	v_mul_f32_e32 v113, v178, v124
	v_fmac_f32_e32 v113, v118, v171
	s_waitcnt lgkmcnt(2)
	v_mul_f32_e32 v118, v186, v125
	v_fmac_f32_e32 v118, v114, v182
	s_waitcnt lgkmcnt(1)
	v_mul_f32_e32 v114, v179, v126
	v_fmac_f32_e32 v114, v119, v176
	s_waitcnt lgkmcnt(0)
	v_mul_f32_e32 v119, v187, v127
	v_cvt_pk_bf16_f32 v112, v120, v112
	v_cvt_pk_bf16_f32 v113, v113, v114
	v_cvt_pk_bf16_f32 v114, v116, v117
	v_cndmask_b32_e64 v116, 0, 1, s[28:29]
	v_fmac_f32_e32 v119, v115, v184
	v_cmp_ne_u32_e64 s[42:43], 1, v116
	s_andn2_b64 vcc, exec, s[28:29]
	s_mov_b64 s[28:29], -1
	v_cvt_pk_bf16_f32 v115, v118, v119
	s_cbranch_vccnz .LBB0_288
	s_lshl_b32 s28, s19, 5
	s_lshl_b32 s29, s8, 7
	s_or_b32 s28, s29, s28
	s_add_i32 s28, s28, s21
	s_addk_i32 s28, 0xff40
	s_ashr_i32 s29, s28, 31
	s_lshl_b64 s[28:29], s[28:29], 13
	s_add_u32 s28, s14, s28
	s_addc_u32 s29, s15, s29
	v_mov_b32_e32 v155, v195
	v_lshl_add_u64 v[116:117], s[28:29], 0, v[194:195]
	s_mov_b64 s[28:29], 0
	v_mov_b64_e32 v[118:119], v[154:155]

; __device__ __forceinline__ u32x4 pack8(const f32x4 v0, const f32x4 v1) { u32x4 w; w.x = cvt_pk_bf16(v0[0], v0[1]); w.y = cvt_pk_bf16(v0[2], v0[3]); w.z = cvt_pk_bf16(v1[0], v1[1]); w.w = cvt_pk_bf16(v1[2], v1[3]); return w; }
;     __device__ __forceinline__ bf16_t* dst(const Unit& u, int row, int bj, int wc, int fq, int col0) const {
;         if (u.pn < 2 || u.pn >= 6) return O + (size_t)row * ldc + col0 + bj * HALF;
;         const int b = row >> 11, t = row & 2047;
;         if (u.pn < 4) { const int hc = (u.pn - 2) * 4 + bj * 2 + (wc >> 1), chunk = (wc & 1) * 4 + fq;
;             return KC + (size_t)((b * 8 + hc) * 32 + (t >> 6)) * 4096 + chunk * 512 + (t & 63) * 8; }
;         const int h = (u.pn - 4) * 2 + bj, piece = wc * 4 + ((t & 63) >> 4);
;         return VC + (size_t)((b * 4 + h) * 32 + (t >> 6)) * 8192 + piece * 512 + (t & 15) * 32 + fq * 8;
;     }
;     __device__ __forceinline__ void operator()(const f32x4 (&acc)[2][2][4][2], const Unit& u, int wr, int wc, int fr, int fq) const {
;     ...
;                 for (int m = 0; m < 4; ++m) { const int row = row0 + ai * HALF + m * 16; const float r = rs[ai * 4 + m] * sc; const float pf = (float)ps[ai * 4 + m];
;                     float c[8], sn[8];
; #pragma unroll
;                     for (int e = 0; e < 8; ++e) { const float rev = __builtin_amdgcn_fractf((pf * invf[e]) * 0.15915494309189535f); c[e] = mine ? __builtin_amdgcn_cosf(rev) : 1.f; sn[e] = mine ? __builtin_amdgcn_sinf(rev) * sgn : 0.f; }
; #pragma unroll
;                     for (int bj = 0; bj < 2; ++bj) { f32x4 v0 = acc[ai][bj][m][0] * r, v1 = acc[ai][bj][m][1] * r; f32x4 p0, p1;
; #pragma unroll
;                         for (int e = 0; e < 4; ++e) { p0[e] = __shfl_xor(v0[e], 16); p1[e] = __shfl_xor(v1[e], 16); }
; #pragma unroll
;                         for (int e = 0; e < 4; ++e) { v0[e] = v0[e] * c[e] + p0[e] * sn[e]; v1[e] = v1[e] * c[4 + e] + p1[e] * sn[4 + e]; }
;                         *(u32x4*)dst(u, row, bj, wc, fq, col0) = pack8(v0, v1); } }
.LBB0_290:
	s_waitcnt vmcnt(7)
	v_cvt_f32_i32_e32 v155, v168
	v_lshl_add_u64 v[116:117], v[118:119], 1, v[116:117]
	global_store_dwordx4 v[116:117], v[112:115], off nt
	s_and_b64 vcc, exec, s[42:43]
	s_mov_b64 s[28:29], -1
	v_mul_f32_e32 v112, 0.15915494, v155
	v_fract_f32_e32 v112, v112
	v_cos_f32_e32 v114, v112
	v_mul_f32_e32 v113, 0x3e4693af, v155
	v_mul_f32_e32 v113, 0.15915494, v113
	v_sin_f32_e32 v112, v112
	v_fract_f32_e32 v113, v113
	v_cndmask_b32_e64 v116, 1.0, v114, s[0:1]
	v_cos_f32_e32 v114, v113
	v_sin_f32_e32 v113, v113
	v_cndmask_b32_e64 v112, v112, -v112, s[40:41]
	v_cndmask_b32_e64 v120, 0, v112, s[0:1]
	v_cndmask_b32_e64 v117, 1.0, v114, s[0:1]
	v_cndmask_b32_e64 v112, v113, -v113, s[40:41]
	v_cndmask_b32_e64 v118, 0, v112, s[0:1]
	v_mul_f32_e32 v112, 0x3d1a08c8, v155
	v_mul_f32_e32 v112, 0.15915494, v112
	v_fract_f32_e32 v112, v112
	v_cos_f32_e32 v113, v112
	v_sin_f32_e32 v112, v112
	v_mul_f32_e32 v114, 0x3beef74e, v155
	v_mul_f32_e32 v114, 0.15915494, v114
	v_cndmask_b32_e64 v121, 1.0, v113, s[0:1]
	v_mul_f32_e32 v113, 0x3ab95d22, v155
	v_fract_f32_e32 v114, v114
	v_cndmask_b32_e64 v112, v112, -v112, s[40:41]
	v_mul_f32_e32 v113, 0.15915494, v113
	v_cndmask_b32_e64 v122, 0, v112, s[0:1]
	v_sin_f32_e32 v112, v114
	v_fract_f32_e32 v113, v113
	v_cos_f32_e32 v115, v114
	v_cos_f32_e32 v114, v113
	v_sin_f32_e32 v113, v113
	v_cndmask_b32_e64 v112, v112, -v112, s[40:41]
	v_cndmask_b32_e64 v123, 0, v112, s[0:1]
	v_cndmask_b32_e64 v124, 1.0, v114, s[0:1]
	v_cndmask_b32_e64 v112, v113, -v113, s[40:41]
	v_cndmask_b32_e64 v125, 0, v112, s[0:1]
	v_mul_f32_e32 v112, 0x398fc8f8, v155
	v_mul_f32_e32 v112, 0.15915494, v112
	v_fract_f32_e32 v112, v112
	v_cos_f32_e32 v113, v112
	v_sin_f32_e32 v112, v112
	v_mul_f32_e32 v114, 0x385f10c4, v155
	v_mul_f32_e32 v114, 0.15915494, v114
	v_cndmask_b32_e64 v127, 1.0, v113, s[0:1]
	v_mul_f32_e32 v113, 0x372d07a7, v155
	v_mul_f32_e32 v113, 0.15915494, v113
	v_fract_f32_e32 v114, v114
	v_cndmask_b32_e64 v112, v112, -v112, s[40:41]
	v_fract_f32_e32 v113, v113
	v_cndmask_b32_e64 v119, 1.0, v115, s[0:1]
	v_cos_f32_e32 v115, v114
	v_cndmask_b32_e64 v162, 0, v112, s[0:1]
	v_sin_f32_e32 v112, v114
	v_cos_f32_e32 v114, v113
	v_sin_f32_e32 v113, v113
	v_cndmask_b32_e64 v126, 1.0, v115, s[0:1]
	v_cndmask_b32_e64 v112, v112, -v112, s[40:41]
	v_cndmask_b32_e64 v155, 1.0, v114, s[0:1]
	v_mul_f32_e32 v114, v149, v174
	v_pk_mul_f32 v[108:109], v[108:109], v[114:115] op_sel_hi:[1,0]
	v_cndmask_b32_e64 v165, 0, v112, s[0:1]
	v_cndmask_b32_e64 v112, v113, -v113, s[40:41]
	v_pk_mul_f32 v[104:105], v[104:105], v[114:115] op_sel_hi:[1,0]
	ds_bpermute_b32 v113, v145, v108
	v_pk_mul_f32 v[110:111], v[110:111], v[114:115] op_sel_hi:[1,0]
	v_pk_mul_f32 v[106:107], v[106:107], v[114:115] op_sel_hi:[1,0]
	ds_bpermute_b32 v115, v145, v104
	ds_bpermute_b32 v168, v145, v109
	ds_bpermute_b32 v169, v145, v105
	ds_bpermute_b32 v170, v145, v110
	ds_bpermute_b32 v171, v145, v106
	s_waitcnt lgkmcnt(5)
	v_mul_f32_e32 v113, v120, v113
	ds_bpermute_b32 v174, v145, v111
	v_fmac_f32_e32 v113, v108, v116
	s_waitcnt lgkmcnt(5)
	v_mul_f32_e32 v108, v125, v115
	ds_bpermute_b32 v175, v145, v107
	v_fmac_f32_e32 v108, v104, v124
	s_waitcnt lgkmcnt(5)
	v_mul_f32_e32 v104, v118, v168
	v_fmac_f32_e32 v104, v109, v117
	s_waitcnt lgkmcnt(4)
	v_mul_f32_e32 v109, v162, v169
	v_fmac_f32_e32 v109, v105, v127
	s_waitcnt lgkmcnt(3)
	v_mul_f32_e32 v105, v122, v170
	v_fmac_f32_e32 v105, v110, v121
	s_waitcnt lgkmcnt(2)
	v_mul_f32_e32 v110, v165, v171
	v_cndmask_b32_e64 v164, 0, v112, s[0:1]
	v_fmac_f32_e32 v110, v106, v126
	s_waitcnt lgkmcnt(1)
	v_mul_f32_e32 v106, v123, v174
	v_lshlrev_b32_e32 v112, 3, v160
	v_fmac_f32_e32 v106, v111, v119
	s_waitcnt lgkmcnt(0)
	v_mul_f32_e32 v111, v164, v175
	v_and_b32_e32 v112, 0xf8, v112
	v_fmac_f32_e32 v111, v107, v155
	v_cvt_pk_bf16_f32 v104, v113, v104
	v_cvt_pk_bf16_f32 v105, v105, v106
	v_cvt_pk_bf16_f32 v106, v108, v109
	v_cvt_pk_bf16_f32 v107, v110, v111
	s_cbranch_vccnz .LBB0_292
	s_lshl_b32 s28, s19, 5
	s_lshl_b32 s29, s8, 7
	s_or_b32 s28, s29, s28
	s_add_i32 s28, s28, s21
	s_addk_i32 s28, 0xff00
	s_ashr_i32 s29, s28, 31
	s_lshl_b64 s[28:29], s[28:29], 13
	s_add_u32 s28, s14, s28
	s_addc_u32 s29, s15, s29
	v_mov_b32_e32 v113, v195
	v_lshl_add_u64 v[108:109], s[28:29], 0, v[194:195]
	s_mov_b64 s[28:29], 0
	v_mov_b64_e32 v[110:111], v[112:113]

; __device__ __forceinline__ u32x4 pack8(const f32x4 v0, const f32x4 v1) { u32x4 w; w.x = cvt_pk_bf16(v0[0], v0[1]); w.y = cvt_pk_bf16(v0[2], v0[3]); w.z = cvt_pk_bf16(v1[0], v1[1]); w.w = cvt_pk_bf16(v1[2], v1[3]); return w; }
;     __device__ __forceinline__ bf16_t* dst(const Unit& u, int row, int bj, int wc, int fq, int col0) const {
;         if (u.pn < 2 || u.pn >= 6) return O + (size_t)row * ldc + col0 + bj * HALF;
;         const int b = row >> 11, t = row & 2047;
;         if (u.pn < 4) { const int hc = (u.pn - 2) * 4 + bj * 2 + (wc >> 1), chunk = (wc & 1) * 4 + fq;
;             return KC + (size_t)((b * 8 + hc) * 32 + (t >> 6)) * 4096 + chunk * 512 + (t & 63) * 8; }
;     __device__ __forceinline__ void operator()(const f32x4 (&acc)[2][2][4][2], const Unit& u, int wr, int wc, int fr, int fq) const {
;     ...
;                     for (int bj = 0; bj < 2; ++bj) { f32x4 v0 = acc[ai][bj][m][0] * r, v1 = acc[ai][bj][m][1] * r; f32x4 p0, p1;
; #pragma unroll
;                         for (int e = 0; e < 4; ++e) { p0[e] = __shfl_xor(v0[e], 16); p1[e] = __shfl_xor(v1[e], 16); }
; #pragma unroll
;                         for (int e = 0; e < 4; ++e) { v0[e] = v0[e] * c[e] + p0[e] * sn[e]; v1[e] = v1[e] * c[4 + e] + p1[e] * sn[4 + e]; }
;                         *(u32x4*)dst(u, row, bj, wc, fq, col0) = pack8(v0, v1); } }
.LBB0_294:
	v_mov_b32_e32 v115, v114
	v_lshl_add_u64 v[108:109], v[110:111], 1, v[108:109]
	global_store_dwordx4 v[108:109], v[104:107], off nt
	v_pk_mul_f32 v[100:101], v[100:101], v[114:115]
	v_pk_mul_f32 v[96:97], v[96:97], v[114:115]
	v_mov_b32_e32 v104, v114
	v_mov_b32_e32 v105, v114
	v_pk_mul_f32 v[102:103], v[102:103], v[104:105]
	v_pk_mul_f32 v[98:99], v[98:99], v[104:105]
	ds_bpermute_b32 v104, v145, v100
	ds_bpermute_b32 v105, v145, v96
	ds_bpermute_b32 v106, v145, v101
	ds_bpermute_b32 v107, v145, v97
	ds_bpermute_b32 v108, v145, v102
	ds_bpermute_b32 v109, v145, v98
	s_waitcnt lgkmcnt(5)
	v_mul_f32_e32 v104, v120, v104
	ds_bpermute_b32 v110, v145, v103
	v_fmac_f32_e32 v104, v100, v116
	s_waitcnt lgkmcnt(5)
	v_mul_f32_e32 v100, v125, v105
	ds_bpermute_b32 v111, v145, v99
	v_fmac_f32_e32 v100, v96, v124
	s_waitcnt lgkmcnt(5)
	v_mul_f32_e32 v96, v118, v106
	v_fmac_f32_e32 v96, v101, v117
	s_waitcnt lgkmcnt(4)
	v_mul_f32_e32 v101, v162, v107
	v_fmac_f32_e32 v101, v97, v127
	s_waitcnt lgkmcnt(3)
	v_mul_f32_e32 v97, v122, v108
	v_fmac_f32_e32 v97, v102, v121
	s_waitcnt lgkmcnt(2)
	v_mul_f32_e32 v102, v165, v109
	v_fmac_f32_e32 v102, v98, v126
	s_waitcnt lgkmcnt(1)
	v_mul_f32_e32 v98, v123, v110
	v_fmac_f32_e32 v98, v103, v119
	s_waitcnt lgkmcnt(0)
	v_mul_f32_e32 v103, v164, v111
	s_and_b64 vcc, exec, s[42:43]
	s_mov_b64 s[28:29], -1
	v_fmac_f32_e32 v103, v99, v155
	v_cvt_pk_bf16_f32 v96, v104, v96
	v_cvt_pk_bf16_f32 v97, v97, v98
	v_cvt_pk_bf16_f32 v98, v100, v101
	v_cvt_pk_bf16_f32 v99, v102, v103
	s_cbranch_vccnz .LBB0_296
	s_lshl_b32 s28, s19, 5
	s_lshl_b32 s29, s8, 7
	s_or_b32 s28, s29, s28
	s_add_i32 s28, s28, s21
	s_addk_i32 s28, 0xff40
	s_ashr_i32 s29, s28, 31
	s_lshl_b64 s[28:29], s[28:29], 13
	s_add_u32 s28, s14, s28
	s_addc_u32 s29, s15, s29
	v_lshl_add_u64 v[100:101], s[28:29], 0, v[194:195]
	v_mov_b32_e32 v113, v195
	s_mov_b64 s[28:29], 0

; __device__ __forceinline__ u32x4 pack8(const f32x4 v0, const f32x4 v1) { u32x4 w; w.x = cvt_pk_bf16(v0[0], v0[1]); w.y = cvt_pk_bf16(v0[2], v0[3]); w.z = cvt_pk_bf16(v1[0], v1[1]); w.w = cvt_pk_bf16(v1[2], v1[3]); return w; }
;     __device__ __forceinline__ bf16_t* dst(const Unit& u, int row, int bj, int wc, int fq, int col0) const {
;         if (u.pn < 2 || u.pn >= 6) return O + (size_t)row * ldc + col0 + bj * HALF;
;         const int b = row >> 11, t = row & 2047;
;         if (u.pn < 4) { const int hc = (u.pn - 2) * 4 + bj * 2 + (wc >> 1), chunk = (wc & 1) * 4 + fq;
;             return KC + (size_t)((b * 8 + hc) * 32 + (t >> 6)) * 4096 + chunk * 512 + (t & 63) * 8; }
;     __device__ __forceinline__ void operator()(const f32x4 (&acc)[2][2][4][2], const Unit& u, int wr, int wc, int fr, int fq) const {
;     ...
;                 for (int m = 0; m < 4; ++m) { const int row = row0 + ai * HALF + m * 16; const float r = rs[ai * 4 + m] * sc; const float pf = (float)ps[ai * 4 + m];
;                     float c[8], sn[8];
; #pragma unroll
;                     for (int e = 0; e < 8; ++e) { const float rev = __builtin_amdgcn_fractf((pf * invf[e]) * 0.15915494309189535f); c[e] = mine ? __builtin_amdgcn_cosf(rev) : 1.f; sn[e] = mine ? __builtin_amdgcn_sinf(rev) * sgn : 0.f; }
; #pragma unroll
;                     for (int bj = 0; bj < 2; ++bj) { f32x4 v0 = acc[ai][bj][m][0] * r, v1 = acc[ai][bj][m][1] * r; f32x4 p0, p1;
; #pragma unroll
;                         for (int e = 0; e < 4; ++e) { p0[e] = __shfl_xor(v0[e], 16); p1[e] = __shfl_xor(v1[e], 16); }
; #pragma unroll
;                         for (int e = 0; e < 4; ++e) { v0[e] = v0[e] * c[e] + p0[e] * sn[e]; v1[e] = v1[e] * c[4 + e] + p1[e] * sn[4 + e]; }
;                         *(u32x4*)dst(u, row, bj, wc, fq, col0) = pack8(v0, v1); } }
.LBB0_298:
	s_waitcnt vmcnt(8)
	v_cvt_f32_i32_e32 v114, v166
	v_lshl_add_u64 v[100:101], v[112:113], 1, v[100:101]
	global_store_dwordx4 v[100:101], v[96:99], off nt
	s_and_b64 vcc, exec, s[42:43]
	s_mov_b64 s[28:29], -1
	v_mul_f32_e32 v96, 0.15915494, v114
	v_fract_f32_e32 v96, v96
	v_cos_f32_e32 v98, v96
	v_mul_f32_e32 v97, 0x3e4693af, v114
	v_mul_f32_e32 v97, 0.15915494, v97
	v_sin_f32_e32 v96, v96
	v_fract_f32_e32 v97, v97
	v_cndmask_b32_e64 v100, 1.0, v98, s[0:1]
	v_cos_f32_e32 v98, v97
	v_sin_f32_e32 v97, v97
	v_cndmask_b32_e64 v96, v96, -v96, s[40:41]
	v_cndmask_b32_e64 v104, 0, v96, s[0:1]
	v_cndmask_b32_e64 v101, 1.0, v98, s[0:1]
	v_cndmask_b32_e64 v96, v97, -v97, s[40:41]
	v_cndmask_b32_e64 v102, 0, v96, s[0:1]
	v_mul_f32_e32 v96, 0x3d1a08c8, v114
	v_mul_f32_e32 v96, 0.15915494, v96
	v_fract_f32_e32 v96, v96
	v_cos_f32_e32 v97, v96
	v_sin_f32_e32 v96, v96
	v_mul_f32_e32 v98, 0x3beef74e, v114
	v_mul_f32_e32 v98, 0.15915494, v98
	v_cndmask_b32_e64 v105, 1.0, v97, s[0:1]
	v_mul_f32_e32 v97, 0x3ab95d22, v114
	v_fract_f32_e32 v98, v98
	v_cndmask_b32_e64 v96, v96, -v96, s[40:41]
	v_mul_f32_e32 v97, 0.15915494, v97
	v_cndmask_b32_e64 v106, 0, v96, s[0:1]
	v_sin_f32_e32 v96, v98
	v_fract_f32_e32 v97, v97
	v_cos_f32_e32 v99, v98
	v_cos_f32_e32 v98, v97
	v_sin_f32_e32 v97, v97
	v_cndmask_b32_e64 v96, v96, -v96, s[40:41]
	v_cndmask_b32_e64 v107, 0, v96, s[0:1]
	v_cndmask_b32_e64 v108, 1.0, v98, s[0:1]
	v_cndmask_b32_e64 v96, v97, -v97, s[40:41]
	v_cndmask_b32_e64 v109, 0, v96, s[0:1]
	v_mul_f32_e32 v96, 0x398fc8f8, v114
	v_mul_f32_e32 v96, 0.15915494, v96
	v_fract_f32_e32 v96, v96
	v_cos_f32_e32 v97, v96
	v_sin_f32_e32 v96, v96
	v_mul_f32_e32 v98, 0x385f10c4, v114
	v_mul_f32_e32 v98, 0.15915494, v98
	v_cndmask_b32_e64 v111, 1.0, v97, s[0:1]
	v_mul_f32_e32 v97, 0x372d07a7, v114
	v_mul_f32_e32 v97, 0.15915494, v97
	v_fract_f32_e32 v98, v98
	v_cndmask_b32_e64 v96, v96, -v96, s[40:41]
	v_fract_f32_e32 v97, v97
	v_cndmask_b32_e64 v103, 1.0, v99, s[0:1]
	v_cos_f32_e32 v99, v98
	v_cndmask_b32_e64 v113, 0, v96, s[0:1]
	v_sin_f32_e32 v96, v98
	v_cos_f32_e32 v98, v97
	v_sin_f32_e32 v97, v97
	v_cndmask_b32_e64 v110, 1.0, v99, s[0:1]
	v_cndmask_b32_e64 v96, v96, -v96, s[40:41]
	v_cndmask_b32_e64 v112, 1.0, v98, s[0:1]
	v_mul_f32_e32 v98, v149, v167
	v_pk_mul_f32 v[92:93], v[92:93], v[98:99] op_sel_hi:[1,0]
	v_cndmask_b32_e64 v115, 0, v96, s[0:1]
	v_cndmask_b32_e64 v96, v97, -v97, s[40:41]
	v_pk_mul_f32 v[88:89], v[88:89], v[98:99] op_sel_hi:[1,0]
	ds_bpermute_b32 v97, v145, v92
	v_pk_mul_f32 v[94:95], v[94:95], v[98:99] op_sel_hi:[1,0]
	v_pk_mul_f32 v[90:91], v[90:91], v[98:99] op_sel_hi:[1,0]
	ds_bpermute_b32 v99, v145, v88
	ds_bpermute_b32 v116, v145, v93
	ds_bpermute_b32 v117, v145, v89
	ds_bpermute_b32 v118, v145, v94
	ds_bpermute_b32 v119, v145, v90
	s_waitcnt lgkmcnt(5)
	v_mul_f32_e32 v97, v104, v97
	ds_bpermute_b32 v120, v145, v95
	v_fmac_f32_e32 v97, v92, v100
	s_waitcnt lgkmcnt(5)
	v_mul_f32_e32 v92, v109, v99
	ds_bpermute_b32 v121, v145, v91
	v_fmac_f32_e32 v92, v88, v108
	s_waitcnt lgkmcnt(5)
	v_mul_f32_e32 v88, v102, v116
	v_fmac_f32_e32 v88, v93, v101
	s_waitcnt lgkmcnt(4)
	v_mul_f32_e32 v93, v113, v117
	v_fmac_f32_e32 v93, v89, v111
	s_waitcnt lgkmcnt(3)
	v_mul_f32_e32 v89, v106, v118
	v_fmac_f32_e32 v89, v94, v105
	s_waitcnt lgkmcnt(2)
	v_mul_f32_e32 v94, v115, v119
	v_cndmask_b32_e64 v114, 0, v96, s[0:1]
	v_fmac_f32_e32 v94, v90, v110
	s_waitcnt lgkmcnt(1)
	v_mul_f32_e32 v90, v107, v120
	v_lshlrev_b32_e32 v96, 3, v158
	v_fmac_f32_e32 v90, v95, v103
	s_waitcnt lgkmcnt(0)
	v_mul_f32_e32 v95, v114, v121
	v_and_b32_e32 v96, 0x178, v96
	v_fmac_f32_e32 v95, v91, v112
	v_cvt_pk_bf16_f32 v88, v97, v88
	v_cvt_pk_bf16_f32 v89, v89, v90
	v_cvt_pk_bf16_f32 v90, v92, v93
	v_cvt_pk_bf16_f32 v91, v94, v95
	s_cbranch_vccnz .LBB0_300
	s_lshl_b32 s28, s19, 5
	s_lshl_b32 s29, s8, 7
	s_or_b32 s28, s29, s28
	s_add_i32 s28, s28, s21
	s_addk_i32 s28, 0xff00
	s_ashr_i32 s29, s28, 31
	s_lshl_b64 s[28:29], s[28:29], 13
	s_add_u32 s28, s14, s28
	s_addc_u32 s29, s15, s29
	v_mov_b32_e32 v97, v195
	v_lshl_add_u64 v[92:93], s[28:29], 0, v[194:195]
	s_mov_b64 s[28:29], 0
	v_mov_b64_e32 v[94:95], v[96:97]

; __device__ __forceinline__ u32x4 pack8(const f32x4 v0, const f32x4 v1) { u32x4 w; w.x = cvt_pk_bf16(v0[0], v0[1]); w.y = cvt_pk_bf16(v0[2], v0[3]); w.z = cvt_pk_bf16(v1[0], v1[1]); w.w = cvt_pk_bf16(v1[2], v1[3]); return w; }
;     __device__ __forceinline__ bf16_t* dst(const Unit& u, int row, int bj, int wc, int fq, int col0) const {
;         if (u.pn < 2 || u.pn >= 6) return O + (size_t)row * ldc + col0 + bj * HALF;
;         const int b = row >> 11, t = row & 2047;
;         if (u.pn < 4) { const int hc = (u.pn - 2) * 4 + bj * 2 + (wc >> 1), chunk = (wc & 1) * 4 + fq;
;             return KC + (size_t)((b * 8 + hc) * 32 + (t >> 6)) * 4096 + chunk * 512 + (t & 63) * 8; }
;     __device__ __forceinline__ void operator()(const f32x4 (&acc)[2][2][4][2], const Unit& u, int wr, int wc, int fr, int fq) const {
;     ...
;                     for (int bj = 0; bj < 2; ++bj) { f32x4 v0 = acc[ai][bj][m][0] * r, v1 = acc[ai][bj][m][1] * r; f32x4 p0, p1;
; #pragma unroll
;                         for (int e = 0; e < 4; ++e) { p0[e] = __shfl_xor(v0[e], 16); p1[e] = __shfl_xor(v1[e], 16); }
; #pragma unroll
;                         for (int e = 0; e < 4; ++e) { v0[e] = v0[e] * c[e] + p0[e] * sn[e]; v1[e] = v1[e] * c[4 + e] + p1[e] * sn[4 + e]; }
;                         *(u32x4*)dst(u, row, bj, wc, fq, col0) = pack8(v0, v1); } }
.LBB0_302:
	v_mov_b32_e32 v99, v98
	v_lshl_add_u64 v[92:93], v[94:95], 1, v[92:93]
	global_store_dwordx4 v[92:93], v[88:91], off nt
	v_pk_mul_f32 v[84:85], v[84:85], v[98:99]
	v_pk_mul_f32 v[80:81], v[80:81], v[98:99]
	v_mov_b32_e32 v88, v98
	v_mov_b32_e32 v89, v98
	v_pk_mul_f32 v[86:87], v[86:87], v[88:89]
	v_pk_mul_f32 v[82:83], v[82:83], v[88:89]
	ds_bpermute_b32 v88, v145, v84
	ds_bpermute_b32 v89, v145, v80
	ds_bpermute_b32 v90, v145, v85
	ds_bpermute_b32 v91, v145, v81
	ds_bpermute_b32 v92, v145, v86
	ds_bpermute_b32 v93, v145, v82
	s_waitcnt lgkmcnt(5)
	v_mul_f32_e32 v88, v104, v88
	ds_bpermute_b32 v94, v145, v87
	v_fmac_f32_e32 v88, v84, v100
	s_waitcnt lgkmcnt(5)
	v_mul_f32_e32 v84, v109, v89
	ds_bpermute_b32 v95, v145, v83
	v_fmac_f32_e32 v84, v80, v108
	s_waitcnt lgkmcnt(5)
	v_mul_f32_e32 v80, v102, v90
	v_fmac_f32_e32 v80, v85, v101
	s_waitcnt lgkmcnt(4)
	v_mul_f32_e32 v85, v113, v91
	v_fmac_f32_e32 v85, v81, v111
	s_waitcnt lgkmcnt(3)
	v_mul_f32_e32 v81, v106, v92
	v_fmac_f32_e32 v81, v86, v105
	s_waitcnt lgkmcnt(2)
	v_mul_f32_e32 v86, v115, v93
	v_fmac_f32_e32 v86, v82, v110
	s_waitcnt lgkmcnt(1)
	v_mul_f32_e32 v82, v107, v94
	v_fmac_f32_e32 v82, v87, v103
	s_waitcnt lgkmcnt(0)
	v_mul_f32_e32 v87, v114, v95
	s_and_b64 vcc, exec, s[42:43]
	s_mov_b64 s[28:29], -1
	v_fmac_f32_e32 v87, v83, v112
	v_cvt_pk_bf16_f32 v80, v88, v80
	v_cvt_pk_bf16_f32 v81, v81, v82
	v_cvt_pk_bf16_f32 v82, v84, v85
	v_cvt_pk_bf16_f32 v83, v86, v87
	s_cbranch_vccnz .LBB0_304
	s_lshl_b32 s28, s19, 5
	s_lshl_b32 s29, s8, 7
	s_or_b32 s28, s29, s28
	s_add_i32 s28, s28, s21
	s_addk_i32 s28, 0xff40
	s_ashr_i32 s29, s28, 31
	s_lshl_b64 s[28:29], s[28:29], 13
	s_add_u32 s28, s14, s28
	s_addc_u32 s29, s15, s29
	v_lshl_add_u64 v[84:85], s[28:29], 0, v[194:195]
	v_mov_b32_e32 v97, v195
	s_mov_b64 s[28:29], 0

; __device__ __forceinline__ u32x4 pack8(const f32x4 v0, const f32x4 v1) { u32x4 w; w.x = cvt_pk_bf16(v0[0], v0[1]); w.y = cvt_pk_bf16(v0[2], v0[3]); w.z = cvt_pk_bf16(v1[0], v1[1]); w.w = cvt_pk_bf16(v1[2], v1[3]); return w; }
;     __device__ __forceinline__ bf16_t* dst(const Unit& u, int row, int bj, int wc, int fq, int col0) const {
;         if (u.pn < 2 || u.pn >= 6) return O + (size_t)row * ldc + col0 + bj * HALF;
;         const int b = row >> 11, t = row & 2047;
;         if (u.pn < 4) { const int hc = (u.pn - 2) * 4 + bj * 2 + (wc >> 1), chunk = (wc & 1) * 4 + fq;
;             return KC + (size_t)((b * 8 + hc) * 32 + (t >> 6)) * 4096 + chunk * 512 + (t & 63) * 8; }
;     __device__ __forceinline__ void operator()(const f32x4 (&acc)[2][2][4][2], const Unit& u, int wr, int wc, int fr, int fq) const {
;     ...
;                 for (int m = 0; m < 4; ++m) { const int row = row0 + ai * HALF + m * 16; const float r = rs[ai * 4 + m] * sc; const float pf = (float)ps[ai * 4 + m];
;                     float c[8], sn[8];
; #pragma unroll
;                     for (int e = 0; e < 8; ++e) { const float rev = __builtin_amdgcn_fractf((pf * invf[e]) * 0.15915494309189535f); c[e] = mine ? __builtin_amdgcn_cosf(rev) : 1.f; sn[e] = mine ? __builtin_amdgcn_sinf(rev) * sgn : 0.f; }
; #pragma unroll
;                     for (int bj = 0; bj < 2; ++bj) { f32x4 v0 = acc[ai][bj][m][0] * r, v1 = acc[ai][bj][m][1] * r; f32x4 p0, p1;
; #pragma unroll
;                         for (int e = 0; e < 4; ++e) { p0[e] = __shfl_xor(v0[e], 16); p1[e] = __shfl_xor(v1[e], 16); }
; #pragma unroll
;                         for (int e = 0; e < 4; ++e) { v0[e] = v0[e] * c[e] + p0[e] * sn[e]; v1[e] = v1[e] * c[4 + e] + p1[e] * sn[4 + e]; }
;                         *(u32x4*)dst(u, row, bj, wc, fq, col0) = pack8(v0, v1); } }
.LBB0_306:
	s_waitcnt vmcnt(9)
	v_cvt_f32_i32_e32 v98, v163
	v_lshl_add_u64 v[84:85], v[96:97], 1, v[84:85]
	global_store_dwordx4 v[84:85], v[80:83], off nt
	s_and_b64 vcc, exec, s[42:43]
	s_mov_b64 s[28:29], -1
	v_mul_f32_e32 v80, 0.15915494, v98
	v_fract_f32_e32 v80, v80
	v_cos_f32_e32 v82, v80
	v_mul_f32_e32 v81, 0x3e4693af, v98
	v_mul_f32_e32 v81, 0.15915494, v81
	v_sin_f32_e32 v80, v80
	v_fract_f32_e32 v81, v81
	v_cndmask_b32_e64 v84, 1.0, v82, s[0:1]
	v_cos_f32_e32 v82, v81
	v_sin_f32_e32 v81, v81
	v_cndmask_b32_e64 v80, v80, -v80, s[40:41]
	v_cndmask_b32_e64 v88, 0, v80, s[0:1]
	v_cndmask_b32_e64 v85, 1.0, v82, s[0:1]
	v_cndmask_b32_e64 v80, v81, -v81, s[40:41]
	v_cndmask_b32_e64 v86, 0, v80, s[0:1]
	v_mul_f32_e32 v80, 0x3d1a08c8, v98
	v_mul_f32_e32 v80, 0.15915494, v80
	v_fract_f32_e32 v80, v80
	v_cos_f32_e32 v81, v80
	v_sin_f32_e32 v80, v80
	v_mul_f32_e32 v82, 0x3beef74e, v98
	v_mul_f32_e32 v82, 0.15915494, v82
	v_cndmask_b32_e64 v89, 1.0, v81, s[0:1]
	v_mul_f32_e32 v81, 0x3ab95d22, v98
	v_fract_f32_e32 v82, v82
	v_cndmask_b32_e64 v80, v80, -v80, s[40:41]
	v_mul_f32_e32 v81, 0.15915494, v81
	v_cndmask_b32_e64 v90, 0, v80, s[0:1]
	v_sin_f32_e32 v80, v82
	v_fract_f32_e32 v81, v81
	v_cos_f32_e32 v83, v82
	v_cos_f32_e32 v82, v81
	v_sin_f32_e32 v81, v81
	v_cndmask_b32_e64 v80, v80, -v80, s[40:41]
	v_cndmask_b32_e64 v91, 0, v80, s[0:1]
	v_cndmask_b32_e64 v92, 1.0, v82, s[0:1]
	v_cndmask_b32_e64 v80, v81, -v81, s[40:41]
	v_cndmask_b32_e64 v93, 0, v80, s[0:1]
	v_mul_f32_e32 v80, 0x398fc8f8, v98
	v_mul_f32_e32 v80, 0.15915494, v80
	v_fract_f32_e32 v80, v80
	v_cos_f32_e32 v81, v80
	v_sin_f32_e32 v80, v80
	v_mul_f32_e32 v82, 0x385f10c4, v98
	v_mul_f32_e32 v82, 0.15915494, v82
	v_cndmask_b32_e64 v95, 1.0, v81, s[0:1]
	v_mul_f32_e32 v81, 0x372d07a7, v98
	v_mul_f32_e32 v81, 0.15915494, v81
	v_fract_f32_e32 v82, v82
	v_cndmask_b32_e64 v80, v80, -v80, s[40:41]
	v_fract_f32_e32 v81, v81
	v_cndmask_b32_e64 v87, 1.0, v83, s[0:1]
	v_cos_f32_e32 v83, v82
	v_cndmask_b32_e64 v97, 0, v80, s[0:1]
	v_sin_f32_e32 v80, v82
	v_cos_f32_e32 v82, v81
	v_sin_f32_e32 v81, v81
	v_cndmask_b32_e64 v94, 1.0, v83, s[0:1]
	v_cndmask_b32_e64 v80, v80, -v80, s[40:41]
	v_cndmask_b32_e64 v96, 1.0, v82, s[0:1]
	v_mul_f32_e32 v82, v149, v161
	v_pk_mul_f32 v[76:77], v[76:77], v[82:83] op_sel_hi:[1,0]
	v_cndmask_b32_e64 v99, 0, v80, s[0:1]
	v_cndmask_b32_e64 v80, v81, -v81, s[40:41]
	v_pk_mul_f32 v[72:73], v[72:73], v[82:83] op_sel_hi:[1,0]
	ds_bpermute_b32 v81, v145, v76
	v_pk_mul_f32 v[78:79], v[78:79], v[82:83] op_sel_hi:[1,0]
	v_pk_mul_f32 v[74:75], v[74:75], v[82:83] op_sel_hi:[1,0]
	ds_bpermute_b32 v83, v145, v72
	ds_bpermute_b32 v100, v145, v77
	ds_bpermute_b32 v101, v145, v73
	ds_bpermute_b32 v102, v145, v78
	ds_bpermute_b32 v103, v145, v74
	s_waitcnt lgkmcnt(5)
	v_mul_f32_e32 v81, v88, v81
	ds_bpermute_b32 v104, v145, v79
	v_fmac_f32_e32 v81, v76, v84
	s_waitcnt lgkmcnt(5)
	v_mul_f32_e32 v76, v93, v83
	ds_bpermute_b32 v105, v145, v75
	v_fmac_f32_e32 v76, v72, v92
	s_waitcnt lgkmcnt(5)
	v_mul_f32_e32 v72, v86, v100
	v_fmac_f32_e32 v72, v77, v85
	s_waitcnt lgkmcnt(4)
	v_mul_f32_e32 v77, v97, v101
	v_fmac_f32_e32 v77, v73, v95
	s_waitcnt lgkmcnt(3)
	v_mul_f32_e32 v73, v90, v102
	v_fmac_f32_e32 v73, v78, v89
	s_waitcnt lgkmcnt(2)
	v_mul_f32_e32 v78, v99, v103
	v_cndmask_b32_e64 v98, 0, v80, s[0:1]
	v_fmac_f32_e32 v78, v74, v94
	s_waitcnt lgkmcnt(1)
	v_mul_f32_e32 v74, v91, v104
	v_lshlrev_b32_e32 v80, 3, v156
	v_fmac_f32_e32 v74, v79, v87
	s_waitcnt lgkmcnt(0)
	v_mul_f32_e32 v79, v98, v105
	v_and_b32_e32 v80, 0x1f8, v80
	v_fmac_f32_e32 v79, v75, v96
	v_cvt_pk_bf16_f32 v72, v81, v72
	v_cvt_pk_bf16_f32 v73, v73, v74
	v_cvt_pk_bf16_f32 v74, v76, v77
	v_cvt_pk_bf16_f32 v75, v78, v79
	s_cbranch_vccnz .LBB0_308
	s_lshl_b32 s28, s19, 5
	s_lshl_b32 s29, s8, 7
	s_or_b32 s28, s29, s28
	s_add_i32 s28, s28, s21
	s_addk_i32 s28, 0xff00
	s_ashr_i32 s29, s28, 31
	s_lshl_b64 s[28:29], s[28:29], 13
	s_add_u32 s28, s14, s28
	s_addc_u32 s29, s15, s29
	v_mov_b32_e32 v81, v195
	v_lshl_add_u64 v[76:77], s[28:29], 0, v[194:195]
	s_mov_b64 s[28:29], 0
	v_mov_b64_e32 v[78:79], v[80:81]

; __device__ __forceinline__ u32x4 pack8(const f32x4 v0, const f32x4 v1) { u32x4 w; w.x = cvt_pk_bf16(v0[0], v0[1]); w.y = cvt_pk_bf16(v0[2], v0[3]); w.z = cvt_pk_bf16(v1[0], v1[1]); w.w = cvt_pk_bf16(v1[2], v1[3]); return w; }
;     __device__ __forceinline__ bf16_t* dst(const Unit& u, int row, int bj, int wc, int fq, int col0) const {
;         if (u.pn < 2 || u.pn >= 6) return O + (size_t)row * ldc + col0 + bj * HALF;
;         const int b = row >> 11, t = row & 2047;
;         if (u.pn < 4) { const int hc = (u.pn - 2) * 4 + bj * 2 + (wc >> 1), chunk = (wc & 1) * 4 + fq;
;             return KC + (size_t)((b * 8 + hc) * 32 + (t >> 6)) * 4096 + chunk * 512 + (t & 63) * 8; }
;     __device__ __forceinline__ void operator()(const f32x4 (&acc)[2][2][4][2], const Unit& u, int wr, int wc, int fr, int fq) const {
;     ...
;                     for (int bj = 0; bj < 2; ++bj) { f32x4 v0 = acc[ai][bj][m][0] * r, v1 = acc[ai][bj][m][1] * r; f32x4 p0, p1;
; #pragma unroll
;                         for (int e = 0; e < 4; ++e) { p0[e] = __shfl_xor(v0[e], 16); p1[e] = __shfl_xor(v1[e], 16); }
; #pragma unroll
;                         for (int e = 0; e < 4; ++e) { v0[e] = v0[e] * c[e] + p0[e] * sn[e]; v1[e] = v1[e] * c[4 + e] + p1[e] * sn[4 + e]; }
;                         *(u32x4*)dst(u, row, bj, wc, fq, col0) = pack8(v0, v1); } }
.LBB0_310:
	v_mov_b32_e32 v83, v82
	v_lshl_add_u64 v[76:77], v[78:79], 1, v[76:77]
	global_store_dwordx4 v[76:77], v[72:75], off nt
	v_pk_mul_f32 v[68:69], v[68:69], v[82:83]
	v_pk_mul_f32 v[64:65], v[64:65], v[82:83]
	v_mov_b32_e32 v72, v82
	v_mov_b32_e32 v73, v82
	v_pk_mul_f32 v[70:71], v[70:71], v[72:73]
	v_pk_mul_f32 v[66:67], v[66:67], v[72:73]
	ds_bpermute_b32 v72, v145, v68
	ds_bpermute_b32 v73, v145, v64
	ds_bpermute_b32 v74, v145, v69
	ds_bpermute_b32 v75, v145, v65
	ds_bpermute_b32 v76, v145, v70
	ds_bpermute_b32 v77, v145, v66
	s_waitcnt lgkmcnt(5)
	v_mul_f32_e32 v72, v88, v72
	ds_bpermute_b32 v78, v145, v71
	v_fmac_f32_e32 v72, v68, v84
	s_waitcnt lgkmcnt(5)
	v_mul_f32_e32 v68, v93, v73
	ds_bpermute_b32 v79, v145, v67
	v_fmac_f32_e32 v68, v64, v92
	s_waitcnt lgkmcnt(5)
	v_mul_f32_e32 v64, v86, v74
	v_fmac_f32_e32 v64, v69, v85
	s_waitcnt lgkmcnt(4)
	v_mul_f32_e32 v69, v97, v75
	v_fmac_f32_e32 v69, v65, v95
	s_waitcnt lgkmcnt(3)
	v_mul_f32_e32 v65, v90, v76
	v_fmac_f32_e32 v65, v70, v89
	s_waitcnt lgkmcnt(2)
	v_mul_f32_e32 v70, v99, v77
	v_fmac_f32_e32 v70, v66, v94
	s_waitcnt lgkmcnt(1)
	v_mul_f32_e32 v66, v91, v78
	v_fmac_f32_e32 v66, v71, v87
	s_waitcnt lgkmcnt(0)
	v_mul_f32_e32 v71, v98, v79
	s_and_b64 vcc, exec, s[42:43]
	s_mov_b64 s[28:29], -1
	v_fmac_f32_e32 v71, v67, v96
	v_cvt_pk_bf16_f32 v64, v72, v64
	v_cvt_pk_bf16_f32 v65, v65, v66
	v_cvt_pk_bf16_f32 v66, v68, v69
	v_cvt_pk_bf16_f32 v67, v70, v71
	s_cbranch_vccnz .LBB0_312
	s_lshl_b32 s28, s19, 5
	s_lshl_b32 s29, s8, 7
	s_or_b32 s28, s29, s28
	s_add_i32 s21, s28, s21
	s_add_i32 s28, s21, 0xffffff40
	s_ashr_i32 s29, s28, 31
	s_lshl_b64 s[28:29], s[28:29], 13
	s_add_u32 s28, s14, s28
	s_addc_u32 s29, s15, s29
	v_lshl_add_u64 v[68:69], s[28:29], 0, v[194:195]
	v_mov_b32_e32 v81, v195
	s_mov_b64 s[28:29], 0

; __device__ __forceinline__ u32x4 pack8(const f32x4 v0, const f32x4 v1) { u32x4 w; w.x = cvt_pk_bf16(v0[0], v0[1]); w.y = cvt_pk_bf16(v0[2], v0[3]); w.z = cvt_pk_bf16(v1[0], v1[1]); w.w = cvt_pk_bf16(v1[2], v1[3]); return w; }
;     __device__ __forceinline__ bf16_t* dst(const Unit& u, int row, int bj, int wc, int fq, int col0) const {
;         if (u.pn < 2 || u.pn >= 6) return O + (size_t)row * ldc + col0 + bj * HALF;
;         const int b = row >> 11, t = row & 2047;
;         if (u.pn < 4) { const int hc = (u.pn - 2) * 4 + bj * 2 + (wc >> 1), chunk = (wc & 1) * 4 + fq;
;             return KC + (size_t)((b * 8 + hc) * 32 + (t >> 6)) * 4096 + chunk * 512 + (t & 63) * 8; }
;     __device__ __forceinline__ void operator()(const f32x4 (&acc)[2][2][4][2], const Unit& u, int wr, int wc, int fr, int fq) const {
;     ...
;                 for (int m = 0; m < 4; ++m) { const int row = row0 + ai * HALF + m * 16; const float r = rs[ai * 4 + m] * sc; const float pf = (float)ps[ai * 4 + m];
;                     float c[8], sn[8];
; #pragma unroll
;                     for (int e = 0; e < 8; ++e) { const float rev = __builtin_amdgcn_fractf((pf * invf[e]) * 0.15915494309189535f); c[e] = mine ? __builtin_amdgcn_cosf(rev) : 1.f; sn[e] = mine ? __builtin_amdgcn_sinf(rev) * sgn : 0.f; }
; #pragma unroll
;                     for (int bj = 0; bj < 2; ++bj) { f32x4 v0 = acc[ai][bj][m][0] * r, v1 = acc[ai][bj][m][1] * r; f32x4 p0, p1;
; #pragma unroll
;                         for (int e = 0; e < 4; ++e) { p0[e] = __shfl_xor(v0[e], 16); p1[e] = __shfl_xor(v1[e], 16); }
; #pragma unroll
;                         for (int e = 0; e < 4; ++e) { v0[e] = v0[e] * c[e] + p0[e] * sn[e]; v1[e] = v1[e] * c[4 + e] + p1[e] * sn[4 + e]; }
;                         *(u32x4*)dst(u, row, bj, wc, fq, col0) = pack8(v0, v1); } }
.LBB0_314:
	s_waitcnt vmcnt(10)
	v_cvt_f32_i32_e32 v75, v131
	v_lshl_add_u64 v[68:69], v[80:81], 1, v[68:69]
	global_store_dwordx4 v[68:69], v[64:67], off nt
	v_ashrrev_i32_e32 v70, 3, v152
	v_mul_f32_e32 v68, 0x3e4693af, v75
	v_mul_f32_e32 v64, 0.15915494, v75
	v_fract_f32_e32 v64, v64
	v_cos_f32_e32 v65, v64
	v_sin_f32_e32 v64, v64
	v_and_b32_e32 v66, 0xffffff00, v70
	v_mul_f32_e32 v70, 0x3beef74e, v75
	v_cndmask_b32_e64 v67, 1.0, v65, s[0:1]
	v_mul_f32_e32 v65, 0.15915494, v68
	v_fract_f32_e32 v65, v65
	v_cos_f32_e32 v68, v65
	v_sin_f32_e32 v65, v65
	v_cndmask_b32_e64 v64, v64, -v64, s[40:41]
	v_cndmask_b32_e64 v71, 0, v64, s[0:1]
	v_mul_f32_e32 v70, 0.15915494, v70
	v_cndmask_b32_e64 v64, v65, -v65, s[40:41]
	v_cndmask_b32_e64 v69, 0, v64, s[0:1]
	v_mul_f32_e32 v64, 0x3d1a08c8, v75
	v_mul_f32_e32 v64, 0.15915494, v64
	v_fract_f32_e32 v64, v64
	v_cos_f32_e32 v65, v64
	v_sin_f32_e32 v64, v64
	v_fract_f32_e32 v74, v70
	v_cos_f32_e32 v70, v74
	v_cndmask_b32_e64 v72, 1.0, v65, s[0:1]
	v_mul_f32_e32 v65, 0x3ab95d22, v75
	v_cndmask_b32_e64 v64, v64, -v64, s[40:41]
	v_mul_f32_e32 v65, 0.15915494, v65
	v_cndmask_b32_e64 v73, 0, v64, s[0:1]
	v_sin_f32_e32 v64, v74
	v_fract_f32_e32 v65, v65
	v_cos_f32_e32 v76, v65
	v_sin_f32_e32 v65, v65
	v_cndmask_b32_e64 v64, v64, -v64, s[40:41]
	v_cndmask_b32_e64 v74, 0, v64, s[0:1]
	v_mul_f32_e32 v78, 0x385f10c4, v75
	v_cndmask_b32_e64 v64, v65, -v65, s[40:41]
	v_cndmask_b32_e64 v77, 0, v64, s[0:1]
	v_mul_f32_e32 v64, 0x398fc8f8, v75
	v_mul_f32_e32 v64, 0.15915494, v64
	v_fract_f32_e32 v64, v64
	v_cos_f32_e32 v65, v64
	v_sin_f32_e32 v64, v64
	v_mul_f32_e32 v78, 0.15915494, v78
	v_fract_f32_e32 v80, v78
	v_cndmask_b32_e64 v79, 1.0, v65, s[0:1]
	v_mul_f32_e32 v65, 0x372d07a7, v75
	v_cndmask_b32_e64 v64, v64, -v64, s[40:41]
	v_mul_f32_e32 v65, 0.15915494, v65
	v_cndmask_b32_e64 v81, 0, v64, s[0:1]
	v_sin_f32_e32 v64, v80
	v_fract_f32_e32 v65, v65
	v_cos_f32_e32 v75, v65
	v_sin_f32_e32 v65, v65
	v_cndmask_b32_e64 v64, v64, -v64, s[40:41]
	v_cndmask_b32_e64 v83, 0, v64, s[0:1]
	v_cos_f32_e32 v78, v80
	v_cndmask_b32_e64 v64, v65, -v65, s[40:41]
	v_cndmask_b32_e64 v82, 0, v64, s[0:1]
	v_mul_f32_e32 v64, v149, v159
	v_lshrrev_b32_e32 v65, 6, v152
	v_pk_mul_f32 v[60:61], v[60:61], v[64:65] op_sel_hi:[1,0]
	v_cndmask_b32_e64 v80, 1.0, v75, s[0:1]
	v_and_or_b32 v75, v65, 31, v66
	v_pk_mul_f32 v[62:63], v[62:63], v[64:65] op_sel_hi:[1,0]
	v_pk_mul_f32 v[58:59], v[58:59], v[64:65] op_sel_hi:[1,0]
	v_pk_mul_f32 v[56:57], v[56:57], v[64:65] op_sel_hi:[1,0]
	ds_bpermute_b32 v65, v145, v60
	ds_bpermute_b32 v84, v145, v56
	ds_bpermute_b32 v85, v145, v61
	ds_bpermute_b32 v86, v145, v57
	ds_bpermute_b32 v87, v145, v62
	ds_bpermute_b32 v88, v145, v58
	s_waitcnt lgkmcnt(5)
	v_mul_f32_e32 v65, v71, v65
	v_cndmask_b32_e64 v76, 1.0, v76, s[0:1]
	ds_bpermute_b32 v89, v145, v63
	v_fmac_f32_e32 v65, v60, v67
	s_waitcnt lgkmcnt(5)
	v_mul_f32_e32 v60, v77, v84
	v_cndmask_b32_e64 v68, 1.0, v68, s[0:1]
	ds_bpermute_b32 v90, v145, v59
	v_fmac_f32_e32 v60, v56, v76
	s_waitcnt lgkmcnt(5)
	v_mul_f32_e32 v56, v69, v85
	v_fmac_f32_e32 v56, v61, v68
	s_waitcnt lgkmcnt(4)
	v_mul_f32_e32 v61, v81, v86
	v_fmac_f32_e32 v61, v57, v79
	s_waitcnt lgkmcnt(3)
	v_mul_f32_e32 v57, v73, v87
	v_cndmask_b32_e64 v78, 1.0, v78, s[0:1]
	v_fmac_f32_e32 v57, v62, v72
	s_waitcnt lgkmcnt(2)
	v_mul_f32_e32 v62, v83, v88
	v_cndmask_b32_e64 v70, 1.0, v70, s[0:1]
	v_fmac_f32_e32 v62, v58, v78
	s_waitcnt lgkmcnt(1)
	v_mul_f32_e32 v58, v74, v89
	v_fmac_f32_e32 v58, v63, v70
	s_waitcnt lgkmcnt(0)
	v_mul_f32_e32 v63, v82, v90
	v_fmac_f32_e32 v63, v59, v80
	s_and_b64 vcc, exec, s[42:43]
	s_mov_b64 s[28:29], -1
	v_cvt_pk_bf16_f32 v56, v65, v56
	v_cvt_pk_bf16_f32 v57, v57, v58
	v_cvt_pk_bf16_f32 v58, v60, v61
	v_cvt_pk_bf16_f32 v59, v62, v63
	s_cbranch_vccnz .LBB0_316
	s_lshl_b32 s21, s19, 5
	s_lshl_b32 s28, s8, 7
	s_or_b32 s21, s28, s21
	s_addk_i32 s21, 0xff00
	v_add_u32_e32 v60, s21, v75
	v_ashrrev_i32_e32 v61, 31, v60
	v_lshlrev_b64 v[60:61], 13, v[60:61]
	v_lshl_add_u64 v[60:61], s[14:15], 0, v[60:61]
	v_mov_b32_e32 v155, v195
	v_lshl_add_u64 v[60:61], v[60:61], 0, v[194:195]
	s_mov_b64 s[28:29], 0
	v_mov_b64_e32 v[62:63], v[154:155]

; __device__ __forceinline__ u32x4 pack8(const f32x4 v0, const f32x4 v1) { u32x4 w; w.x = cvt_pk_bf16(v0[0], v0[1]); w.y = cvt_pk_bf16(v0[2], v0[3]); w.z = cvt_pk_bf16(v1[0], v1[1]); w.w = cvt_pk_bf16(v1[2], v1[3]); return w; }
;     __device__ __forceinline__ bf16_t* dst(const Unit& u, int row, int bj, int wc, int fq, int col0) const {
;         if (u.pn < 2 || u.pn >= 6) return O + (size_t)row * ldc + col0 + bj * HALF;
;         const int b = row >> 11, t = row & 2047;
;         if (u.pn < 4) { const int hc = (u.pn - 2) * 4 + bj * 2 + (wc >> 1), chunk = (wc & 1) * 4 + fq;
;             return KC + (size_t)((b * 8 + hc) * 32 + (t >> 6)) * 4096 + chunk * 512 + (t & 63) * 8; }
;     __device__ __forceinline__ void operator()(const f32x4 (&acc)[2][2][4][2], const Unit& u, int wr, int wc, int fr, int fq) const {
;     ...
;                     for (int bj = 0; bj < 2; ++bj) { f32x4 v0 = acc[ai][bj][m][0] * r, v1 = acc[ai][bj][m][1] * r; f32x4 p0, p1;
; #pragma unroll
;                         for (int e = 0; e < 4; ++e) { p0[e] = __shfl_xor(v0[e], 16); p1[e] = __shfl_xor(v1[e], 16); }
; #pragma unroll
;                         for (int e = 0; e < 4; ++e) { v0[e] = v0[e] * c[e] + p0[e] * sn[e]; v1[e] = v1[e] * c[4 + e] + p1[e] * sn[4 + e]; }
;                         *(u32x4*)dst(u, row, bj, wc, fq, col0) = pack8(v0, v1); } }
.LBB0_318:
	v_mov_b32_e32 v65, v64
	v_lshl_add_u64 v[60:61], v[62:63], 1, v[60:61]
	global_store_dwordx4 v[60:61], v[56:59], off nt
	v_pk_mul_f32 v[52:53], v[52:53], v[64:65]
	v_pk_mul_f32 v[48:49], v[48:49], v[64:65]
	v_mov_b32_e32 v56, v64
	v_mov_b32_e32 v57, v64
	v_pk_mul_f32 v[54:55], v[54:55], v[56:57]
	v_pk_mul_f32 v[50:51], v[50:51], v[56:57]
	ds_bpermute_b32 v56, v145, v52
	ds_bpermute_b32 v57, v145, v48
	ds_bpermute_b32 v58, v145, v53
	ds_bpermute_b32 v59, v145, v49
	ds_bpermute_b32 v60, v145, v54
	ds_bpermute_b32 v61, v145, v50
	s_waitcnt lgkmcnt(5)
	v_mul_f32_e32 v56, v71, v56
	ds_bpermute_b32 v62, v145, v55
	v_fmac_f32_e32 v56, v52, v67
	s_waitcnt lgkmcnt(5)
	v_mul_f32_e32 v52, v77, v57
	ds_bpermute_b32 v63, v145, v51
	v_fmac_f32_e32 v52, v48, v76
	s_waitcnt lgkmcnt(5)
	v_mul_f32_e32 v48, v69, v58
	v_fmac_f32_e32 v48, v53, v68
	s_waitcnt lgkmcnt(4)
	v_mul_f32_e32 v53, v81, v59
	v_fmac_f32_e32 v53, v49, v79
	s_waitcnt lgkmcnt(3)
	v_mul_f32_e32 v49, v73, v60
	v_fmac_f32_e32 v49, v54, v72
	s_waitcnt lgkmcnt(2)
	v_mul_f32_e32 v54, v83, v61
	v_fmac_f32_e32 v54, v50, v78
	s_waitcnt lgkmcnt(1)
	v_mul_f32_e32 v50, v74, v62
	v_fmac_f32_e32 v50, v55, v70
	s_waitcnt lgkmcnt(0)
	v_mul_f32_e32 v55, v82, v63
	s_and_b64 vcc, exec, s[42:43]
	s_mov_b64 s[28:29], -1
	v_fmac_f32_e32 v55, v51, v80
	v_cvt_pk_bf16_f32 v48, v56, v48
	v_cvt_pk_bf16_f32 v49, v49, v50
	v_cvt_pk_bf16_f32 v50, v52, v53
	v_cvt_pk_bf16_f32 v51, v54, v55
	s_cbranch_vccnz .LBB0_320
	s_lshl_b32 s21, s19, 5
	s_lshl_b32 s28, s8, 7
	s_or_b32 s21, s28, s21
	s_addk_i32 s21, 0xff40
	v_add_u32_e32 v52, s21, v75
	v_ashrrev_i32_e32 v53, 31, v52
	v_lshlrev_b64 v[52:53], 13, v[52:53]
	v_lshl_add_u64 v[52:53], s[14:15], 0, v[52:53]
	v_lshl_add_u64 v[52:53], v[52:53], 0, v[194:195]
	v_mov_b32_e32 v155, v195
	s_mov_b64 s[28:29], 0

; __device__ __forceinline__ u32x4 pack8(const f32x4 v0, const f32x4 v1) { u32x4 w; w.x = cvt_pk_bf16(v0[0], v0[1]); w.y = cvt_pk_bf16(v0[2], v0[3]); w.z = cvt_pk_bf16(v1[0], v1[1]); w.w = cvt_pk_bf16(v1[2], v1[3]); return w; }
;     __device__ __forceinline__ bf16_t* dst(const Unit& u, int row, int bj, int wc, int fq, int col0) const {
;         if (u.pn < 2 || u.pn >= 6) return O + (size_t)row * ldc + col0 + bj * HALF;
;         const int b = row >> 11, t = row & 2047;
;         if (u.pn < 4) { const int hc = (u.pn - 2) * 4 + bj * 2 + (wc >> 1), chunk = (wc & 1) * 4 + fq;
;             return KC + (size_t)((b * 8 + hc) * 32 + (t >> 6)) * 4096 + chunk * 512 + (t & 63) * 8; }
;     __device__ __forceinline__ void operator()(const f32x4 (&acc)[2][2][4][2], const Unit& u, int wr, int wc, int fr, int fq) const {
;     ...
;                 for (int m = 0; m < 4; ++m) { const int row = row0 + ai * HALF + m * 16; const float r = rs[ai * 4 + m] * sc; const float pf = (float)ps[ai * 4 + m];
;                     float c[8], sn[8];
; #pragma unroll
;                     for (int e = 0; e < 8; ++e) { const float rev = __builtin_amdgcn_fractf((pf * invf[e]) * 0.15915494309189535f); c[e] = mine ? __builtin_amdgcn_cosf(rev) : 1.f; sn[e] = mine ? __builtin_amdgcn_sinf(rev) * sgn : 0.f; }
; #pragma unroll
;                     for (int bj = 0; bj < 2; ++bj) { f32x4 v0 = acc[ai][bj][m][0] * r, v1 = acc[ai][bj][m][1] * r; f32x4 p0, p1;
; #pragma unroll
;                         for (int e = 0; e < 4; ++e) { p0[e] = __shfl_xor(v0[e], 16); p1[e] = __shfl_xor(v1[e], 16); }
; #pragma unroll
;                         for (int e = 0; e < 4; ++e) { v0[e] = v0[e] * c[e] + p0[e] * sn[e]; v1[e] = v1[e] * c[4 + e] + p1[e] * sn[4 + e]; }
;                         *(u32x4*)dst(u, row, bj, wc, fq, col0) = pack8(v0, v1); } }
.LBB0_322:
	s_waitcnt vmcnt(11)
	v_cvt_f32_i32_e32 v60, v130
	v_lshl_add_u64 v[52:53], v[154:155], 1, v[52:53]
	global_store_dwordx4 v[52:53], v[48:51], off nt
	s_and_b64 vcc, exec, s[42:43]
	s_mov_b64 s[28:29], -1
	v_mul_f32_e32 v48, 0.15915494, v60
	v_fract_f32_e32 v48, v48
	v_cos_f32_e32 v50, v48
	v_mul_f32_e32 v49, 0x3e4693af, v60
	v_mul_f32_e32 v49, 0.15915494, v49
	v_sin_f32_e32 v48, v48
	v_fract_f32_e32 v49, v49
	v_cndmask_b32_e64 v52, 1.0, v50, s[0:1]
	v_cos_f32_e32 v50, v49
	v_sin_f32_e32 v49, v49
	v_cndmask_b32_e64 v48, v48, -v48, s[40:41]
	v_cndmask_b32_e64 v56, 0, v48, s[0:1]
	v_cndmask_b32_e64 v53, 1.0, v50, s[0:1]
	v_cndmask_b32_e64 v48, v49, -v49, s[40:41]
	v_cndmask_b32_e64 v54, 0, v48, s[0:1]
	v_mul_f32_e32 v48, 0x3d1a08c8, v60
	v_mul_f32_e32 v48, 0.15915494, v48
	v_fract_f32_e32 v48, v48
	v_cos_f32_e32 v49, v48
	v_sin_f32_e32 v48, v48
	v_mul_f32_e32 v50, 0x3beef74e, v60
	v_mul_f32_e32 v50, 0.15915494, v50
	v_cndmask_b32_e64 v57, 1.0, v49, s[0:1]
	v_mul_f32_e32 v49, 0x3ab95d22, v60
	v_fract_f32_e32 v50, v50
	v_cndmask_b32_e64 v48, v48, -v48, s[40:41]
	v_mul_f32_e32 v49, 0.15915494, v49
	v_cndmask_b32_e64 v58, 0, v48, s[0:1]
	v_sin_f32_e32 v48, v50
	v_fract_f32_e32 v49, v49
	v_cos_f32_e32 v51, v50
	v_cos_f32_e32 v50, v49
	v_sin_f32_e32 v49, v49
	v_cndmask_b32_e64 v48, v48, -v48, s[40:41]
	v_cndmask_b32_e64 v59, 0, v48, s[0:1]
	v_cndmask_b32_e64 v61, 1.0, v50, s[0:1]
	v_cndmask_b32_e64 v48, v49, -v49, s[40:41]
	v_cndmask_b32_e64 v62, 0, v48, s[0:1]
	v_mul_f32_e32 v48, 0x398fc8f8, v60
	v_mul_f32_e32 v48, 0.15915494, v48
	v_fract_f32_e32 v48, v48
	v_cos_f32_e32 v49, v48
	v_sin_f32_e32 v48, v48
	v_mul_f32_e32 v50, 0x385f10c4, v60
	v_mul_f32_e32 v50, 0.15915494, v50
	v_cndmask_b32_e64 v64, 1.0, v49, s[0:1]
	v_mul_f32_e32 v49, 0x372d07a7, v60
	v_mul_f32_e32 v49, 0.15915494, v49
	v_fract_f32_e32 v50, v50
	v_cndmask_b32_e64 v48, v48, -v48, s[40:41]
	v_fract_f32_e32 v49, v49
	v_cndmask_b32_e64 v55, 1.0, v51, s[0:1]
	v_cos_f32_e32 v51, v50
	v_cndmask_b32_e64 v67, 0, v48, s[0:1]
	v_sin_f32_e32 v48, v50
	v_cos_f32_e32 v50, v49
	v_sin_f32_e32 v49, v49
	v_cndmask_b32_e64 v63, 1.0, v51, s[0:1]
	v_cndmask_b32_e64 v48, v48, -v48, s[40:41]
	v_cndmask_b32_e64 v65, 1.0, v50, s[0:1]
	v_mul_f32_e32 v50, v149, v157
	v_pk_mul_f32 v[44:45], v[44:45], v[50:51] op_sel_hi:[1,0]
	v_cndmask_b32_e64 v69, 0, v48, s[0:1]
	v_cndmask_b32_e64 v48, v49, -v49, s[40:41]
	v_pk_mul_f32 v[40:41], v[40:41], v[50:51] op_sel_hi:[1,0]
	ds_bpermute_b32 v49, v145, v44
	v_pk_mul_f32 v[46:47], v[46:47], v[50:51] op_sel_hi:[1,0]
	v_pk_mul_f32 v[42:43], v[42:43], v[50:51] op_sel_hi:[1,0]
	ds_bpermute_b32 v51, v145, v40
	ds_bpermute_b32 v70, v145, v45
	ds_bpermute_b32 v71, v145, v41
	ds_bpermute_b32 v72, v145, v46
	ds_bpermute_b32 v73, v145, v42
	s_waitcnt lgkmcnt(5)
	v_mul_f32_e32 v49, v56, v49
	ds_bpermute_b32 v74, v145, v47
	v_fmac_f32_e32 v49, v44, v52
	s_waitcnt lgkmcnt(5)
	v_mul_f32_e32 v44, v62, v51
	ds_bpermute_b32 v75, v145, v43
	v_fmac_f32_e32 v44, v40, v61
	s_waitcnt lgkmcnt(5)
	v_mul_f32_e32 v40, v54, v70
	v_fmac_f32_e32 v40, v45, v53
	s_waitcnt lgkmcnt(4)
	v_mul_f32_e32 v45, v67, v71
	v_fmac_f32_e32 v45, v41, v64
	s_waitcnt lgkmcnt(3)
	v_mul_f32_e32 v41, v58, v72
	v_fmac_f32_e32 v41, v46, v57
	s_waitcnt lgkmcnt(2)
	v_mul_f32_e32 v46, v69, v73
	v_cndmask_b32_e64 v68, 0, v48, s[0:1]
	v_lshrrev_b32_e32 v48, 6, v150
	v_fmac_f32_e32 v46, v42, v63
	s_waitcnt lgkmcnt(1)
	v_mul_f32_e32 v42, v59, v74
	v_and_or_b32 v60, v48, 31, v66
	v_lshlrev_b32_e32 v48, 3, v150
	v_fmac_f32_e32 v42, v47, v55
	s_waitcnt lgkmcnt(0)
	v_mul_f32_e32 v47, v68, v75
	v_and_b32_e32 v48, 0xf8, v48
	v_fmac_f32_e32 v47, v43, v65
	v_cvt_pk_bf16_f32 v40, v49, v40
	v_cvt_pk_bf16_f32 v41, v41, v42
	v_cvt_pk_bf16_f32 v42, v44, v45
	v_cvt_pk_bf16_f32 v43, v46, v47
	s_cbranch_vccnz .LBB0_324
	s_lshl_b32 s21, s19, 5
	s_lshl_b32 s28, s8, 7
	s_or_b32 s21, s28, s21
	s_addk_i32 s21, 0xff00
	v_add_u32_e32 v44, s21, v60
	v_ashrrev_i32_e32 v45, 31, v44
	v_lshlrev_b64 v[44:45], 13, v[44:45]
	v_lshl_add_u64 v[44:45], s[14:15], 0, v[44:45]
	v_mov_b32_e32 v49, v195
	v_lshl_add_u64 v[44:45], v[44:45], 0, v[194:195]
	s_mov_b64 s[28:29], 0
	v_mov_b64_e32 v[46:47], v[48:49]

; __device__ __forceinline__ u32x4 pack8(const f32x4 v0, const f32x4 v1) { u32x4 w; w.x = cvt_pk_bf16(v0[0], v0[1]); w.y = cvt_pk_bf16(v0[2], v0[3]); w.z = cvt_pk_bf16(v1[0], v1[1]); w.w = cvt_pk_bf16(v1[2], v1[3]); return w; }
;     __device__ __forceinline__ bf16_t* dst(const Unit& u, int row, int bj, int wc, int fq, int col0) const {
;         if (u.pn < 2 || u.pn >= 6) return O + (size_t)row * ldc + col0 + bj * HALF;
;         const int b = row >> 11, t = row & 2047;
;         if (u.pn < 4) { const int hc = (u.pn - 2) * 4 + bj * 2 + (wc >> 1), chunk = (wc & 1) * 4 + fq;
;             return KC + (size_t)((b * 8 + hc) * 32 + (t >> 6)) * 4096 + chunk * 512 + (t & 63) * 8; }
;     __device__ __forceinline__ void operator()(const f32x4 (&acc)[2][2][4][2], const Unit& u, int wr, int wc, int fr, int fq) const {
;     ...
;                     for (int bj = 0; bj < 2; ++bj) { f32x4 v0 = acc[ai][bj][m][0] * r, v1 = acc[ai][bj][m][1] * r; f32x4 p0, p1;
; #pragma unroll
;                         for (int e = 0; e < 4; ++e) { p0[e] = __shfl_xor(v0[e], 16); p1[e] = __shfl_xor(v1[e], 16); }
; #pragma unroll
;                         for (int e = 0; e < 4; ++e) { v0[e] = v0[e] * c[e] + p0[e] * sn[e]; v1[e] = v1[e] * c[4 + e] + p1[e] * sn[4 + e]; }
;                         *(u32x4*)dst(u, row, bj, wc, fq, col0) = pack8(v0, v1); } }
.LBB0_326:
	v_mov_b32_e32 v51, v50
	v_lshl_add_u64 v[44:45], v[46:47], 1, v[44:45]
	global_store_dwordx4 v[44:45], v[40:43], off nt
	v_pk_mul_f32 v[36:37], v[36:37], v[50:51]
	v_pk_mul_f32 v[32:33], v[32:33], v[50:51]
	v_mov_b32_e32 v40, v50
	v_mov_b32_e32 v41, v50
	v_pk_mul_f32 v[38:39], v[38:39], v[40:41]
	v_pk_mul_f32 v[34:35], v[34:35], v[40:41]
	ds_bpermute_b32 v40, v145, v36
	ds_bpermute_b32 v41, v145, v32
	ds_bpermute_b32 v42, v145, v37
	ds_bpermute_b32 v43, v145, v33
	ds_bpermute_b32 v44, v145, v38
	ds_bpermute_b32 v45, v145, v34
	s_waitcnt lgkmcnt(5)
	v_mul_f32_e32 v40, v56, v40
	ds_bpermute_b32 v46, v145, v39
	v_fmac_f32_e32 v40, v36, v52
	s_waitcnt lgkmcnt(5)
	v_mul_f32_e32 v36, v62, v41
	ds_bpermute_b32 v47, v145, v35
	v_fmac_f32_e32 v36, v32, v61
	s_waitcnt lgkmcnt(5)
	v_mul_f32_e32 v32, v54, v42
	v_fmac_f32_e32 v32, v37, v53
	s_waitcnt lgkmcnt(4)
	v_mul_f32_e32 v37, v67, v43
	v_fmac_f32_e32 v37, v33, v64
	s_waitcnt lgkmcnt(3)
	v_mul_f32_e32 v33, v58, v44
	v_fmac_f32_e32 v33, v38, v57
	s_waitcnt lgkmcnt(2)
	v_mul_f32_e32 v38, v69, v45
	v_fmac_f32_e32 v38, v34, v63
	s_waitcnt lgkmcnt(1)
	v_mul_f32_e32 v34, v59, v46
	v_fmac_f32_e32 v34, v39, v55
	s_waitcnt lgkmcnt(0)
	v_mul_f32_e32 v39, v68, v47
	s_and_b64 vcc, exec, s[42:43]
	s_mov_b64 s[28:29], -1
	v_fmac_f32_e32 v39, v35, v65
	v_cvt_pk_bf16_f32 v32, v40, v32
	v_cvt_pk_bf16_f32 v33, v33, v34
	v_cvt_pk_bf16_f32 v34, v36, v37
	v_cvt_pk_bf16_f32 v35, v38, v39
	s_cbranch_vccnz .LBB0_328
	s_lshl_b32 s21, s19, 5
	s_lshl_b32 s28, s8, 7
	s_or_b32 s21, s28, s21
	s_addk_i32 s21, 0xff40
	v_add_u32_e32 v36, s21, v60
	v_ashrrev_i32_e32 v37, 31, v36
	v_lshlrev_b64 v[36:37], 13, v[36:37]
	v_lshl_add_u64 v[36:37], s[14:15], 0, v[36:37]
	v_lshl_add_u64 v[36:37], v[36:37], 0, v[194:195]
	v_mov_b32_e32 v49, v195
	s_mov_b64 s[28:29], 0

; __device__ __forceinline__ u32x4 pack8(const f32x4 v0, const f32x4 v1) { u32x4 w; w.x = cvt_pk_bf16(v0[0], v0[1]); w.y = cvt_pk_bf16(v0[2], v0[3]); w.z = cvt_pk_bf16(v1[0], v1[1]); w.w = cvt_pk_bf16(v1[2], v1[3]); return w; }
;     __device__ __forceinline__ bf16_t* dst(const Unit& u, int row, int bj, int wc, int fq, int col0) const {
;         if (u.pn < 2 || u.pn >= 6) return O + (size_t)row * ldc + col0 + bj * HALF;
;         const int b = row >> 11, t = row & 2047;
;         if (u.pn < 4) { const int hc = (u.pn - 2) * 4 + bj * 2 + (wc >> 1), chunk = (wc & 1) * 4 + fq;
;             return KC + (size_t)((b * 8 + hc) * 32 + (t >> 6)) * 4096 + chunk * 512 + (t & 63) * 8; }
;     __device__ __forceinline__ void operator()(const f32x4 (&acc)[2][2][4][2], const Unit& u, int wr, int wc, int fr, int fq) const {
;     ...
;                 for (int m = 0; m < 4; ++m) { const int row = row0 + ai * HALF + m * 16; const float r = rs[ai * 4 + m] * sc; const float pf = (float)ps[ai * 4 + m];
;                     float c[8], sn[8];
; #pragma unroll
;                     for (int e = 0; e < 8; ++e) { const float rev = __builtin_amdgcn_fractf((pf * invf[e]) * 0.15915494309189535f); c[e] = mine ? __builtin_amdgcn_cosf(rev) : 1.f; sn[e] = mine ? __builtin_amdgcn_sinf(rev) * sgn : 0.f; }
; #pragma unroll
;                     for (int bj = 0; bj < 2; ++bj) { f32x4 v0 = acc[ai][bj][m][0] * r, v1 = acc[ai][bj][m][1] * r; f32x4 p0, p1;
; #pragma unroll
;                         for (int e = 0; e < 4; ++e) { p0[e] = __shfl_xor(v0[e], 16); p1[e] = __shfl_xor(v1[e], 16); }
; #pragma unroll
;                         for (int e = 0; e < 4; ++e) { v0[e] = v0[e] * c[e] + p0[e] * sn[e]; v1[e] = v1[e] * c[4 + e] + p1[e] * sn[4 + e]; }
;                         *(u32x4*)dst(u, row, bj, wc, fq, col0) = pack8(v0, v1); } }
.LBB0_330:
	s_waitcnt vmcnt(12)
	v_cvt_f32_i32_e32 v44, v129
	v_lshl_add_u64 v[36:37], v[48:49], 1, v[36:37]
	global_store_dwordx4 v[36:37], v[32:35], off nt
	s_and_b64 vcc, exec, s[42:43]
	s_mov_b64 s[28:29], -1
	v_mul_f32_e32 v32, 0.15915494, v44
	v_fract_f32_e32 v32, v32
	v_cos_f32_e32 v34, v32
	v_mul_f32_e32 v33, 0x3e4693af, v44
	v_mul_f32_e32 v33, 0.15915494, v33
	v_sin_f32_e32 v32, v32
	v_fract_f32_e32 v33, v33
	v_cndmask_b32_e64 v36, 1.0, v34, s[0:1]
	v_cos_f32_e32 v34, v33
	v_sin_f32_e32 v33, v33
	v_cndmask_b32_e64 v32, v32, -v32, s[40:41]
	v_cndmask_b32_e64 v40, 0, v32, s[0:1]
	v_cndmask_b32_e64 v37, 1.0, v34, s[0:1]
	v_cndmask_b32_e64 v32, v33, -v33, s[40:41]
	v_cndmask_b32_e64 v38, 0, v32, s[0:1]
	v_mul_f32_e32 v32, 0x3d1a08c8, v44
	v_mul_f32_e32 v32, 0.15915494, v32
	v_fract_f32_e32 v32, v32
	v_cos_f32_e32 v33, v32
	v_sin_f32_e32 v32, v32
	v_mul_f32_e32 v34, 0x3beef74e, v44
	v_mul_f32_e32 v34, 0.15915494, v34
	v_cndmask_b32_e64 v41, 1.0, v33, s[0:1]
	v_mul_f32_e32 v33, 0x3ab95d22, v44
	v_fract_f32_e32 v34, v34
	v_cndmask_b32_e64 v32, v32, -v32, s[40:41]
	v_mul_f32_e32 v33, 0.15915494, v33
	v_cndmask_b32_e64 v42, 0, v32, s[0:1]
	v_sin_f32_e32 v32, v34
	v_fract_f32_e32 v33, v33
	v_cos_f32_e32 v35, v34
	v_cos_f32_e32 v34, v33
	v_sin_f32_e32 v33, v33
	v_cndmask_b32_e64 v32, v32, -v32, s[40:41]
	v_cndmask_b32_e64 v43, 0, v32, s[0:1]
	v_cndmask_b32_e64 v45, 1.0, v34, s[0:1]
	v_cndmask_b32_e64 v32, v33, -v33, s[40:41]
	v_cndmask_b32_e64 v46, 0, v32, s[0:1]
	v_mul_f32_e32 v32, 0x398fc8f8, v44
	v_mul_f32_e32 v32, 0.15915494, v32
	v_fract_f32_e32 v32, v32
	v_cos_f32_e32 v33, v32
	v_sin_f32_e32 v32, v32
	v_mul_f32_e32 v34, 0x385f10c4, v44
	v_mul_f32_e32 v34, 0.15915494, v34
	v_cndmask_b32_e64 v48, 1.0, v33, s[0:1]
	v_mul_f32_e32 v33, 0x372d07a7, v44
	v_mul_f32_e32 v33, 0.15915494, v33
	v_fract_f32_e32 v34, v34
	v_cndmask_b32_e64 v32, v32, -v32, s[40:41]
	v_fract_f32_e32 v33, v33
	v_cndmask_b32_e64 v39, 1.0, v35, s[0:1]
	v_cos_f32_e32 v35, v34
	v_cndmask_b32_e64 v50, 0, v32, s[0:1]
	v_sin_f32_e32 v32, v34
	v_cos_f32_e32 v34, v33
	v_sin_f32_e32 v33, v33
	v_cndmask_b32_e64 v47, 1.0, v35, s[0:1]
	v_cndmask_b32_e64 v32, v32, -v32, s[40:41]
	v_cndmask_b32_e64 v49, 1.0, v34, s[0:1]
	v_mul_f32_e32 v34, v149, v153
	v_pk_mul_f32 v[28:29], v[28:29], v[34:35] op_sel_hi:[1,0]
	v_cndmask_b32_e64 v52, 0, v32, s[0:1]
	v_cndmask_b32_e64 v32, v33, -v33, s[40:41]
	v_pk_mul_f32 v[24:25], v[24:25], v[34:35] op_sel_hi:[1,0]
	ds_bpermute_b32 v33, v145, v28
	v_pk_mul_f32 v[30:31], v[30:31], v[34:35] op_sel_hi:[1,0]
	v_pk_mul_f32 v[26:27], v[26:27], v[34:35] op_sel_hi:[1,0]
	ds_bpermute_b32 v35, v145, v24
	ds_bpermute_b32 v53, v145, v29
	ds_bpermute_b32 v54, v145, v25
	ds_bpermute_b32 v55, v145, v30
	ds_bpermute_b32 v56, v145, v26
	s_waitcnt lgkmcnt(5)
	v_mul_f32_e32 v33, v40, v33
	ds_bpermute_b32 v57, v145, v31
	v_fmac_f32_e32 v33, v28, v36
	s_waitcnt lgkmcnt(5)
	v_mul_f32_e32 v28, v46, v35
	ds_bpermute_b32 v58, v145, v27
	v_fmac_f32_e32 v28, v24, v45
	s_waitcnt lgkmcnt(5)
	v_mul_f32_e32 v24, v38, v53
	v_fmac_f32_e32 v24, v29, v37
	s_waitcnt lgkmcnt(4)
	v_mul_f32_e32 v29, v50, v54
	v_fmac_f32_e32 v29, v25, v48
	s_waitcnt lgkmcnt(3)
	v_mul_f32_e32 v25, v42, v55
	v_fmac_f32_e32 v25, v30, v41
	s_waitcnt lgkmcnt(2)
	v_mul_f32_e32 v30, v52, v56
	v_cndmask_b32_e64 v51, 0, v32, s[0:1]
	v_lshrrev_b32_e32 v32, 6, v148
	v_fmac_f32_e32 v30, v26, v47
	s_waitcnt lgkmcnt(1)
	v_mul_f32_e32 v26, v43, v57
	v_and_or_b32 v44, v32, 31, v66
	v_lshlrev_b32_e32 v32, 3, v148
	v_fmac_f32_e32 v26, v31, v39
	s_waitcnt lgkmcnt(0)
	v_mul_f32_e32 v31, v51, v58
	v_and_b32_e32 v32, 0x178, v32
	v_fmac_f32_e32 v31, v27, v49
	v_cvt_pk_bf16_f32 v24, v33, v24
	v_cvt_pk_bf16_f32 v25, v25, v26
	v_cvt_pk_bf16_f32 v26, v28, v29
	v_cvt_pk_bf16_f32 v27, v30, v31
	s_cbranch_vccnz .LBB0_332
	s_lshl_b32 s21, s19, 5
	s_lshl_b32 s28, s8, 7
	s_or_b32 s21, s28, s21
	s_addk_i32 s21, 0xff00
	v_add_u32_e32 v28, s21, v44
	v_ashrrev_i32_e32 v29, 31, v28
	v_lshlrev_b64 v[28:29], 13, v[28:29]
	v_lshl_add_u64 v[28:29], s[14:15], 0, v[28:29]
	v_mov_b32_e32 v33, v195
	v_lshl_add_u64 v[28:29], v[28:29], 0, v[194:195]
	s_mov_b64 s[28:29], 0
	v_mov_b64_e32 v[30:31], v[32:33]

; __device__ __forceinline__ u32x4 pack8(const f32x4 v0, const f32x4 v1) { u32x4 w; w.x = cvt_pk_bf16(v0[0], v0[1]); w.y = cvt_pk_bf16(v0[2], v0[3]); w.z = cvt_pk_bf16(v1[0], v1[1]); w.w = cvt_pk_bf16(v1[2], v1[3]); return w; }
;     __device__ __forceinline__ bf16_t* dst(const Unit& u, int row, int bj, int wc, int fq, int col0) const {
;         if (u.pn < 2 || u.pn >= 6) return O + (size_t)row * ldc + col0 + bj * HALF;
;         const int b = row >> 11, t = row & 2047;
;         if (u.pn < 4) { const int hc = (u.pn - 2) * 4 + bj * 2 + (wc >> 1), chunk = (wc & 1) * 4 + fq;
;             return KC + (size_t)((b * 8 + hc) * 32 + (t >> 6)) * 4096 + chunk * 512 + (t & 63) * 8; }
;     __device__ __forceinline__ void operator()(const f32x4 (&acc)[2][2][4][2], const Unit& u, int wr, int wc, int fr, int fq) const {
;     ...
;                     for (int bj = 0; bj < 2; ++bj) { f32x4 v0 = acc[ai][bj][m][0] * r, v1 = acc[ai][bj][m][1] * r; f32x4 p0, p1;
; #pragma unroll
;                         for (int e = 0; e < 4; ++e) { p0[e] = __shfl_xor(v0[e], 16); p1[e] = __shfl_xor(v1[e], 16); }
; #pragma unroll
;                         for (int e = 0; e < 4; ++e) { v0[e] = v0[e] * c[e] + p0[e] * sn[e]; v1[e] = v1[e] * c[4 + e] + p1[e] * sn[4 + e]; }
;                         *(u32x4*)dst(u, row, bj, wc, fq, col0) = pack8(v0, v1); } }
.LBB0_334:
	v_mov_b32_e32 v35, v34
	v_lshl_add_u64 v[28:29], v[30:31], 1, v[28:29]
	global_store_dwordx4 v[28:29], v[24:27], off nt
	v_pk_mul_f32 v[20:21], v[20:21], v[34:35]
	v_pk_mul_f32 v[16:17], v[16:17], v[34:35]
	v_mov_b32_e32 v24, v34
	v_mov_b32_e32 v25, v34
	v_pk_mul_f32 v[22:23], v[22:23], v[24:25]
	v_pk_mul_f32 v[18:19], v[18:19], v[24:25]
	ds_bpermute_b32 v24, v145, v20
	ds_bpermute_b32 v25, v145, v16
	ds_bpermute_b32 v26, v145, v21
	ds_bpermute_b32 v27, v145, v17
	ds_bpermute_b32 v28, v145, v22
	ds_bpermute_b32 v29, v145, v18
	s_waitcnt lgkmcnt(5)
	v_mul_f32_e32 v24, v40, v24
	ds_bpermute_b32 v30, v145, v23
	v_fmac_f32_e32 v24, v20, v36
	s_waitcnt lgkmcnt(5)
	v_mul_f32_e32 v20, v46, v25
	ds_bpermute_b32 v31, v145, v19
	v_fmac_f32_e32 v20, v16, v45
	s_waitcnt lgkmcnt(5)
	v_mul_f32_e32 v16, v38, v26
	v_fmac_f32_e32 v16, v21, v37
	s_waitcnt lgkmcnt(4)
	v_mul_f32_e32 v21, v50, v27
	v_fmac_f32_e32 v21, v17, v48
	s_waitcnt lgkmcnt(3)
	v_mul_f32_e32 v17, v42, v28
	v_fmac_f32_e32 v17, v22, v41
	s_waitcnt lgkmcnt(2)
	v_mul_f32_e32 v22, v52, v29
	v_fmac_f32_e32 v22, v18, v47
	s_waitcnt lgkmcnt(1)
	v_mul_f32_e32 v18, v43, v30
	v_fmac_f32_e32 v18, v23, v39
	s_waitcnt lgkmcnt(0)
	v_mul_f32_e32 v23, v51, v31
	s_and_b64 vcc, exec, s[42:43]
	s_mov_b64 s[28:29], -1
	v_fmac_f32_e32 v23, v19, v49
	v_cvt_pk_bf16_f32 v16, v24, v16
	v_cvt_pk_bf16_f32 v17, v17, v18
	v_cvt_pk_bf16_f32 v18, v20, v21
	v_cvt_pk_bf16_f32 v19, v22, v23
	s_cbranch_vccnz .LBB0_336
	s_lshl_b32 s21, s19, 5
	s_lshl_b32 s28, s8, 7
	s_or_b32 s21, s28, s21
	s_addk_i32 s21, 0xff40
	v_add_u32_e32 v20, s21, v44
	v_ashrrev_i32_e32 v21, 31, v20
	v_lshlrev_b64 v[20:21], 13, v[20:21]
	v_lshl_add_u64 v[20:21], s[14:15], 0, v[20:21]
	v_lshl_add_u64 v[20:21], v[20:21], 0, v[194:195]
	v_mov_b32_e32 v33, v195
	s_mov_b64 s[28:29], 0

; __device__ __forceinline__ u32x4 pack8(const f32x4 v0, const f32x4 v1) { u32x4 w; w.x = cvt_pk_bf16(v0[0], v0[1]); w.y = cvt_pk_bf16(v0[2], v0[3]); w.z = cvt_pk_bf16(v1[0], v1[1]); w.w = cvt_pk_bf16(v1[2], v1[3]); return w; }
;     __device__ __forceinline__ bf16_t* dst(const Unit& u, int row, int bj, int wc, int fq, int col0) const {
;         if (u.pn < 2 || u.pn >= 6) return O + (size_t)row * ldc + col0 + bj * HALF;
;         const int b = row >> 11, t = row & 2047;
;         if (u.pn < 4) { const int hc = (u.pn - 2) * 4 + bj * 2 + (wc >> 1), chunk = (wc & 1) * 4 + fq;
;             return KC + (size_t)((b * 8 + hc) * 32 + (t >> 6)) * 4096 + chunk * 512 + (t & 63) * 8; }
;     __device__ __forceinline__ void operator()(const f32x4 (&acc)[2][2][4][2], const Unit& u, int wr, int wc, int fr, int fq) const {
;     ...
;                 for (int m = 0; m < 4; ++m) { const int row = row0 + ai * HALF + m * 16; const float r = rs[ai * 4 + m] * sc; const float pf = (float)ps[ai * 4 + m];
;                     float c[8], sn[8];
; #pragma unroll
;                     for (int e = 0; e < 8; ++e) { const float rev = __builtin_amdgcn_fractf((pf * invf[e]) * 0.15915494309189535f); c[e] = mine ? __builtin_amdgcn_cosf(rev) : 1.f; sn[e] = mine ? __builtin_amdgcn_sinf(rev) * sgn : 0.f; }
; #pragma unroll
;                     for (int bj = 0; bj < 2; ++bj) { f32x4 v0 = acc[ai][bj][m][0] * r, v1 = acc[ai][bj][m][1] * r; f32x4 p0, p1;
; #pragma unroll
;                         for (int e = 0; e < 4; ++e) { p0[e] = __shfl_xor(v0[e], 16); p1[e] = __shfl_xor(v1[e], 16); }
; #pragma unroll
;                         for (int e = 0; e < 4; ++e) { v0[e] = v0[e] * c[e] + p0[e] * sn[e]; v1[e] = v1[e] * c[4 + e] + p1[e] * sn[4 + e]; }
;                         *(u32x4*)dst(u, row, bj, wc, fq, col0) = pack8(v0, v1); } }
.LBB0_338:
	s_waitcnt vmcnt(13)
	v_cvt_f32_i32_e32 v27, v128
	v_lshl_add_u64 v[20:21], v[32:33], 1, v[20:21]
	global_store_dwordx4 v[20:21], v[16:19], off nt
	s_and_b64 vcc, exec, s[42:43]
	v_mul_f32_e32 v21, 0x3beef74e, v27
	v_mul_f32_e32 v16, 0.15915494, v27
	v_mul_f32_e32 v17, 0x3e4693af, v27
	v_fract_f32_e32 v16, v16
	v_mul_f32_e32 v17, 0.15915494, v17
	v_cos_f32_e32 v18, v16
	v_sin_f32_e32 v16, v16
	v_fract_f32_e32 v17, v17
	v_cos_f32_e32 v19, v17
	v_sin_f32_e32 v17, v17
	v_cndmask_b32_e64 v16, v16, -v16, s[40:41]
	v_cndmask_b32_e64 v22, 0, v16, s[0:1]
	v_mul_f32_e32 v21, 0.15915494, v21
	v_cndmask_b32_e64 v16, v17, -v17, s[40:41]
	v_cndmask_b32_e64 v20, 0, v16, s[0:1]
	v_mul_f32_e32 v16, 0x3d1a08c8, v27
	v_mul_f32_e32 v16, 0.15915494, v16
	v_fract_f32_e32 v16, v16
	v_cos_f32_e32 v17, v16
	v_sin_f32_e32 v16, v16
	v_fract_f32_e32 v25, v21
	v_cos_f32_e32 v21, v25
	v_cndmask_b32_e64 v23, 1.0, v17, s[0:1]
	v_mul_f32_e32 v17, 0x3ab95d22, v27
	v_cndmask_b32_e64 v16, v16, -v16, s[40:41]
	v_mul_f32_e32 v17, 0.15915494, v17
	v_cndmask_b32_e64 v24, 0, v16, s[0:1]
	v_sin_f32_e32 v16, v25
	v_fract_f32_e32 v17, v17
	v_cos_f32_e32 v26, v17
	v_sin_f32_e32 v17, v17
	v_cndmask_b32_e64 v16, v16, -v16, s[40:41]
	v_cndmask_b32_e64 v25, 0, v16, s[0:1]
	v_mul_f32_e32 v29, 0x385f10c4, v27
	v_cndmask_b32_e64 v16, v17, -v17, s[40:41]
	v_cndmask_b32_e64 v28, 0, v16, s[0:1]
	v_mul_f32_e32 v16, 0x398fc8f8, v27
	v_mul_f32_e32 v16, 0.15915494, v16
	v_fract_f32_e32 v16, v16
	v_cos_f32_e32 v17, v16
	v_sin_f32_e32 v16, v16
	v_mul_f32_e32 v29, 0.15915494, v29
	v_fract_f32_e32 v31, v29
	v_cndmask_b32_e64 v30, 1.0, v17, s[0:1]
	v_mul_f32_e32 v17, 0x372d07a7, v27
	v_cndmask_b32_e64 v16, v16, -v16, s[40:41]
	v_mul_f32_e32 v17, 0.15915494, v17
	v_cndmask_b32_e64 v32, 0, v16, s[0:1]
	v_sin_f32_e32 v16, v31
	v_fract_f32_e32 v17, v17
	v_cos_f32_e32 v27, v17
	v_sin_f32_e32 v17, v17
	v_cndmask_b32_e64 v16, v16, -v16, s[40:41]
	v_cndmask_b32_e64 v34, 0, v16, s[0:1]
	v_cos_f32_e32 v29, v31
	v_cndmask_b32_e64 v16, v17, -v17, s[40:41]
	v_lshrrev_b32_e32 v17, 6, v144
	v_cndmask_b32_e64 v31, 1.0, v27, s[0:1]
	v_cndmask_b32_e64 v33, 0, v16, s[0:1]
	v_mul_f32_e32 v16, v149, v151
	v_and_or_b32 v27, v17, 31, v66
	v_lshlrev_b32_e32 v17, 3, v144
	v_pk_mul_f32 v[12:13], v[12:13], v[16:17] op_sel_hi:[1,0]
	v_and_b32_e32 v166, 0x1f8, v17
	v_pk_mul_f32 v[14:15], v[14:15], v[16:17] op_sel_hi:[1,0]
	v_pk_mul_f32 v[10:11], v[10:11], v[16:17] op_sel_hi:[1,0]
	v_pk_mul_f32 v[8:9], v[8:9], v[16:17] op_sel_hi:[1,0]
	ds_bpermute_b32 v17, v145, v12
	ds_bpermute_b32 v35, v145, v8
	ds_bpermute_b32 v36, v145, v13
	ds_bpermute_b32 v37, v145, v9
	ds_bpermute_b32 v38, v145, v14
	v_cndmask_b32_e64 v18, 1.0, v18, s[0:1]
	ds_bpermute_b32 v39, v145, v10
	s_waitcnt lgkmcnt(5)
	v_mul_f32_e32 v17, v22, v17
	v_cndmask_b32_e64 v26, 1.0, v26, s[0:1]
	ds_bpermute_b32 v40, v145, v15
	v_fmac_f32_e32 v17, v12, v18
	s_waitcnt lgkmcnt(5)
	v_mul_f32_e32 v12, v28, v35
	v_cndmask_b32_e64 v19, 1.0, v19, s[0:1]
	ds_bpermute_b32 v41, v145, v11
	v_fmac_f32_e32 v12, v8, v26
	s_waitcnt lgkmcnt(5)
	v_mul_f32_e32 v8, v20, v36
	v_fmac_f32_e32 v8, v13, v19
	s_waitcnt lgkmcnt(4)
	v_mul_f32_e32 v13, v32, v37
	v_fmac_f32_e32 v13, v9, v30
	s_waitcnt lgkmcnt(3)
	v_mul_f32_e32 v9, v24, v38
	v_cndmask_b32_e64 v29, 1.0, v29, s[0:1]
	v_fmac_f32_e32 v9, v14, v23
	s_waitcnt lgkmcnt(2)
	v_mul_f32_e32 v14, v34, v39
	v_cndmask_b32_e64 v21, 1.0, v21, s[0:1]
	v_fmac_f32_e32 v14, v10, v29
	s_waitcnt lgkmcnt(1)
	v_mul_f32_e32 v10, v25, v40
	v_fmac_f32_e32 v10, v15, v21
	s_waitcnt lgkmcnt(0)
	v_mul_f32_e32 v15, v33, v41
	v_fmac_f32_e32 v15, v11, v31
	s_mov_b64 s[0:1], -1
	v_cvt_pk_bf16_f32 v8, v17, v8
	v_cvt_pk_bf16_f32 v9, v9, v10
	v_cvt_pk_bf16_f32 v10, v12, v13
	v_cvt_pk_bf16_f32 v11, v14, v15
	s_cbranch_vccnz .LBB0_340
	s_lshl_b32 s0, s19, 5
	s_lshl_b32 s1, s8, 7
	s_or_b32 s0, s1, s0
	s_addk_i32 s0, 0xff00
	v_add_u32_e32 v12, s0, v27
	v_ashrrev_i32_e32 v13, 31, v12
	v_lshlrev_b64 v[12:13], 13, v[12:13]
	v_lshl_add_u64 v[12:13], s[14:15], 0, v[12:13]
	v_mov_b32_e32 v167, v195
	v_lshl_add_u64 v[12:13], v[12:13], 0, v[194:195]
	s_mov_b64 s[0:1], 0
	v_mov_b64_e32 v[14:15], v[166:167]

; __device__ __forceinline__ u32x4 pack8(const f32x4 v0, const f32x4 v1) { u32x4 w; w.x = cvt_pk_bf16(v0[0], v0[1]); w.y = cvt_pk_bf16(v0[2], v0[3]); w.z = cvt_pk_bf16(v1[0], v1[1]); w.w = cvt_pk_bf16(v1[2], v1[3]); return w; }
;     __device__ __forceinline__ bf16_t* dst(const Unit& u, int row, int bj, int wc, int fq, int col0) const {
;         if (u.pn < 2 || u.pn >= 6) return O + (size_t)row * ldc + col0 + bj * HALF;
;         const int b = row >> 11, t = row & 2047;
;         if (u.pn < 4) { const int hc = (u.pn - 2) * 4 + bj * 2 + (wc >> 1), chunk = (wc & 1) * 4 + fq;
;             return KC + (size_t)((b * 8 + hc) * 32 + (t >> 6)) * 4096 + chunk * 512 + (t & 63) * 8; }
;     __device__ __forceinline__ void operator()(const f32x4 (&acc)[2][2][4][2], const Unit& u, int wr, int wc, int fr, int fq) const {
;     ...
;                     for (int bj = 0; bj < 2; ++bj) { f32x4 v0 = acc[ai][bj][m][0] * r, v1 = acc[ai][bj][m][1] * r; f32x4 p0, p1;
; #pragma unroll
;                         for (int e = 0; e < 4; ++e) { p0[e] = __shfl_xor(v0[e], 16); p1[e] = __shfl_xor(v1[e], 16); }
; #pragma unroll
;                         for (int e = 0; e < 4; ++e) { v0[e] = v0[e] * c[e] + p0[e] * sn[e]; v1[e] = v1[e] * c[4 + e] + p1[e] * sn[4 + e]; }
;                         *(u32x4*)dst(u, row, bj, wc, fq, col0) = pack8(v0, v1); } }
.LBB0_342:
	v_mov_b32_e32 v17, v16
	v_lshl_add_u64 v[12:13], v[14:15], 1, v[12:13]
	global_store_dwordx4 v[12:13], v[8:11], off nt
	v_pk_mul_f32 v[4:5], v[4:5], v[16:17]
	v_pk_mul_f32 v[0:1], v[0:1], v[16:17]
	v_mov_b32_e32 v8, v16
	v_mov_b32_e32 v9, v16
	v_pk_mul_f32 v[6:7], v[6:7], v[8:9]
	v_pk_mul_f32 v[2:3], v[2:3], v[8:9]
	ds_bpermute_b32 v8, v145, v4
	ds_bpermute_b32 v9, v145, v0
	ds_bpermute_b32 v10, v145, v5
	ds_bpermute_b32 v11, v145, v1
	ds_bpermute_b32 v12, v145, v6
	ds_bpermute_b32 v13, v145, v2
	s_waitcnt lgkmcnt(5)
	v_mul_f32_e32 v8, v22, v8
	ds_bpermute_b32 v14, v145, v7
	v_fmac_f32_e32 v8, v4, v18
	s_waitcnt lgkmcnt(5)
	v_mul_f32_e32 v4, v28, v9
	ds_bpermute_b32 v15, v145, v3
	v_fmac_f32_e32 v4, v0, v26
	s_waitcnt lgkmcnt(5)
	v_mul_f32_e32 v0, v20, v10
	v_fmac_f32_e32 v0, v5, v19
	s_waitcnt lgkmcnt(4)
	v_mul_f32_e32 v5, v32, v11
	v_fmac_f32_e32 v5, v1, v30
	s_waitcnt lgkmcnt(3)
	v_mul_f32_e32 v1, v24, v12
	v_fmac_f32_e32 v1, v6, v23
	s_waitcnt lgkmcnt(2)
	v_mul_f32_e32 v6, v34, v13
	v_fmac_f32_e32 v6, v2, v29
	s_waitcnt lgkmcnt(1)
	v_mul_f32_e32 v2, v25, v14
	v_fmac_f32_e32 v2, v7, v21
	s_waitcnt lgkmcnt(0)
	v_mul_f32_e32 v7, v33, v15
	s_and_b64 vcc, exec, s[42:43]
	s_mov_b64 s[0:1], -1
	v_fmac_f32_e32 v7, v3, v31
	v_cvt_pk_bf16_f32 v128, v8, v0
	v_cvt_pk_bf16_f32 v129, v1, v2
	v_cvt_pk_bf16_f32 v130, v4, v5
	v_cvt_pk_bf16_f32 v131, v6, v7
	s_cbranch_vccnz .LBB0_344
	s_lshl_b32 s0, s19, 5
	s_lshl_b32 s1, s8, 7
	s_or_b32 s0, s1, s0
	s_addk_i32 s0, 0xff40
	v_add_u32_e32 v0, s0, v27
	v_ashrrev_i32_e32 v1, 31, v0
	v_lshlrev_b64 v[0:1], 13, v[0:1]
	v_lshl_add_u64 v[0:1], s[14:15], 0, v[0:1]
	v_lshl_add_u64 v[168:169], v[0:1], 0, v[194:195]
	s_mov_b64 s[0:1], 0

; __device__ __forceinline__ int tid_opaque() { int t = threadIdx.x; asm volatile("" : "+v"(t)); return t; }
; __device__ __forceinline__ u32x4 pack8(const f32x4 v0, const f32x4 v1) { u32x4 w; w.x = cvt_pk_bf16(v0[0], v0[1]); w.y = cvt_pk_bf16(v0[2], v0[3]); w.z = cvt_pk_bf16(v1[0], v1[1]); w.w = cvt_pk_bf16(v1[2], v1[3]); return w; }
; #define PG8_BAR __builtin_amdgcn_s_barrier()
;     __device__ __forceinline__ void operator()(const f32x4 (&acc)[2][2][4][2], const Unit& u, int wr, int wc, int fr, int fq) const {
;     ...
;                         *(u32x4*)dst(u, row, bj, wc, fq, col0) = pack8(v0, v1); } }
;     ...
;                     for (int bj = 0; bj < 2; ++bj) *(u32x4*)dst(u, row, bj, wc, fq, col0) = pack8(acc[ai][bj][m][0] * r, acc[ai][bj][m][1] * r); }
; template <class Epi, class Sched, bool ALIGN_EPI = false, bool SP2 = false>
; __device__ __forceinline__ void gemm_phase(PG8_LAS unsigned char* lds, const Gemm g, const Sched& S, const Epi& E) {
;     ...
;         if constexpr (ALIGN_EPI) { if (wr == 0) PG8_BAR; }
;         if constexpr (!Epi::AFTER_DRAIN) { const int t2 = tid_opaque(), w2 = __builtin_amdgcn_readfirstlane(t2 >> 6), l2 = t2 & 63;
;             E(acc, cur, w2 >> 2, w2 & 3, l2 & 15, l2 >> 4); S.done(cur); }
;         if (!has_next) break;
.LBB0_346:
	v_mov_b32_e32 v167, v195
	v_lshl_add_u64 v[0:1], v[166:167], 1, v[168:169]
	s_mov_b64 s[42:43], -1
	s_andn2_b64 vcc, exec, s[22:23]
	s_mov_b64 s[0:1], -1
	global_store_dwordx4 v[0:1], v[128:131], off nt
	s_cbranch_vccnz .LBB0_142
	s_andn2_b64 vcc, exec, s[10:11]
	s_cbranch_vccnz .LBB0_141
	s_barrier
	s_branch .LBB0_141

; __device__ __forceinline__ u32x4 pack8(const f32x4 v0, const f32x4 v1) { u32x4 w; w.x = cvt_pk_bf16(v0[0], v0[1]); w.y = cvt_pk_bf16(v0[2], v0[3]); w.z = cvt_pk_bf16(v1[0], v1[1]); w.w = cvt_pk_bf16(v1[2], v1[3]); return w; }
; __device__ __forceinline__ float sumsq8(const f32x4 a, const f32x4 b) { return ((a[0] * a[0] + a[1] * a[1]) + (a[2] * a[2] + a[3] * a[3])) + ((b[0] * b[0] + b[1] * b[1]) + (b[2] * b[2] + b[3] * b[3])); }
; __device__ __forceinline__ void unpack8(const u32x4 w, f32x4& a, f32x4& b) { a = (f32x4){bf_lo(w.x), bf_hi(w.x), bf_lo(w.y), bf_hi(w.y)}; b = (f32x4){bf_lo(w.z), bf_hi(w.z), bf_lo(w.w), bf_hi(w.w)}; }
;     __device__ __forceinline__ void operator()(const f32x4 (&acc)[2][2][4][2], const Unit& u, int wr, int wc, int fr, int fq) const {
;         const int row0 = u.pm * BM + wr * 64 + fr, col0 = u.pn * BM + wc * 32 + 8 * fq;
;         u32x4 rv[8][2];
; #pragma unroll
;         for (int i = 0; i < 8; ++i)
; #pragma unroll
;             for (int bj = 0; bj < 2; ++bj) rv[i][bj] = *(const u32x4*)(Rin + (size_t)(row0 + (i >> 2) * HALF + (i & 3) * 16) * DMODEL + col0 + bj * HALF);
; #pragma unroll
;         for (int ai = 0; ai < 2; ++ai)
; #pragma unroll
;             for (int m = 0; m < 4; ++m) { const int row = row0 + ai * HALF + m * 16; float part = 0.f;
; #pragma unroll
;                 for (int bj = 0; bj < 2; ++bj) { f32x4 r0, r1; unpack8(rv[ai * 4 + m][bj], r0, r1);
;                     const f32x4 h0 = r0 + acc[ai][bj][m][0], h1 = r1 + acc[ai][bj][m][1]; part += sumsq8(h0, h1);
;                     *(u32x4*)(XBo + (size_t)row * DMODEL + col0 + bj * HALF) = pack8(h0, h1); }
;                 part += __shfl_xor(part, 16); part += __shfl_xor(part, 32);
;                 if (fq == 0) ssq[(size_t)row * 16 + u.pn * 4 + wc] = part; }
.LBB0_517:
	v_mov_b32_e32 v116, v192
	s_lshl_b32 s1, s40, 8
	v_readfirstlane_b32 s0, v116
	s_bfe_u32 s17, s0, 0x20006
	s_ashr_i32 s0, s0, 2
	s_andn2_b32 s0, s0, 63
	s_add_i32 s0, s0, s1
	v_and_or_b32 v216, v116, 15, s0
	s_lshl_b32 s0, s26, 8
	s_lshl_b32 s1, s17, 5
	v_bfe_u32 v249, v116, 4, 2
	s_or_b32 s0, s1, s0
	v_lshl_or_b32 v214, v249, 3, s0
	v_ashrrev_i32_e32 v215, 31, v214
	v_lshlrev_b64 v[234:235], 1, v[214:215]
	v_ashrrev_i32_e32 v217, 31, v216
	v_lshl_add_u64 v[120:121], s[6:7], 0, v[234:235]
	v_lshlrev_b64 v[236:237], 11, v[216:217]
	v_lshl_add_u64 v[116:117], v[120:121], 0, v[236:237]
	global_load_dwordx4 v[188:191], v[116:117], off
	global_load_dwordx4 v[184:187], v[116:117], off offset:256
	v_or_b32_e32 v230, 16, v216
	v_ashrrev_i32_e32 v231, 31, v230
	v_or_b32_e32 v226, 32, v216
	v_lshlrev_b64 v[232:233], 11, v[230:231]
	v_ashrrev_i32_e32 v227, 31, v226
	v_or_b32_e32 v222, 48, v216
	v_lshl_add_u64 v[116:117], v[120:121], 0, v[232:233]
	v_lshlrev_b64 v[228:229], 11, v[226:227]
	v_ashrrev_i32_e32 v223, 31, v222
	v_add_u32_e32 v218, 0x80, v216
	global_load_dwordx4 v[180:183], v[116:117], off
	global_load_dwordx4 v[176:179], v[116:117], off offset:256
	v_lshl_add_u64 v[116:117], v[120:121], 0, v[228:229]
	v_lshlrev_b64 v[224:225], 11, v[222:223]
	v_ashrrev_i32_e32 v219, 31, v218
	global_load_dwordx4 v[172:175], v[116:117], off
	global_load_dwordx4 v[168:171], v[116:117], off offset:256
	v_lshl_add_u64 v[116:117], v[120:121], 0, v[224:225]
	v_lshlrev_b64 v[220:221], 11, v[218:219]
	global_load_dwordx4 v[164:167], v[116:117], off
	global_load_dwordx4 v[160:163], v[116:117], off offset:256
	v_lshl_add_u64 v[116:117], v[120:121], 0, v[220:221]
	global_load_dwordx4 v[156:159], v[116:117], off
	global_load_dwordx4 v[144:147], v[116:117], off offset:256
	v_add_u32_e32 v116, 0x90, v216
	v_ashrrev_i32_e32 v117, 31, v116
	v_lshlrev_b64 v[116:117], 11, v[116:117]
	v_lshl_add_u64 v[116:117], v[120:121], 0, v[116:117]
	global_load_dwordx4 v[140:143], v[116:117], off
	global_load_dwordx4 v[136:139], v[116:117], off offset:256
	v_add_u32_e32 v116, 0xa0, v216
	v_add_u32_e32 v122, 0xb0, v216
	v_ashrrev_i32_e32 v117, 31, v116
	v_ashrrev_i32_e32 v123, 31, v122
	v_lshlrev_b64 v[116:117], 11, v[116:117]
	v_lshlrev_b64 v[122:123], 11, v[122:123]
	v_lshl_add_u64 v[116:117], v[120:121], 0, v[116:117]
	v_lshl_add_u64 v[120:121], v[120:121], 0, v[122:123]
	global_load_dwordx4 v[128:131], v[116:117], off
	s_nop 0
	global_load_dwordx4 v[116:119], v[116:117], off offset:256
	s_nop 0
	global_load_dwordx4 v[132:135], v[120:121], off
	s_nop 0
	global_load_dwordx4 v[120:123], v[120:121], off offset:256
	s_lshl_b32 s26, s26, 2
	v_cmp_eq_u32_e32 vcc, 0, v249
	s_ashr_i32 s27, s26, 31
	s_waitcnt vmcnt(14)
	v_lshlrev_b32_e32 v250, 16, v188
	v_and_b32_e32 v251, 0xffff0000, v188
	v_lshlrev_b32_e32 v188, 16, v189
	v_and_b32_e32 v189, 0xffff0000, v189
	v_lshlrev_b32_e32 v252, 16, v190
	v_and_b32_e32 v253, 0xffff0000, v190
	v_lshlrev_b32_e32 v190, 16, v191
	v_and_b32_e32 v191, 0xffff0000, v191
	v_pk_add_f32 v[154:155], v[154:155], v[188:189]
	v_pk_add_f32 v[152:153], v[152:153], v[250:251]
	v_pk_add_f32 v[188:189], v[150:151], v[190:191]
	v_pk_add_f32 v[150:151], v[148:149], v[252:253]
	v_mul_f32_e32 v148, v153, v153
	v_mul_f32_e32 v149, v155, v155
	v_fmac_f32_e32 v148, v152, v152
	v_fmac_f32_e32 v149, v154, v154
	v_add_f32_e32 v148, v148, v149
	v_mul_f32_e32 v149, v151, v151
	v_mul_f32_e32 v190, v189, v189
	v_fmac_f32_e32 v149, v150, v150
	v_fmac_f32_e32 v190, v188, v188
	v_add_f32_e32 v149, v149, v190
	v_add_f32_e32 v190, v148, v149
	v_cvt_pk_bf16_f32 v148, v152, v153
	v_lshl_add_u64 v[152:153], s[10:11], 0, v[236:237]
	v_cvt_pk_bf16_f32 v149, v154, v155
	v_cvt_pk_bf16_f32 v150, v150, v151
	v_cvt_pk_bf16_f32 v151, v188, v189
	v_lshl_add_u64 v[152:153], v[152:153], 0, v[234:235]
	global_store_dwordx4 v[152:153], v[148:151], off nt
	v_lshlrev_b32_e32 v154, 16, v186
	v_and_b32_e32 v155, 0xffff0000, v186
	v_lshlrev_b32_e32 v148, 16, v184
	v_and_b32_e32 v149, 0xffff0000, v184
	v_lshlrev_b32_e32 v150, 16, v185
	v_and_b32_e32 v151, 0xffff0000, v185
	v_lshlrev_b32_e32 v184, 16, v187
	v_and_b32_e32 v185, 0xffff0000, v187
	v_pk_add_f32 v[126:127], v[126:127], v[150:151]
	v_pk_add_f32 v[124:125], v[124:125], v[148:149]
	v_pk_add_f32 v[148:149], v[114:115], v[184:185]
	v_pk_add_f32 v[114:115], v[112:113], v[154:155]
	v_mul_f32_e32 v112, v125, v125
	v_mul_f32_e32 v113, v127, v127
	v_fmac_f32_e32 v112, v124, v124
	v_fmac_f32_e32 v113, v126, v126
	v_add_f32_e32 v112, v112, v113
	v_mul_f32_e32 v113, v115, v115
	v_mul_f32_e32 v150, v149, v149
	v_fmac_f32_e32 v113, v114, v114
	v_fmac_f32_e32 v150, v148, v148
	v_add_f32_e32 v113, v113, v150
	v_add_f32_e32 v112, v112, v113
	v_add_f32_e32 v150, v190, v112
	v_cvt_pk_bf16_f32 v112, v124, v125
	v_cvt_pk_bf16_f32 v113, v126, v127
	v_cvt_pk_bf16_f32 v114, v114, v115
	v_cvt_pk_bf16_f32 v115, v148, v149
	global_store_dwordx4 v[152:153], v[112:115], off offset:256 nt
	s_nop 1
	v_and_b32_e32 v113, 64, v241
	v_xor_b32_e32 v112, 16, v241
	v_add_u32_e32 v113, 64, v113
	v_cmp_lt_i32_e64 s[0:1], v112, v113
	v_xor_b32_e32 v115, 32, v241
	s_nop 0
	v_cndmask_b32_e64 v112, v241, v112, s[0:1]
	v_lshlrev_b32_e32 v112, 2, v112
	ds_bpermute_b32 v114, v112, v150
	v_cmp_lt_i32_e64 s[0:1], v115, v113
	s_waitcnt lgkmcnt(0)
	v_add_f32_e32 v114, v150, v114
	v_cndmask_b32_e64 v113, v241, v115, s[0:1]
	v_lshlrev_b32_e32 v113, 2, v113
	ds_bpermute_b32 v115, v113, v114
	s_and_saveexec_b64 s[0:1], vcc
	s_cbranch_execz .LBB0_519
	v_lshlrev_b64 v[124:125], 6, v[216:217]
	v_lshl_add_u64 v[124:125], s[12:13], 0, v[124:125]
	v_lshl_add_u64 v[124:125], s[26:27], 2, v[124:125]
	s_lshl_b32 s72, s17, 2
	v_lshl_add_u64 v[124:125], v[124:125], 0, s[72:73]
	s_waitcnt lgkmcnt(0)
	v_add_f32_e32 v114, v114, v115
	global_store_dword v[124:125], v114, off
; __device__ __forceinline__ u32x4 pack8(const f32x4 v0, const f32x4 v1) { u32x4 w; w.x = cvt_pk_bf16(v0[0], v0[1]); w.y = cvt_pk_bf16(v0[2], v0[3]); w.z = cvt_pk_bf16(v1[0], v1[1]); w.w = cvt_pk_bf16(v1[2], v1[3]); return w; }
; __device__ __forceinline__ float sumsq8(const f32x4 a, const f32x4 b) { return ((a[0] * a[0] + a[1] * a[1]) + (a[2] * a[2] + a[3] * a[3])) + ((b[0] * b[0] + b[1] * b[1]) + (b[2] * b[2] + b[3] * b[3])); }
; __device__ __forceinline__ void unpack8(const u32x4 w, f32x4& a, f32x4& b) { a = (f32x4){bf_lo(w.x), bf_hi(w.x), bf_lo(w.y), bf_hi(w.y)}; b = (f32x4){bf_lo(w.z), bf_hi(w.z), bf_lo(w.w), bf_hi(w.w)}; }
;     __device__ __forceinline__ void operator()(const f32x4 (&acc)[2][2][4][2], const Unit& u, int wr, int wc, int fr, int fq) const {
;     ...
;         for (int ai = 0; ai < 2; ++ai)
; #pragma unroll
;             for (int m = 0; m < 4; ++m) { const int row = row0 + ai * HALF + m * 16; float part = 0.f;
; #pragma unroll
;                 for (int bj = 0; bj < 2; ++bj) { f32x4 r0, r1; unpack8(rv[ai * 4 + m][bj], r0, r1);
;                     const f32x4 h0 = r0 + acc[ai][bj][m][0], h1 = r1 + acc[ai][bj][m][1]; part += sumsq8(h0, h1);
;                     *(u32x4*)(XBo + (size_t)row * DMODEL + col0 + bj * HALF) = pack8(h0, h1); }
;                 part += __shfl_xor(part, 16); part += __shfl_xor(part, 32);
;                 if (fq == 0) ssq[(size_t)row * 16 + u.pn * 4 + wc] = part; }
.LBB0_519:
	s_or_b64 exec, exec, s[0:1]
	s_waitcnt vmcnt(15)
	v_lshlrev_b32_e32 v114, 16, v180
	s_waitcnt lgkmcnt(0)
	v_and_b32_e32 v115, 0xffff0000, v180
	v_lshlrev_b32_e32 v124, 16, v181
	v_and_b32_e32 v125, 0xffff0000, v181
	v_lshlrev_b32_e32 v126, 16, v182
	v_and_b32_e32 v127, 0xffff0000, v182
	v_lshlrev_b32_e32 v148, 16, v183
	v_and_b32_e32 v149, 0xffff0000, v183
	v_pk_add_f32 v[110:111], v[110:111], v[124:125]
	v_pk_add_f32 v[108:109], v[108:109], v[114:115]
	v_pk_add_f32 v[114:115], v[106:107], v[148:149]
	v_pk_add_f32 v[106:107], v[104:105], v[126:127]
	v_mul_f32_e32 v104, v109, v109
	v_mul_f32_e32 v105, v111, v111
	v_fmac_f32_e32 v104, v108, v108
	v_fmac_f32_e32 v105, v110, v110
	v_add_f32_e32 v104, v104, v105
	v_mul_f32_e32 v105, v107, v107
	v_mul_f32_e32 v124, v115, v115
	v_fmac_f32_e32 v105, v106, v106
	v_fmac_f32_e32 v124, v114, v114
	v_add_f32_e32 v105, v105, v124
	v_add_f32_e32 v126, v104, v105
	v_cvt_pk_bf16_f32 v104, v108, v109
	v_cvt_pk_bf16_f32 v105, v110, v111
	v_lshlrev_b32_e32 v108, 16, v176
	v_and_b32_e32 v109, 0xffff0000, v176
	v_lshlrev_b32_e32 v110, 16, v177
	v_and_b32_e32 v111, 0xffff0000, v177
	v_cvt_pk_bf16_f32 v106, v106, v107
	v_cvt_pk_bf16_f32 v107, v114, v115
	v_lshlrev_b32_e32 v114, 16, v178
	v_and_b32_e32 v115, 0xffff0000, v178
	v_pk_add_f32 v[102:103], v[102:103], v[110:111]
	v_pk_add_f32 v[100:101], v[100:101], v[108:109]
	v_lshlrev_b32_e32 v124, 16, v179
	v_and_b32_e32 v125, 0xffff0000, v179
	v_pk_add_f32 v[110:111], v[96:97], v[114:115]
	v_mul_f32_e32 v96, v101, v101
	v_mul_f32_e32 v97, v103, v103
	v_pk_add_f32 v[108:109], v[98:99], v[124:125]
	v_fmac_f32_e32 v96, v100, v100
	v_fmac_f32_e32 v97, v102, v102
	v_add_f32_e32 v96, v96, v97
	v_mul_f32_e32 v97, v111, v111
	v_mul_f32_e32 v98, v109, v109
	v_fmac_f32_e32 v97, v110, v110
	v_fmac_f32_e32 v98, v108, v108
	v_add_f32_e32 v97, v97, v98
	v_add_f32_e32 v96, v96, v97
	v_add_f32_e32 v99, v126, v96
	ds_bpermute_b32 v124, v112, v99
	v_lshl_add_u64 v[96:97], s[10:11], 0, v[232:233]
	v_lshl_add_u64 v[114:115], v[214:215], 1, v[96:97]
	global_store_dwordx4 v[114:115], v[104:107], off nt
	v_cvt_pk_bf16_f32 v98, v100, v101
	s_waitcnt lgkmcnt(0)
	v_add_f32_e32 v96, v99, v124
	ds_bpermute_b32 v97, v113, v96
	v_cvt_pk_bf16_f32 v99, v102, v103
	v_cvt_pk_bf16_f32 v100, v110, v111
	v_cvt_pk_bf16_f32 v101, v108, v109
	global_store_dwordx4 v[114:115], v[98:101], off offset:256 nt
	s_and_saveexec_b64 s[0:1], vcc
	s_cbranch_execz .LBB0_521
	v_lshlrev_b64 v[98:99], 6, v[230:231]
	v_lshl_add_u64 v[98:99], s[12:13], 0, v[98:99]
	v_lshl_add_u64 v[98:99], s[26:27], 2, v[98:99]
	s_lshl_b32 s72, s17, 2
	v_lshl_add_u64 v[98:99], v[98:99], 0, s[72:73]
	s_waitcnt lgkmcnt(0)
	v_add_f32_e32 v96, v96, v97
	global_store_dword v[98:99], v96, off
.LBB0_521:
	s_or_b64 exec, exec, s[0:1]
	s_waitcnt vmcnt(16)
	v_lshlrev_b32_e32 v96, 16, v172
	s_waitcnt lgkmcnt(0)
	v_and_b32_e32 v97, 0xffff0000, v172
	v_lshlrev_b32_e32 v98, 16, v173
	v_and_b32_e32 v99, 0xffff0000, v173
	v_lshlrev_b32_e32 v100, 16, v174
	v_and_b32_e32 v101, 0xffff0000, v174
	v_lshlrev_b32_e32 v102, 16, v175
	v_and_b32_e32 v103, 0xffff0000, v175
	v_pk_add_f32 v[94:95], v[94:95], v[98:99]
	v_pk_add_f32 v[92:93], v[92:93], v[96:97]
	v_pk_add_f32 v[96:97], v[90:91], v[102:103]
	v_pk_add_f32 v[90:91], v[88:89], v[100:101]
	v_mul_f32_e32 v88, v93, v93
	v_mul_f32_e32 v89, v95, v95
	v_fmac_f32_e32 v88, v92, v92
	v_fmac_f32_e32 v89, v94, v94
	v_add_f32_e32 v88, v88, v89
	v_mul_f32_e32 v89, v91, v91
	v_mul_f32_e32 v98, v97, v97
	v_fmac_f32_e32 v89, v90, v90
	v_fmac_f32_e32 v98, v96, v96
	v_add_f32_e32 v89, v89, v98
	v_add_f32_e32 v100, v88, v89
	v_cvt_pk_bf16_f32 v88, v92, v93
	v_cvt_pk_bf16_f32 v89, v94, v95
	v_lshlrev_b32_e32 v92, 16, v168
	v_and_b32_e32 v93, 0xffff0000, v168
	v_lshlrev_b32_e32 v94, 16, v169
	v_and_b32_e32 v95, 0xffff0000, v169
	v_cvt_pk_bf16_f32 v90, v90, v91
	v_cvt_pk_bf16_f32 v91, v96, v97
	v_lshlrev_b32_e32 v96, 16, v170
	v_and_b32_e32 v97, 0xffff0000, v170
	v_pk_add_f32 v[86:87], v[86:87], v[94:95]
	v_pk_add_f32 v[84:85], v[84:85], v[92:93]
	v_lshlrev_b32_e32 v98, 16, v171
	v_and_b32_e32 v99, 0xffff0000, v171
	v_pk_add_f32 v[94:95], v[80:81], v[96:97]
	v_mul_f32_e32 v80, v85, v85
	v_mul_f32_e32 v81, v87, v87
	v_pk_add_f32 v[92:93], v[82:83], v[98:99]
	v_fmac_f32_e32 v80, v84, v84
	v_fmac_f32_e32 v81, v86, v86
	v_add_f32_e32 v80, v80, v81
	v_mul_f32_e32 v81, v95, v95
	v_mul_f32_e32 v82, v93, v93
	v_fmac_f32_e32 v81, v94, v94
	v_fmac_f32_e32 v82, v92, v92
	v_add_f32_e32 v81, v81, v82
	v_add_f32_e32 v80, v80, v81
	v_add_f32_e32 v83, v100, v80
	ds_bpermute_b32 v98, v112, v83
	v_lshl_add_u64 v[80:81], s[10:11], 0, v[228:229]
	v_lshl_add_u64 v[96:97], v[214:215], 1, v[80:81]
	global_store_dwordx4 v[96:97], v[88:91], off nt
	v_cvt_pk_bf16_f32 v82, v84, v85
	s_waitcnt lgkmcnt(0)
	v_add_f32_e32 v80, v83, v98
	ds_bpermute_b32 v81, v113, v80
	v_cvt_pk_bf16_f32 v83, v86, v87
	v_cvt_pk_bf16_f32 v84, v94, v95
	v_cvt_pk_bf16_f32 v85, v92, v93
	global_store_dwordx4 v[96:97], v[82:85], off offset:256 nt
	s_and_saveexec_b64 s[0:1], vcc
	s_cbranch_execz .LBB0_523
	v_lshlrev_b64 v[82:83], 6, v[226:227]
	v_lshl_add_u64 v[82:83], s[12:13], 0, v[82:83]
	v_lshl_add_u64 v[82:83], s[26:27], 2, v[82:83]
	s_lshl_b32 s72, s17, 2
	v_lshl_add_u64 v[82:83], v[82:83], 0, s[72:73]
	s_waitcnt lgkmcnt(0)
	v_add_f32_e32 v80, v80, v81
	global_store_dword v[82:83], v80, off
; __device__ __forceinline__ u32x4 pack8(const f32x4 v0, const f32x4 v1) { u32x4 w; w.x = cvt_pk_bf16(v0[0], v0[1]); w.y = cvt_pk_bf16(v0[2], v0[3]); w.z = cvt_pk_bf16(v1[0], v1[1]); w.w = cvt_pk_bf16(v1[2], v1[3]); return w; }
; __device__ __forceinline__ float sumsq8(const f32x4 a, const f32x4 b) { return ((a[0] * a[0] + a[1] * a[1]) + (a[2] * a[2] + a[3] * a[3])) + ((b[0] * b[0] + b[1] * b[1]) + (b[2] * b[2] + b[3] * b[3])); }
; __device__ __forceinline__ void unpack8(const u32x4 w, f32x4& a, f32x4& b) { a = (f32x4){bf_lo(w.x), bf_hi(w.x), bf_lo(w.y), bf_hi(w.y)}; b = (f32x4){bf_lo(w.z), bf_hi(w.z), bf_lo(w.w), bf_hi(w.w)}; }
;     __device__ __forceinline__ void operator()(const f32x4 (&acc)[2][2][4][2], const Unit& u, int wr, int wc, int fr, int fq) const {
;     ...
;         for (int ai = 0; ai < 2; ++ai)
; #pragma unroll
;             for (int m = 0; m < 4; ++m) { const int row = row0 + ai * HALF + m * 16; float part = 0.f;
; #pragma unroll
;                 for (int bj = 0; bj < 2; ++bj) { f32x4 r0, r1; unpack8(rv[ai * 4 + m][bj], r0, r1);
;                     const f32x4 h0 = r0 + acc[ai][bj][m][0], h1 = r1 + acc[ai][bj][m][1]; part += sumsq8(h0, h1);
;                     *(u32x4*)(XBo + (size_t)row * DMODEL + col0 + bj * HALF) = pack8(h0, h1); }
;                 part += __shfl_xor(part, 16); part += __shfl_xor(part, 32);
;                 if (fq == 0) ssq[(size_t)row * 16 + u.pn * 4 + wc] = part; }
.LBB0_523:
	s_or_b64 exec, exec, s[0:1]
	s_waitcnt vmcnt(17)
	v_lshlrev_b32_e32 v80, 16, v164
	s_waitcnt lgkmcnt(0)
	v_and_b32_e32 v81, 0xffff0000, v164
	v_lshlrev_b32_e32 v82, 16, v165
	v_and_b32_e32 v83, 0xffff0000, v165
	v_lshlrev_b32_e32 v84, 16, v166
	v_and_b32_e32 v85, 0xffff0000, v166
	v_lshlrev_b32_e32 v86, 16, v167
	v_and_b32_e32 v87, 0xffff0000, v167
	v_pk_add_f32 v[78:79], v[78:79], v[82:83]
	v_pk_add_f32 v[76:77], v[76:77], v[80:81]
	v_pk_add_f32 v[80:81], v[74:75], v[86:87]
	v_pk_add_f32 v[74:75], v[72:73], v[84:85]
	v_mul_f32_e32 v72, v77, v77
	v_mul_f32_e32 v73, v79, v79
	v_fmac_f32_e32 v72, v76, v76
	v_fmac_f32_e32 v73, v78, v78
	v_add_f32_e32 v72, v72, v73
	v_mul_f32_e32 v73, v75, v75
	v_mul_f32_e32 v82, v81, v81
	v_fmac_f32_e32 v73, v74, v74
	v_fmac_f32_e32 v82, v80, v80
	v_add_f32_e32 v73, v73, v82
	v_add_f32_e32 v84, v72, v73
	v_cvt_pk_bf16_f32 v72, v76, v77
	v_cvt_pk_bf16_f32 v73, v78, v79
	v_lshlrev_b32_e32 v76, 16, v160
	v_and_b32_e32 v77, 0xffff0000, v160
	v_lshlrev_b32_e32 v78, 16, v161
	v_and_b32_e32 v79, 0xffff0000, v161
	v_cvt_pk_bf16_f32 v74, v74, v75
	v_cvt_pk_bf16_f32 v75, v80, v81
	v_lshlrev_b32_e32 v80, 16, v162
	v_and_b32_e32 v81, 0xffff0000, v162
	v_pk_add_f32 v[70:71], v[70:71], v[78:79]
	v_pk_add_f32 v[68:69], v[68:69], v[76:77]
	v_lshlrev_b32_e32 v82, 16, v163
	v_and_b32_e32 v83, 0xffff0000, v163
	v_pk_add_f32 v[78:79], v[64:65], v[80:81]
	v_mul_f32_e32 v64, v69, v69
	v_mul_f32_e32 v65, v71, v71
	v_pk_add_f32 v[76:77], v[66:67], v[82:83]
	v_fmac_f32_e32 v64, v68, v68
	v_fmac_f32_e32 v65, v70, v70
	v_add_f32_e32 v64, v64, v65
	v_mul_f32_e32 v65, v79, v79
	v_mul_f32_e32 v66, v77, v77
	v_fmac_f32_e32 v65, v78, v78
	v_fmac_f32_e32 v66, v76, v76
	v_add_f32_e32 v65, v65, v66
	v_add_f32_e32 v64, v64, v65
	v_add_f32_e32 v67, v84, v64
	ds_bpermute_b32 v82, v112, v67
	v_lshl_add_u64 v[64:65], s[10:11], 0, v[224:225]
	v_lshl_add_u64 v[80:81], v[214:215], 1, v[64:65]
	global_store_dwordx4 v[80:81], v[72:75], off nt
	v_cvt_pk_bf16_f32 v66, v68, v69
	s_waitcnt lgkmcnt(0)
	v_add_f32_e32 v64, v67, v82
	ds_bpermute_b32 v65, v113, v64
	v_cvt_pk_bf16_f32 v67, v70, v71
	v_cvt_pk_bf16_f32 v68, v78, v79
	v_cvt_pk_bf16_f32 v69, v76, v77
	global_store_dwordx4 v[80:81], v[66:69], off offset:256 nt
	s_and_saveexec_b64 s[0:1], vcc
	s_cbranch_execz .LBB0_525
	v_lshlrev_b64 v[66:67], 6, v[222:223]
	v_lshl_add_u64 v[66:67], s[12:13], 0, v[66:67]
	v_lshl_add_u64 v[66:67], s[26:27], 2, v[66:67]
	s_lshl_b32 s72, s17, 2
	v_lshl_add_u64 v[66:67], v[66:67], 0, s[72:73]
	s_waitcnt lgkmcnt(0)
	v_add_f32_e32 v64, v64, v65
	global_store_dword v[66:67], v64, off
.LBB0_525:
	s_or_b64 exec, exec, s[0:1]
	s_waitcnt vmcnt(18)
	v_lshlrev_b32_e32 v64, 16, v156
	s_waitcnt lgkmcnt(0)
	v_and_b32_e32 v65, 0xffff0000, v156
	v_lshlrev_b32_e32 v66, 16, v157
	v_and_b32_e32 v67, 0xffff0000, v157
	v_lshlrev_b32_e32 v68, 16, v158
	v_and_b32_e32 v69, 0xffff0000, v158
	v_lshlrev_b32_e32 v70, 16, v159
	v_and_b32_e32 v71, 0xffff0000, v159
	v_pk_add_f32 v[62:63], v[62:63], v[66:67]
	v_pk_add_f32 v[60:61], v[60:61], v[64:65]
	v_pk_add_f32 v[64:65], v[58:59], v[70:71]
	v_pk_add_f32 v[58:59], v[56:57], v[68:69]
	v_mul_f32_e32 v56, v61, v61
	v_mul_f32_e32 v57, v63, v63
	v_fmac_f32_e32 v56, v60, v60
	v_fmac_f32_e32 v57, v62, v62
	v_add_f32_e32 v56, v56, v57
	v_mul_f32_e32 v57, v59, v59
	v_mul_f32_e32 v66, v65, v65
	v_fmac_f32_e32 v57, v58, v58
	v_fmac_f32_e32 v66, v64, v64
	v_add_f32_e32 v57, v57, v66
	v_add_f32_e32 v68, v56, v57
	v_cvt_pk_bf16_f32 v56, v60, v61
	v_cvt_pk_bf16_f32 v57, v62, v63
	v_lshlrev_b32_e32 v60, 16, v144
	v_and_b32_e32 v61, 0xffff0000, v144
	v_lshlrev_b32_e32 v62, 16, v145
	v_and_b32_e32 v63, 0xffff0000, v145
	v_cvt_pk_bf16_f32 v58, v58, v59
	v_cvt_pk_bf16_f32 v59, v64, v65
	v_lshlrev_b32_e32 v64, 16, v146
	v_and_b32_e32 v65, 0xffff0000, v146
	v_pk_add_f32 v[54:55], v[54:55], v[62:63]
	v_pk_add_f32 v[52:53], v[52:53], v[60:61]
	v_lshlrev_b32_e32 v66, 16, v147
	v_and_b32_e32 v67, 0xffff0000, v147
	v_pk_add_f32 v[62:63], v[48:49], v[64:65]
	v_mul_f32_e32 v48, v53, v53
	v_mul_f32_e32 v49, v55, v55
	v_pk_add_f32 v[60:61], v[50:51], v[66:67]
	v_fmac_f32_e32 v48, v52, v52
	v_fmac_f32_e32 v49, v54, v54
	v_add_f32_e32 v48, v48, v49
	v_mul_f32_e32 v49, v63, v63
	v_mul_f32_e32 v50, v61, v61
	v_fmac_f32_e32 v49, v62, v62
	v_fmac_f32_e32 v50, v60, v60
	v_add_f32_e32 v49, v49, v50
	v_add_f32_e32 v48, v48, v49
	v_add_f32_e32 v51, v68, v48
	ds_bpermute_b32 v66, v112, v51
	v_lshl_add_u64 v[48:49], s[10:11], 0, v[220:221]
	v_lshl_add_u64 v[64:65], v[214:215], 1, v[48:49]
	global_store_dwordx4 v[64:65], v[56:59], off nt
	v_cvt_pk_bf16_f32 v50, v52, v53
	s_waitcnt lgkmcnt(0)
	v_add_f32_e32 v48, v51, v66
	ds_bpermute_b32 v49, v113, v48
	v_cvt_pk_bf16_f32 v51, v54, v55
	v_cvt_pk_bf16_f32 v52, v62, v63
	v_cvt_pk_bf16_f32 v53, v60, v61
	global_store_dwordx4 v[64:65], v[50:53], off offset:256 nt
	s_and_saveexec_b64 s[0:1], vcc
	s_cbranch_execz .LBB0_527
	v_lshlrev_b64 v[50:51], 6, v[218:219]
	v_lshl_add_u64 v[50:51], s[12:13], 0, v[50:51]
	v_lshl_add_u64 v[50:51], s[26:27], 2, v[50:51]
	s_lshl_b32 s72, s17, 2
	v_lshl_add_u64 v[50:51], v[50:51], 0, s[72:73]
	s_waitcnt lgkmcnt(0)
	v_add_f32_e32 v48, v48, v49
	global_store_dword v[50:51], v48, off
; __device__ __forceinline__ u32x4 pack8(const f32x4 v0, const f32x4 v1) { u32x4 w; w.x = cvt_pk_bf16(v0[0], v0[1]); w.y = cvt_pk_bf16(v0[2], v0[3]); w.z = cvt_pk_bf16(v1[0], v1[1]); w.w = cvt_pk_bf16(v1[2], v1[3]); return w; }
; __device__ __forceinline__ float sumsq8(const f32x4 a, const f32x4 b) { return ((a[0] * a[0] + a[1] * a[1]) + (a[2] * a[2] + a[3] * a[3])) + ((b[0] * b[0] + b[1] * b[1]) + (b[2] * b[2] + b[3] * b[3])); }
; __device__ __forceinline__ void unpack8(const u32x4 w, f32x4& a, f32x4& b) { a = (f32x4){bf_lo(w.x), bf_hi(w.x), bf_lo(w.y), bf_hi(w.y)}; b = (f32x4){bf_lo(w.z), bf_hi(w.z), bf_lo(w.w), bf_hi(w.w)}; }
;     __device__ __forceinline__ void operator()(const f32x4 (&acc)[2][2][4][2], const Unit& u, int wr, int wc, int fr, int fq) const {
;     ...
;         for (int ai = 0; ai < 2; ++ai)
; #pragma unroll
;             for (int m = 0; m < 4; ++m) { const int row = row0 + ai * HALF + m * 16; float part = 0.f;
; #pragma unroll
;                 for (int bj = 0; bj < 2; ++bj) { f32x4 r0, r1; unpack8(rv[ai * 4 + m][bj], r0, r1);
;                     const f32x4 h0 = r0 + acc[ai][bj][m][0], h1 = r1 + acc[ai][bj][m][1]; part += sumsq8(h0, h1);
;                     *(u32x4*)(XBo + (size_t)row * DMODEL + col0 + bj * HALF) = pack8(h0, h1); }
;                 part += __shfl_xor(part, 16); part += __shfl_xor(part, 32);
;                 if (fq == 0) ssq[(size_t)row * 16 + u.pn * 4 + wc] = part; }
.LBB0_527:
	s_or_b64 exec, exec, s[0:1]
	s_waitcnt vmcnt(19)
	v_lshlrev_b32_e32 v52, 16, v140
	v_and_b32_e32 v53, 0xffff0000, v140
	v_lshlrev_b32_e32 v54, 16, v141
	v_and_b32_e32 v55, 0xffff0000, v141
	v_lshlrev_b32_e32 v56, 16, v142
	v_and_b32_e32 v57, 0xffff0000, v142
	v_lshlrev_b32_e32 v58, 16, v143
	v_and_b32_e32 v59, 0xffff0000, v143
	v_pk_add_f32 v[46:47], v[46:47], v[54:55]
	v_pk_add_f32 v[44:45], v[44:45], v[52:53]
	v_pk_add_f32 v[52:53], v[42:43], v[58:59]
	v_pk_add_f32 v[42:43], v[40:41], v[56:57]
	v_mul_f32_e32 v40, v45, v45
	v_mul_f32_e32 v41, v47, v47
	v_fmac_f32_e32 v40, v44, v44
	v_fmac_f32_e32 v41, v46, v46
	v_add_f32_e32 v40, v40, v41
	v_mul_f32_e32 v41, v43, v43
	v_mul_f32_e32 v54, v53, v53
	v_fmac_f32_e32 v41, v42, v42
	v_fmac_f32_e32 v54, v52, v52
	v_add_f32_e32 v41, v41, v54
	v_add_f32_e32 v56, v40, v41
	v_cvt_pk_bf16_f32 v40, v44, v45
	v_cvt_pk_bf16_f32 v41, v46, v47
	v_lshlrev_b32_e32 v44, 16, v136
	v_and_b32_e32 v45, 0xffff0000, v136
	v_lshlrev_b32_e32 v46, 16, v137
	v_and_b32_e32 v47, 0xffff0000, v137
	v_cvt_pk_bf16_f32 v42, v42, v43
	v_cvt_pk_bf16_f32 v43, v52, v53
	v_lshlrev_b32_e32 v52, 16, v138
	v_and_b32_e32 v53, 0xffff0000, v138
	v_pk_add_f32 v[38:39], v[38:39], v[46:47]
	v_pk_add_f32 v[36:37], v[36:37], v[44:45]
	v_lshlrev_b32_e32 v54, 16, v139
	v_and_b32_e32 v55, 0xffff0000, v139
	v_pk_add_f32 v[46:47], v[32:33], v[52:53]
	v_mul_f32_e32 v32, v37, v37
	v_mul_f32_e32 v33, v39, v39
	v_pk_add_f32 v[44:45], v[34:35], v[54:55]
	v_fmac_f32_e32 v32, v36, v36
	v_fmac_f32_e32 v33, v38, v38
	v_add_f32_e32 v32, v32, v33
	v_mul_f32_e32 v33, v47, v47
	v_mul_f32_e32 v34, v45, v45
	v_fmac_f32_e32 v33, v46, v46
	v_fmac_f32_e32 v34, v44, v44
	v_add_f32_e32 v33, v33, v34
	v_add_f32_e32 v32, v32, v33
	v_add_f32_e32 v35, v56, v32
	ds_bpermute_b32 v52, v112, v35
	v_add_u32_e32 v48, 0x90, v216
	s_waitcnt lgkmcnt(1)
	v_ashrrev_i32_e32 v49, 31, v48
	v_lshlrev_b64 v[50:51], 11, v[48:49]
	v_lshl_add_u64 v[32:33], s[10:11], 0, v[50:51]
	v_lshl_add_u64 v[50:51], v[214:215], 1, v[32:33]
	s_waitcnt lgkmcnt(0)
	v_add_f32_e32 v32, v35, v52
	ds_bpermute_b32 v33, v113, v32
	global_store_dwordx4 v[50:51], v[40:43], off nt
	v_cvt_pk_bf16_f32 v34, v36, v37
	v_cvt_pk_bf16_f32 v35, v38, v39
	v_cvt_pk_bf16_f32 v36, v46, v47
	v_cvt_pk_bf16_f32 v37, v44, v45
	global_store_dwordx4 v[50:51], v[34:37], off offset:256 nt
	s_and_saveexec_b64 s[0:1], vcc
	s_cbranch_execz .LBB0_529
	v_lshlrev_b64 v[34:35], 6, v[48:49]
	v_lshl_add_u64 v[34:35], s[12:13], 0, v[34:35]
	v_lshl_add_u64 v[34:35], s[26:27], 2, v[34:35]
	s_lshl_b32 s72, s17, 2
	v_lshl_add_u64 v[34:35], v[34:35], 0, s[72:73]
	s_waitcnt lgkmcnt(0)
	v_add_f32_e32 v32, v32, v33
	global_store_dword v[34:35], v32, off
; __device__ __forceinline__ u32x4 pack8(const f32x4 v0, const f32x4 v1) { u32x4 w; w.x = cvt_pk_bf16(v0[0], v0[1]); w.y = cvt_pk_bf16(v0[2], v0[3]); w.z = cvt_pk_bf16(v1[0], v1[1]); w.w = cvt_pk_bf16(v1[2], v1[3]); return w; }
; __device__ __forceinline__ float sumsq8(const f32x4 a, const f32x4 b) { return ((a[0] * a[0] + a[1] * a[1]) + (a[2] * a[2] + a[3] * a[3])) + ((b[0] * b[0] + b[1] * b[1]) + (b[2] * b[2] + b[3] * b[3])); }
; __device__ __forceinline__ void unpack8(const u32x4 w, f32x4& a, f32x4& b) { a = (f32x4){bf_lo(w.x), bf_hi(w.x), bf_lo(w.y), bf_hi(w.y)}; b = (f32x4){bf_lo(w.z), bf_hi(w.z), bf_lo(w.w), bf_hi(w.w)}; }
;     __device__ __forceinline__ void operator()(const f32x4 (&acc)[2][2][4][2], const Unit& u, int wr, int wc, int fr, int fq) const {
;     ...
;         for (int ai = 0; ai < 2; ++ai)
; #pragma unroll
;             for (int m = 0; m < 4; ++m) { const int row = row0 + ai * HALF + m * 16; float part = 0.f;
; #pragma unroll
;                 for (int bj = 0; bj < 2; ++bj) { f32x4 r0, r1; unpack8(rv[ai * 4 + m][bj], r0, r1);
;                     const f32x4 h0 = r0 + acc[ai][bj][m][0], h1 = r1 + acc[ai][bj][m][1]; part += sumsq8(h0, h1);
;                     *(u32x4*)(XBo + (size_t)row * DMODEL + col0 + bj * HALF) = pack8(h0, h1); }
;                 part += __shfl_xor(part, 16); part += __shfl_xor(part, 32);
;                 if (fq == 0) ssq[(size_t)row * 16 + u.pn * 4 + wc] = part; }
.LBB0_529:
	s_or_b64 exec, exec, s[0:1]
	s_waitcnt vmcnt(20)
	v_lshlrev_b32_e32 v36, 16, v128
	v_and_b32_e32 v37, 0xffff0000, v128
	v_lshlrev_b32_e32 v38, 16, v129
	v_and_b32_e32 v39, 0xffff0000, v129
	v_lshlrev_b32_e32 v40, 16, v130
	v_and_b32_e32 v41, 0xffff0000, v130
	v_lshlrev_b32_e32 v42, 16, v131
	v_and_b32_e32 v43, 0xffff0000, v131
	v_pk_add_f32 v[30:31], v[30:31], v[38:39]
	v_pk_add_f32 v[28:29], v[28:29], v[36:37]
	v_pk_add_f32 v[36:37], v[26:27], v[42:43]
	v_pk_add_f32 v[26:27], v[24:25], v[40:41]
	v_mul_f32_e32 v24, v29, v29
	v_mul_f32_e32 v25, v31, v31
	v_fmac_f32_e32 v24, v28, v28
	v_fmac_f32_e32 v25, v30, v30
	v_add_f32_e32 v24, v24, v25
	v_mul_f32_e32 v25, v27, v27
	v_mul_f32_e32 v38, v37, v37
	v_fmac_f32_e32 v25, v26, v26
	v_fmac_f32_e32 v38, v36, v36
	v_add_f32_e32 v25, v25, v38
	v_add_f32_e32 v40, v24, v25
	v_cvt_pk_bf16_f32 v24, v28, v29
	v_cvt_pk_bf16_f32 v25, v30, v31
	v_lshlrev_b32_e32 v28, 16, v116
	v_and_b32_e32 v29, 0xffff0000, v116
	v_lshlrev_b32_e32 v30, 16, v117
	v_and_b32_e32 v31, 0xffff0000, v117
	v_cvt_pk_bf16_f32 v26, v26, v27
	v_cvt_pk_bf16_f32 v27, v36, v37
	v_lshlrev_b32_e32 v36, 16, v118
	v_and_b32_e32 v37, 0xffff0000, v118
	v_pk_add_f32 v[22:23], v[22:23], v[30:31]
	v_pk_add_f32 v[20:21], v[20:21], v[28:29]
	v_lshlrev_b32_e32 v38, 16, v119
	v_and_b32_e32 v39, 0xffff0000, v119
	v_pk_add_f32 v[30:31], v[16:17], v[36:37]
	v_mul_f32_e32 v16, v21, v21
	v_mul_f32_e32 v17, v23, v23
	v_pk_add_f32 v[28:29], v[18:19], v[38:39]
	v_fmac_f32_e32 v16, v20, v20
	v_fmac_f32_e32 v17, v22, v22
	v_add_f32_e32 v16, v16, v17
	v_mul_f32_e32 v17, v31, v31
	v_mul_f32_e32 v18, v29, v29
	v_fmac_f32_e32 v17, v30, v30
	v_fmac_f32_e32 v18, v28, v28
	v_add_f32_e32 v17, v17, v18
	v_add_f32_e32 v16, v16, v17
	v_add_f32_e32 v19, v40, v16
	ds_bpermute_b32 v36, v112, v19
	v_add_u32_e32 v32, 0xa0, v216
	s_waitcnt lgkmcnt(1)
	v_ashrrev_i32_e32 v33, 31, v32
	v_lshlrev_b64 v[34:35], 11, v[32:33]
	v_lshl_add_u64 v[16:17], s[10:11], 0, v[34:35]
	v_lshl_add_u64 v[34:35], v[214:215], 1, v[16:17]
	s_waitcnt lgkmcnt(0)
	v_add_f32_e32 v16, v19, v36
	ds_bpermute_b32 v17, v113, v16
	global_store_dwordx4 v[34:35], v[24:27], off nt
	v_cvt_pk_bf16_f32 v18, v20, v21
	v_cvt_pk_bf16_f32 v19, v22, v23
	v_cvt_pk_bf16_f32 v20, v30, v31
	v_cvt_pk_bf16_f32 v21, v28, v29
	global_store_dwordx4 v[34:35], v[18:21], off offset:256 nt
	s_and_saveexec_b64 s[0:1], vcc
	s_cbranch_execz .LBB0_531
	v_lshlrev_b64 v[18:19], 6, v[32:33]
	v_lshl_add_u64 v[18:19], s[12:13], 0, v[18:19]
	v_lshl_add_u64 v[18:19], s[26:27], 2, v[18:19]
	s_lshl_b32 s72, s17, 2
	v_lshl_add_u64 v[18:19], v[18:19], 0, s[72:73]
	s_waitcnt lgkmcnt(0)
	v_add_f32_e32 v16, v16, v17
	global_store_dword v[18:19], v16, off
.LBB0_531:
	s_or_b64 exec, exec, s[0:1]
	s_waitcnt vmcnt(21)
	v_lshlrev_b32_e32 v20, 16, v132
	v_and_b32_e32 v21, 0xffff0000, v132
	v_lshlrev_b32_e32 v22, 16, v133
	v_and_b32_e32 v23, 0xffff0000, v133
	v_lshlrev_b32_e32 v24, 16, v134
	v_and_b32_e32 v25, 0xffff0000, v134
	v_lshlrev_b32_e32 v26, 16, v135
	v_and_b32_e32 v27, 0xffff0000, v135
	v_pk_add_f32 v[14:15], v[14:15], v[22:23]
	v_pk_add_f32 v[12:13], v[12:13], v[20:21]
	v_pk_add_f32 v[20:21], v[10:11], v[26:27]
	v_pk_add_f32 v[10:11], v[8:9], v[24:25]
	v_mul_f32_e32 v8, v13, v13
	v_mul_f32_e32 v9, v15, v15
	v_fmac_f32_e32 v8, v12, v12
	v_fmac_f32_e32 v9, v14, v14
	v_add_f32_e32 v8, v8, v9
	v_mul_f32_e32 v9, v11, v11
	v_mul_f32_e32 v22, v21, v21
	v_fmac_f32_e32 v9, v10, v10
	v_fmac_f32_e32 v22, v20, v20
	v_add_f32_e32 v9, v9, v22
	v_add_f32_e32 v24, v8, v9
	v_cvt_pk_bf16_f32 v8, v12, v13
	v_cvt_pk_bf16_f32 v9, v14, v15
	v_lshlrev_b32_e32 v12, 16, v120
	v_and_b32_e32 v13, 0xffff0000, v120
	v_lshlrev_b32_e32 v14, 16, v121
	v_and_b32_e32 v15, 0xffff0000, v121
	v_cvt_pk_bf16_f32 v10, v10, v11
	v_cvt_pk_bf16_f32 v11, v20, v21
	v_lshlrev_b32_e32 v20, 16, v122
	v_and_b32_e32 v21, 0xffff0000, v122
	v_pk_add_f32 v[6:7], v[6:7], v[14:15]
	v_pk_add_f32 v[4:5], v[4:5], v[12:13]
	v_lshlrev_b32_e32 v22, 16, v123
	v_and_b32_e32 v23, 0xffff0000, v123
	v_pk_add_f32 v[14:15], v[0:1], v[20:21]
	v_mul_f32_e32 v0, v5, v5
	v_mul_f32_e32 v1, v7, v7
	v_pk_add_f32 v[12:13], v[2:3], v[22:23]
	v_fmac_f32_e32 v0, v4, v4
	v_fmac_f32_e32 v1, v6, v6
	v_add_f32_e32 v0, v0, v1
	v_mul_f32_e32 v1, v15, v15
	v_mul_f32_e32 v2, v13, v13
	v_fmac_f32_e32 v1, v14, v14
	v_fmac_f32_e32 v2, v12, v12
	v_add_f32_e32 v1, v1, v2
	v_add_f32_e32 v0, v0, v1
	v_add_f32_e32 v3, v24, v0
	ds_bpermute_b32 v20, v112, v3
	v_add_u32_e32 v16, 0xb0, v216
	s_waitcnt lgkmcnt(1)
	v_ashrrev_i32_e32 v17, 31, v16
	v_lshlrev_b64 v[18:19], 11, v[16:17]
	v_lshl_add_u64 v[0:1], s[10:11], 0, v[18:19]
	v_lshl_add_u64 v[18:19], v[214:215], 1, v[0:1]
	s_waitcnt lgkmcnt(0)
	v_add_f32_e32 v0, v3, v20
	ds_bpermute_b32 v1, v113, v0
	global_store_dwordx4 v[18:19], v[8:11], off nt
	v_cvt_pk_bf16_f32 v2, v4, v5
	v_cvt_pk_bf16_f32 v3, v6, v7
	v_cvt_pk_bf16_f32 v4, v14, v15
	v_cvt_pk_bf16_f32 v5, v12, v13
	global_store_dwordx4 v[18:19], v[2:5], off offset:256 nt
	s_and_saveexec_b64 s[0:1], vcc
	s_cbranch_execz .LBB0_533
	v_lshlrev_b64 v[2:3], 6, v[16:17]
	v_lshl_add_u64 v[2:3], s[12:13], 0, v[2:3]
	v_lshl_add_u64 v[2:3], s[26:27], 2, v[2:3]
	s_lshl_b32 s72, s17, 2
	v_lshl_add_u64 v[2:3], v[2:3], 0, s[72:73]
	s_waitcnt lgkmcnt(0)
	v_add_f32_e32 v0, v0, v1
	global_store_dword v[2:3], v0, off

; __device__ __forceinline__ u32x4 pack8(const f32x4 v0, const f32x4 v1) { u32x4 w; w.x = cvt_pk_bf16(v0[0], v0[1]); w.y = cvt_pk_bf16(v0[2], v0[3]); w.z = cvt_pk_bf16(v1[0], v1[1]); w.w = cvt_pk_bf16(v1[2], v1[3]); return w; }
; __device__ __forceinline__ float sumsq8(const f32x4 a, const f32x4 b) { return ((a[0] * a[0] + a[1] * a[1]) + (a[2] * a[2] + a[3] * a[3])) + ((b[0] * b[0] + b[1] * b[1]) + (b[2] * b[2] + b[3] * b[3])); }
; __device__ __forceinline__ void unpack8(const u32x4 w, f32x4& a, f32x4& b) { a = (f32x4){bf_lo(w.x), bf_hi(w.x), bf_lo(w.y), bf_hi(w.y)}; b = (f32x4){bf_lo(w.z), bf_hi(w.z), bf_lo(w.w), bf_hi(w.w)}; }
;     __device__ __forceinline__ void operator()(const f32x4 (&acc)[2][2][4][2], const Unit& u, int wr, int wc, int fr, int fq) const {
;         const int row0 = u.pm * BM + wr * 64 + fr, col0 = u.pn * BM + wc * 32 + 8 * fq;
;         u32x4 rv[8][2];
; #pragma unroll
;         for (int i = 0; i < 8; ++i)
; #pragma unroll
;             for (int bj = 0; bj < 2; ++bj) rv[i][bj] = *(const u32x4*)(Rin + (size_t)(row0 + (i >> 2) * HALF + (i & 3) * 16) * DMODEL + col0 + bj * HALF);
; #pragma unroll
;         for (int ai = 0; ai < 2; ++ai)
; #pragma unroll
;             for (int m = 0; m < 4; ++m) { const int row = row0 + ai * HALF + m * 16; float part = 0.f;
; #pragma unroll
;                 for (int bj = 0; bj < 2; ++bj) { f32x4 r0, r1; unpack8(rv[ai * 4 + m][bj], r0, r1);
;                     const f32x4 h0 = r0 + acc[ai][bj][m][0], h1 = r1 + acc[ai][bj][m][1]; part += sumsq8(h0, h1);
;                     *(u32x4*)(XBo + (size_t)row * DMODEL + col0 + bj * HALF) = pack8(h0, h1); }
;                 part += __shfl_xor(part, 16); part += __shfl_xor(part, 32);
;                 if (fq == 0) ssq[(size_t)row * 16 + u.pn * 4 + wc] = part; }
.LBB0_968:
	v_mov_b32_e32 v116, v192
	s_lshl_b32 s1, s24, 8
	v_readfirstlane_b32 s0, v116
	s_bfe_u32 s13, s0, 0x20006
	s_ashr_i32 s0, s0, 2
	s_andn2_b32 s0, s0, 63
	s_add_i32 s0, s0, s1
	v_and_or_b32 v216, v116, 15, s0
	s_lshl_b32 s0, s22, 8
	s_lshl_b32 s1, s13, 5
	v_bfe_u32 v249, v116, 4, 2
	s_or_b32 s0, s1, s0
	v_lshl_or_b32 v214, v249, 3, s0
	v_ashrrev_i32_e32 v215, 31, v214
	v_lshlrev_b64 v[234:235], 1, v[214:215]
	v_ashrrev_i32_e32 v217, 31, v216
	v_lshl_add_u64 v[120:121], s[6:7], 0, v[234:235]
	v_lshlrev_b64 v[236:237], 11, v[216:217]
	v_lshl_add_u64 v[116:117], v[120:121], 0, v[236:237]
	global_load_dwordx4 v[188:191], v[116:117], off
	global_load_dwordx4 v[184:187], v[116:117], off offset:256
	v_or_b32_e32 v230, 16, v216
	v_ashrrev_i32_e32 v231, 31, v230
	v_or_b32_e32 v226, 32, v216
	v_lshlrev_b64 v[232:233], 11, v[230:231]
	v_ashrrev_i32_e32 v227, 31, v226
	v_or_b32_e32 v222, 48, v216
	v_lshl_add_u64 v[116:117], v[120:121], 0, v[232:233]
	v_lshlrev_b64 v[228:229], 11, v[226:227]
	v_ashrrev_i32_e32 v223, 31, v222
	v_add_u32_e32 v218, 0x80, v216
	global_load_dwordx4 v[180:183], v[116:117], off
	global_load_dwordx4 v[176:179], v[116:117], off offset:256
	v_lshl_add_u64 v[116:117], v[120:121], 0, v[228:229]
	v_lshlrev_b64 v[224:225], 11, v[222:223]
	v_ashrrev_i32_e32 v219, 31, v218
	global_load_dwordx4 v[172:175], v[116:117], off
	global_load_dwordx4 v[168:171], v[116:117], off offset:256
	v_lshl_add_u64 v[116:117], v[120:121], 0, v[224:225]
	v_lshlrev_b64 v[220:221], 11, v[218:219]
	global_load_dwordx4 v[164:167], v[116:117], off
	global_load_dwordx4 v[160:163], v[116:117], off offset:256
	v_lshl_add_u64 v[116:117], v[120:121], 0, v[220:221]
	global_load_dwordx4 v[156:159], v[116:117], off
	global_load_dwordx4 v[144:147], v[116:117], off offset:256
	v_add_u32_e32 v116, 0x90, v216
	v_ashrrev_i32_e32 v117, 31, v116
	v_lshlrev_b64 v[116:117], 11, v[116:117]
	v_lshl_add_u64 v[116:117], v[120:121], 0, v[116:117]
	global_load_dwordx4 v[140:143], v[116:117], off
	global_load_dwordx4 v[136:139], v[116:117], off offset:256
	v_add_u32_e32 v116, 0xa0, v216
	v_add_u32_e32 v122, 0xb0, v216
	v_ashrrev_i32_e32 v117, 31, v116
	v_ashrrev_i32_e32 v123, 31, v122
	v_lshlrev_b64 v[116:117], 11, v[116:117]
	v_lshlrev_b64 v[122:123], 11, v[122:123]
	v_lshl_add_u64 v[116:117], v[120:121], 0, v[116:117]
	v_lshl_add_u64 v[120:121], v[120:121], 0, v[122:123]
	global_load_dwordx4 v[128:131], v[116:117], off
	s_nop 0
	global_load_dwordx4 v[116:119], v[116:117], off offset:256
	s_nop 0
	global_load_dwordx4 v[132:135], v[120:121], off
	s_nop 0
	global_load_dwordx4 v[120:123], v[120:121], off offset:256
	s_lshl_b32 s22, s22, 2
	v_cmp_eq_u32_e32 vcc, 0, v249
	s_ashr_i32 s23, s22, 31
	s_waitcnt vmcnt(14)
	v_lshlrev_b32_e32 v250, 16, v188
	v_and_b32_e32 v251, 0xffff0000, v188
	v_lshlrev_b32_e32 v188, 16, v189
	v_and_b32_e32 v189, 0xffff0000, v189
	v_lshlrev_b32_e32 v252, 16, v190
	v_and_b32_e32 v253, 0xffff0000, v190
	v_lshlrev_b32_e32 v190, 16, v191
	v_and_b32_e32 v191, 0xffff0000, v191
	v_pk_add_f32 v[154:155], v[154:155], v[188:189]
	v_pk_add_f32 v[152:153], v[152:153], v[250:251]
	v_pk_add_f32 v[188:189], v[150:151], v[190:191]
	v_pk_add_f32 v[150:151], v[148:149], v[252:253]
	v_mul_f32_e32 v148, v153, v153
	v_mul_f32_e32 v149, v155, v155
	v_fmac_f32_e32 v148, v152, v152
	v_fmac_f32_e32 v149, v154, v154
	v_add_f32_e32 v148, v148, v149
	v_mul_f32_e32 v149, v151, v151
	v_mul_f32_e32 v190, v189, v189
	v_fmac_f32_e32 v149, v150, v150
	v_fmac_f32_e32 v190, v188, v188
	v_add_f32_e32 v149, v149, v190
	v_add_f32_e32 v190, v148, v149
	v_cvt_pk_bf16_f32 v148, v152, v153
	v_lshl_add_u64 v[152:153], s[6:7], 0, v[236:237]
	v_cvt_pk_bf16_f32 v149, v154, v155
	v_cvt_pk_bf16_f32 v150, v150, v151
	v_cvt_pk_bf16_f32 v151, v188, v189
	v_lshl_add_u64 v[152:153], v[152:153], 0, v[234:235]
	global_store_dwordx4 v[152:153], v[148:151], off nt
	v_lshlrev_b32_e32 v154, 16, v186
	v_and_b32_e32 v155, 0xffff0000, v186
	v_lshlrev_b32_e32 v148, 16, v184
	v_and_b32_e32 v149, 0xffff0000, v184
	v_lshlrev_b32_e32 v150, 16, v185
	v_and_b32_e32 v151, 0xffff0000, v185
	v_lshlrev_b32_e32 v184, 16, v187
	v_and_b32_e32 v185, 0xffff0000, v187
	v_pk_add_f32 v[126:127], v[126:127], v[150:151]
	v_pk_add_f32 v[124:125], v[124:125], v[148:149]
	v_pk_add_f32 v[148:149], v[114:115], v[184:185]
	v_pk_add_f32 v[114:115], v[112:113], v[154:155]
	v_mul_f32_e32 v112, v125, v125
	v_mul_f32_e32 v113, v127, v127
	v_fmac_f32_e32 v112, v124, v124
	v_fmac_f32_e32 v113, v126, v126
	v_add_f32_e32 v112, v112, v113
	v_mul_f32_e32 v113, v115, v115
	v_mul_f32_e32 v150, v149, v149
	v_fmac_f32_e32 v113, v114, v114
	v_fmac_f32_e32 v150, v148, v148
	v_add_f32_e32 v113, v113, v150
	v_add_f32_e32 v112, v112, v113
	v_add_f32_e32 v150, v190, v112
	v_cvt_pk_bf16_f32 v112, v124, v125
	v_cvt_pk_bf16_f32 v113, v126, v127
	v_cvt_pk_bf16_f32 v114, v114, v115
	v_cvt_pk_bf16_f32 v115, v148, v149
	global_store_dwordx4 v[152:153], v[112:115], off offset:256 nt
	s_nop 1
	v_and_b32_e32 v113, 64, v241
	v_xor_b32_e32 v112, 16, v241
	v_add_u32_e32 v113, 64, v113
	v_cmp_lt_i32_e64 s[0:1], v112, v113
	v_xor_b32_e32 v115, 32, v241
	s_nop 0
	v_cndmask_b32_e64 v112, v241, v112, s[0:1]
	v_lshlrev_b32_e32 v112, 2, v112
	ds_bpermute_b32 v114, v112, v150
	v_cmp_lt_i32_e64 s[0:1], v115, v113
	s_waitcnt lgkmcnt(0)
	v_add_f32_e32 v114, v150, v114
	v_cndmask_b32_e64 v113, v241, v115, s[0:1]
	v_lshlrev_b32_e32 v113, 2, v113
	ds_bpermute_b32 v115, v113, v114
	s_and_saveexec_b64 s[0:1], vcc
	s_cbranch_execz .LBB0_970
	v_lshlrev_b64 v[124:125], 6, v[216:217]
	v_lshl_add_u64 v[124:125], s[8:9], 0, v[124:125]
	v_lshl_add_u64 v[124:125], s[22:23], 2, v[124:125]
	s_lshl_b32 s72, s13, 2
	v_lshl_add_u64 v[124:125], v[124:125], 0, s[72:73]
	s_waitcnt lgkmcnt(0)
	v_add_f32_e32 v114, v114, v115
	global_store_dword v[124:125], v114, off
; __device__ __forceinline__ u32x4 pack8(const f32x4 v0, const f32x4 v1) { u32x4 w; w.x = cvt_pk_bf16(v0[0], v0[1]); w.y = cvt_pk_bf16(v0[2], v0[3]); w.z = cvt_pk_bf16(v1[0], v1[1]); w.w = cvt_pk_bf16(v1[2], v1[3]); return w; }
; __device__ __forceinline__ float sumsq8(const f32x4 a, const f32x4 b) { return ((a[0] * a[0] + a[1] * a[1]) + (a[2] * a[2] + a[3] * a[3])) + ((b[0] * b[0] + b[1] * b[1]) + (b[2] * b[2] + b[3] * b[3])); }
; __device__ __forceinline__ void unpack8(const u32x4 w, f32x4& a, f32x4& b) { a = (f32x4){bf_lo(w.x), bf_hi(w.x), bf_lo(w.y), bf_hi(w.y)}; b = (f32x4){bf_lo(w.z), bf_hi(w.z), bf_lo(w.w), bf_hi(w.w)}; }
;     __device__ __forceinline__ void operator()(const f32x4 (&acc)[2][2][4][2], const Unit& u, int wr, int wc, int fr, int fq) const {
;     ...
;         for (int ai = 0; ai < 2; ++ai)
; #pragma unroll
;             for (int m = 0; m < 4; ++m) { const int row = row0 + ai * HALF + m * 16; float part = 0.f;
; #pragma unroll
;                 for (int bj = 0; bj < 2; ++bj) { f32x4 r0, r1; unpack8(rv[ai * 4 + m][bj], r0, r1);
;                     const f32x4 h0 = r0 + acc[ai][bj][m][0], h1 = r1 + acc[ai][bj][m][1]; part += sumsq8(h0, h1);
;                     *(u32x4*)(XBo + (size_t)row * DMODEL + col0 + bj * HALF) = pack8(h0, h1); }
;                 part += __shfl_xor(part, 16); part += __shfl_xor(part, 32);
;                 if (fq == 0) ssq[(size_t)row * 16 + u.pn * 4 + wc] = part; }
.LBB0_970:
	s_or_b64 exec, exec, s[0:1]
	s_waitcnt vmcnt(15)
	v_lshlrev_b32_e32 v114, 16, v180
	s_waitcnt lgkmcnt(0)
	v_and_b32_e32 v115, 0xffff0000, v180
	v_lshlrev_b32_e32 v124, 16, v181
	v_and_b32_e32 v125, 0xffff0000, v181
	v_lshlrev_b32_e32 v126, 16, v182
	v_and_b32_e32 v127, 0xffff0000, v182
	v_lshlrev_b32_e32 v148, 16, v183
	v_and_b32_e32 v149, 0xffff0000, v183
	v_pk_add_f32 v[110:111], v[110:111], v[124:125]
	v_pk_add_f32 v[108:109], v[108:109], v[114:115]
	v_pk_add_f32 v[114:115], v[106:107], v[148:149]
	v_pk_add_f32 v[106:107], v[104:105], v[126:127]
	v_mul_f32_e32 v104, v109, v109
	v_mul_f32_e32 v105, v111, v111
	v_fmac_f32_e32 v104, v108, v108
	v_fmac_f32_e32 v105, v110, v110
	v_add_f32_e32 v104, v104, v105
	v_mul_f32_e32 v105, v107, v107
	v_mul_f32_e32 v124, v115, v115
	v_fmac_f32_e32 v105, v106, v106
	v_fmac_f32_e32 v124, v114, v114
	v_add_f32_e32 v105, v105, v124
	v_add_f32_e32 v126, v104, v105
	v_cvt_pk_bf16_f32 v104, v108, v109
	v_cvt_pk_bf16_f32 v105, v110, v111
	v_lshlrev_b32_e32 v108, 16, v176
	v_and_b32_e32 v109, 0xffff0000, v176
	v_lshlrev_b32_e32 v110, 16, v177
	v_and_b32_e32 v111, 0xffff0000, v177
	v_cvt_pk_bf16_f32 v106, v106, v107
	v_cvt_pk_bf16_f32 v107, v114, v115
	v_lshlrev_b32_e32 v114, 16, v178
	v_and_b32_e32 v115, 0xffff0000, v178
	v_pk_add_f32 v[102:103], v[102:103], v[110:111]
	v_pk_add_f32 v[100:101], v[100:101], v[108:109]
	v_lshlrev_b32_e32 v124, 16, v179
	v_and_b32_e32 v125, 0xffff0000, v179
	v_pk_add_f32 v[110:111], v[96:97], v[114:115]
	v_mul_f32_e32 v96, v101, v101
	v_mul_f32_e32 v97, v103, v103
	v_pk_add_f32 v[108:109], v[98:99], v[124:125]
	v_fmac_f32_e32 v96, v100, v100
	v_fmac_f32_e32 v97, v102, v102
	v_add_f32_e32 v96, v96, v97
	v_mul_f32_e32 v97, v111, v111
	v_mul_f32_e32 v98, v109, v109
	v_fmac_f32_e32 v97, v110, v110
	v_fmac_f32_e32 v98, v108, v108
	v_add_f32_e32 v97, v97, v98
	v_add_f32_e32 v96, v96, v97
	v_add_f32_e32 v99, v126, v96
	ds_bpermute_b32 v124, v112, v99
	v_lshl_add_u64 v[96:97], s[6:7], 0, v[232:233]
	v_lshl_add_u64 v[114:115], v[214:215], 1, v[96:97]
	global_store_dwordx4 v[114:115], v[104:107], off nt
	v_cvt_pk_bf16_f32 v98, v100, v101
	s_waitcnt lgkmcnt(0)
	v_add_f32_e32 v96, v99, v124
	ds_bpermute_b32 v97, v113, v96
	v_cvt_pk_bf16_f32 v99, v102, v103
	v_cvt_pk_bf16_f32 v100, v110, v111
	v_cvt_pk_bf16_f32 v101, v108, v109
	global_store_dwordx4 v[114:115], v[98:101], off offset:256 nt
	s_and_saveexec_b64 s[0:1], vcc
	s_cbranch_execz .LBB0_972
	v_lshlrev_b64 v[98:99], 6, v[230:231]
	v_lshl_add_u64 v[98:99], s[8:9], 0, v[98:99]
	v_lshl_add_u64 v[98:99], s[22:23], 2, v[98:99]
	s_lshl_b32 s72, s13, 2
	v_lshl_add_u64 v[98:99], v[98:99], 0, s[72:73]
	s_waitcnt lgkmcnt(0)
	v_add_f32_e32 v96, v96, v97
	global_store_dword v[98:99], v96, off
.LBB0_972:
	s_or_b64 exec, exec, s[0:1]
	s_waitcnt vmcnt(16)
	v_lshlrev_b32_e32 v96, 16, v172
	s_waitcnt lgkmcnt(0)
	v_and_b32_e32 v97, 0xffff0000, v172
	v_lshlrev_b32_e32 v98, 16, v173
	v_and_b32_e32 v99, 0xffff0000, v173
	v_lshlrev_b32_e32 v100, 16, v174
	v_and_b32_e32 v101, 0xffff0000, v174
	v_lshlrev_b32_e32 v102, 16, v175
	v_and_b32_e32 v103, 0xffff0000, v175
	v_pk_add_f32 v[94:95], v[94:95], v[98:99]
	v_pk_add_f32 v[92:93], v[92:93], v[96:97]
	v_pk_add_f32 v[96:97], v[90:91], v[102:103]
	v_pk_add_f32 v[90:91], v[88:89], v[100:101]
	v_mul_f32_e32 v88, v93, v93
	v_mul_f32_e32 v89, v95, v95
	v_fmac_f32_e32 v88, v92, v92
	v_fmac_f32_e32 v89, v94, v94
	v_add_f32_e32 v88, v88, v89
	v_mul_f32_e32 v89, v91, v91
	v_mul_f32_e32 v98, v97, v97
	v_fmac_f32_e32 v89, v90, v90
	v_fmac_f32_e32 v98, v96, v96
	v_add_f32_e32 v89, v89, v98
	v_add_f32_e32 v100, v88, v89
	v_cvt_pk_bf16_f32 v88, v92, v93
	v_cvt_pk_bf16_f32 v89, v94, v95
	v_lshlrev_b32_e32 v92, 16, v168
	v_and_b32_e32 v93, 0xffff0000, v168
	v_lshlrev_b32_e32 v94, 16, v169
	v_and_b32_e32 v95, 0xffff0000, v169
	v_cvt_pk_bf16_f32 v90, v90, v91
	v_cvt_pk_bf16_f32 v91, v96, v97
	v_lshlrev_b32_e32 v96, 16, v170
	v_and_b32_e32 v97, 0xffff0000, v170
	v_pk_add_f32 v[86:87], v[86:87], v[94:95]
	v_pk_add_f32 v[84:85], v[84:85], v[92:93]
	v_lshlrev_b32_e32 v98, 16, v171
	v_and_b32_e32 v99, 0xffff0000, v171
	v_pk_add_f32 v[94:95], v[80:81], v[96:97]
	v_mul_f32_e32 v80, v85, v85
	v_mul_f32_e32 v81, v87, v87
	v_pk_add_f32 v[92:93], v[82:83], v[98:99]
	v_fmac_f32_e32 v80, v84, v84
	v_fmac_f32_e32 v81, v86, v86
	v_add_f32_e32 v80, v80, v81
	v_mul_f32_e32 v81, v95, v95
	v_mul_f32_e32 v82, v93, v93
	v_fmac_f32_e32 v81, v94, v94
	v_fmac_f32_e32 v82, v92, v92
	v_add_f32_e32 v81, v81, v82
	v_add_f32_e32 v80, v80, v81
	v_add_f32_e32 v83, v100, v80
	ds_bpermute_b32 v98, v112, v83
	v_lshl_add_u64 v[80:81], s[6:7], 0, v[228:229]
	v_lshl_add_u64 v[96:97], v[214:215], 1, v[80:81]
	global_store_dwordx4 v[96:97], v[88:91], off nt
	v_cvt_pk_bf16_f32 v82, v84, v85
	s_waitcnt lgkmcnt(0)
	v_add_f32_e32 v80, v83, v98
	ds_bpermute_b32 v81, v113, v80
	v_cvt_pk_bf16_f32 v83, v86, v87
	v_cvt_pk_bf16_f32 v84, v94, v95
	v_cvt_pk_bf16_f32 v85, v92, v93
	global_store_dwordx4 v[96:97], v[82:85], off offset:256 nt
	s_and_saveexec_b64 s[0:1], vcc
	s_cbranch_execz .LBB0_974
	v_lshlrev_b64 v[82:83], 6, v[226:227]
	v_lshl_add_u64 v[82:83], s[8:9], 0, v[82:83]
	v_lshl_add_u64 v[82:83], s[22:23], 2, v[82:83]
	s_lshl_b32 s72, s13, 2
	v_lshl_add_u64 v[82:83], v[82:83], 0, s[72:73]
	s_waitcnt lgkmcnt(0)
	v_add_f32_e32 v80, v80, v81
	global_store_dword v[82:83], v80, off
; __device__ __forceinline__ u32x4 pack8(const f32x4 v0, const f32x4 v1) { u32x4 w; w.x = cvt_pk_bf16(v0[0], v0[1]); w.y = cvt_pk_bf16(v0[2], v0[3]); w.z = cvt_pk_bf16(v1[0], v1[1]); w.w = cvt_pk_bf16(v1[2], v1[3]); return w; }
; __device__ __forceinline__ float sumsq8(const f32x4 a, const f32x4 b) { return ((a[0] * a[0] + a[1] * a[1]) + (a[2] * a[2] + a[3] * a[3])) + ((b[0] * b[0] + b[1] * b[1]) + (b[2] * b[2] + b[3] * b[3])); }
; __device__ __forceinline__ void unpack8(const u32x4 w, f32x4& a, f32x4& b) { a = (f32x4){bf_lo(w.x), bf_hi(w.x), bf_lo(w.y), bf_hi(w.y)}; b = (f32x4){bf_lo(w.z), bf_hi(w.z), bf_lo(w.w), bf_hi(w.w)}; }
;     __device__ __forceinline__ void operator()(const f32x4 (&acc)[2][2][4][2], const Unit& u, int wr, int wc, int fr, int fq) const {
;     ...
;         for (int ai = 0; ai < 2; ++ai)
; #pragma unroll
;             for (int m = 0; m < 4; ++m) { const int row = row0 + ai * HALF + m * 16; float part = 0.f;
; #pragma unroll
;                 for (int bj = 0; bj < 2; ++bj) { f32x4 r0, r1; unpack8(rv[ai * 4 + m][bj], r0, r1);
;                     const f32x4 h0 = r0 + acc[ai][bj][m][0], h1 = r1 + acc[ai][bj][m][1]; part += sumsq8(h0, h1);
;                     *(u32x4*)(XBo + (size_t)row * DMODEL + col0 + bj * HALF) = pack8(h0, h1); }
;                 part += __shfl_xor(part, 16); part += __shfl_xor(part, 32);
;                 if (fq == 0) ssq[(size_t)row * 16 + u.pn * 4 + wc] = part; }
.LBB0_974:
	s_or_b64 exec, exec, s[0:1]
	s_waitcnt vmcnt(17)
	v_lshlrev_b32_e32 v80, 16, v164
	s_waitcnt lgkmcnt(0)
	v_and_b32_e32 v81, 0xffff0000, v164
	v_lshlrev_b32_e32 v82, 16, v165
	v_and_b32_e32 v83, 0xffff0000, v165
	v_lshlrev_b32_e32 v84, 16, v166
	v_and_b32_e32 v85, 0xffff0000, v166
	v_lshlrev_b32_e32 v86, 16, v167
	v_and_b32_e32 v87, 0xffff0000, v167
	v_pk_add_f32 v[78:79], v[78:79], v[82:83]
	v_pk_add_f32 v[76:77], v[76:77], v[80:81]
	v_pk_add_f32 v[80:81], v[74:75], v[86:87]
	v_pk_add_f32 v[74:75], v[72:73], v[84:85]
	v_mul_f32_e32 v72, v77, v77
	v_mul_f32_e32 v73, v79, v79
	v_fmac_f32_e32 v72, v76, v76
	v_fmac_f32_e32 v73, v78, v78
	v_add_f32_e32 v72, v72, v73
	v_mul_f32_e32 v73, v75, v75
	v_mul_f32_e32 v82, v81, v81
	v_fmac_f32_e32 v73, v74, v74
	v_fmac_f32_e32 v82, v80, v80
	v_add_f32_e32 v73, v73, v82
	v_add_f32_e32 v84, v72, v73
	v_cvt_pk_bf16_f32 v72, v76, v77
	v_cvt_pk_bf16_f32 v73, v78, v79
	v_lshlrev_b32_e32 v76, 16, v160
	v_and_b32_e32 v77, 0xffff0000, v160
	v_lshlrev_b32_e32 v78, 16, v161
	v_and_b32_e32 v79, 0xffff0000, v161
	v_cvt_pk_bf16_f32 v74, v74, v75
	v_cvt_pk_bf16_f32 v75, v80, v81
	v_lshlrev_b32_e32 v80, 16, v162
	v_and_b32_e32 v81, 0xffff0000, v162
	v_pk_add_f32 v[70:71], v[70:71], v[78:79]
	v_pk_add_f32 v[68:69], v[68:69], v[76:77]
	v_lshlrev_b32_e32 v82, 16, v163
	v_and_b32_e32 v83, 0xffff0000, v163
	v_pk_add_f32 v[78:79], v[64:65], v[80:81]
	v_mul_f32_e32 v64, v69, v69
	v_mul_f32_e32 v65, v71, v71
	v_pk_add_f32 v[76:77], v[66:67], v[82:83]
	v_fmac_f32_e32 v64, v68, v68
	v_fmac_f32_e32 v65, v70, v70
	v_add_f32_e32 v64, v64, v65
	v_mul_f32_e32 v65, v79, v79
	v_mul_f32_e32 v66, v77, v77
	v_fmac_f32_e32 v65, v78, v78
	v_fmac_f32_e32 v66, v76, v76
	v_add_f32_e32 v65, v65, v66
	v_add_f32_e32 v64, v64, v65
	v_add_f32_e32 v67, v84, v64
	ds_bpermute_b32 v82, v112, v67
	v_lshl_add_u64 v[64:65], s[6:7], 0, v[224:225]
	v_lshl_add_u64 v[80:81], v[214:215], 1, v[64:65]
	global_store_dwordx4 v[80:81], v[72:75], off nt
	v_cvt_pk_bf16_f32 v66, v68, v69
	s_waitcnt lgkmcnt(0)
	v_add_f32_e32 v64, v67, v82
	ds_bpermute_b32 v65, v113, v64
	v_cvt_pk_bf16_f32 v67, v70, v71
	v_cvt_pk_bf16_f32 v68, v78, v79
	v_cvt_pk_bf16_f32 v69, v76, v77
	global_store_dwordx4 v[80:81], v[66:69], off offset:256 nt
	s_and_saveexec_b64 s[0:1], vcc
	s_cbranch_execz .LBB0_976
	v_lshlrev_b64 v[66:67], 6, v[222:223]
	v_lshl_add_u64 v[66:67], s[8:9], 0, v[66:67]
	v_lshl_add_u64 v[66:67], s[22:23], 2, v[66:67]
	s_lshl_b32 s72, s13, 2
	v_lshl_add_u64 v[66:67], v[66:67], 0, s[72:73]
	s_waitcnt lgkmcnt(0)
	v_add_f32_e32 v64, v64, v65
	global_store_dword v[66:67], v64, off
.LBB0_976:
	s_or_b64 exec, exec, s[0:1]
	s_waitcnt vmcnt(18)
	v_lshlrev_b32_e32 v64, 16, v156
	s_waitcnt lgkmcnt(0)
	v_and_b32_e32 v65, 0xffff0000, v156
	v_lshlrev_b32_e32 v66, 16, v157
	v_and_b32_e32 v67, 0xffff0000, v157
	v_lshlrev_b32_e32 v68, 16, v158
	v_and_b32_e32 v69, 0xffff0000, v158
	v_lshlrev_b32_e32 v70, 16, v159
	v_and_b32_e32 v71, 0xffff0000, v159
	v_pk_add_f32 v[62:63], v[62:63], v[66:67]
	v_pk_add_f32 v[60:61], v[60:61], v[64:65]
	v_pk_add_f32 v[64:65], v[58:59], v[70:71]
	v_pk_add_f32 v[58:59], v[56:57], v[68:69]
	v_mul_f32_e32 v56, v61, v61
	v_mul_f32_e32 v57, v63, v63
	v_fmac_f32_e32 v56, v60, v60
	v_fmac_f32_e32 v57, v62, v62
	v_add_f32_e32 v56, v56, v57
	v_mul_f32_e32 v57, v59, v59
	v_mul_f32_e32 v66, v65, v65
	v_fmac_f32_e32 v57, v58, v58
	v_fmac_f32_e32 v66, v64, v64
	v_add_f32_e32 v57, v57, v66
	v_add_f32_e32 v68, v56, v57
	v_cvt_pk_bf16_f32 v56, v60, v61
	v_cvt_pk_bf16_f32 v57, v62, v63
	v_lshlrev_b32_e32 v60, 16, v144
	v_and_b32_e32 v61, 0xffff0000, v144
	v_lshlrev_b32_e32 v62, 16, v145
	v_and_b32_e32 v63, 0xffff0000, v145
	v_cvt_pk_bf16_f32 v58, v58, v59
	v_cvt_pk_bf16_f32 v59, v64, v65
	v_lshlrev_b32_e32 v64, 16, v146
	v_and_b32_e32 v65, 0xffff0000, v146
	v_pk_add_f32 v[54:55], v[54:55], v[62:63]
	v_pk_add_f32 v[52:53], v[52:53], v[60:61]
	v_lshlrev_b32_e32 v66, 16, v147
	v_and_b32_e32 v67, 0xffff0000, v147
	v_pk_add_f32 v[62:63], v[48:49], v[64:65]
	v_mul_f32_e32 v48, v53, v53
	v_mul_f32_e32 v49, v55, v55
	v_pk_add_f32 v[60:61], v[50:51], v[66:67]
	v_fmac_f32_e32 v48, v52, v52
	v_fmac_f32_e32 v49, v54, v54
	v_add_f32_e32 v48, v48, v49
	v_mul_f32_e32 v49, v63, v63
	v_mul_f32_e32 v50, v61, v61
	v_fmac_f32_e32 v49, v62, v62
	v_fmac_f32_e32 v50, v60, v60
	v_add_f32_e32 v49, v49, v50
	v_add_f32_e32 v48, v48, v49
	v_add_f32_e32 v51, v68, v48
	ds_bpermute_b32 v66, v112, v51
	v_lshl_add_u64 v[48:49], s[6:7], 0, v[220:221]
	v_lshl_add_u64 v[64:65], v[214:215], 1, v[48:49]
	global_store_dwordx4 v[64:65], v[56:59], off nt
	v_cvt_pk_bf16_f32 v50, v52, v53
	s_waitcnt lgkmcnt(0)
	v_add_f32_e32 v48, v51, v66
	ds_bpermute_b32 v49, v113, v48
	v_cvt_pk_bf16_f32 v51, v54, v55
	v_cvt_pk_bf16_f32 v52, v62, v63
	v_cvt_pk_bf16_f32 v53, v60, v61
	global_store_dwordx4 v[64:65], v[50:53], off offset:256 nt
	s_and_saveexec_b64 s[0:1], vcc
	s_cbranch_execz .LBB0_978
	v_lshlrev_b64 v[50:51], 6, v[218:219]
	v_lshl_add_u64 v[50:51], s[8:9], 0, v[50:51]
	v_lshl_add_u64 v[50:51], s[22:23], 2, v[50:51]
	s_lshl_b32 s72, s13, 2
	v_lshl_add_u64 v[50:51], v[50:51], 0, s[72:73]
	s_waitcnt lgkmcnt(0)
	v_add_f32_e32 v48, v48, v49
	global_store_dword v[50:51], v48, off
; __device__ __forceinline__ u32x4 pack8(const f32x4 v0, const f32x4 v1) { u32x4 w; w.x = cvt_pk_bf16(v0[0], v0[1]); w.y = cvt_pk_bf16(v0[2], v0[3]); w.z = cvt_pk_bf16(v1[0], v1[1]); w.w = cvt_pk_bf16(v1[2], v1[3]); return w; }
; __device__ __forceinline__ float sumsq8(const f32x4 a, const f32x4 b) { return ((a[0] * a[0] + a[1] * a[1]) + (a[2] * a[2] + a[3] * a[3])) + ((b[0] * b[0] + b[1] * b[1]) + (b[2] * b[2] + b[3] * b[3])); }
; __device__ __forceinline__ void unpack8(const u32x4 w, f32x4& a, f32x4& b) { a = (f32x4){bf_lo(w.x), bf_hi(w.x), bf_lo(w.y), bf_hi(w.y)}; b = (f32x4){bf_lo(w.z), bf_hi(w.z), bf_lo(w.w), bf_hi(w.w)}; }
;     __device__ __forceinline__ void operator()(const f32x4 (&acc)[2][2][4][2], const Unit& u, int wr, int wc, int fr, int fq) const {
;     ...
;         for (int ai = 0; ai < 2; ++ai)
; #pragma unroll
;             for (int m = 0; m < 4; ++m) { const int row = row0 + ai * HALF + m * 16; float part = 0.f;
; #pragma unroll
;                 for (int bj = 0; bj < 2; ++bj) { f32x4 r0, r1; unpack8(rv[ai * 4 + m][bj], r0, r1);
;                     const f32x4 h0 = r0 + acc[ai][bj][m][0], h1 = r1 + acc[ai][bj][m][1]; part += sumsq8(h0, h1);
;                     *(u32x4*)(XBo + (size_t)row * DMODEL + col0 + bj * HALF) = pack8(h0, h1); }
;                 part += __shfl_xor(part, 16); part += __shfl_xor(part, 32);
;                 if (fq == 0) ssq[(size_t)row * 16 + u.pn * 4 + wc] = part; }
.LBB0_978:
	s_or_b64 exec, exec, s[0:1]
	s_waitcnt vmcnt(19)
	v_lshlrev_b32_e32 v52, 16, v140
	v_and_b32_e32 v53, 0xffff0000, v140
	v_lshlrev_b32_e32 v54, 16, v141
	v_and_b32_e32 v55, 0xffff0000, v141
	v_lshlrev_b32_e32 v56, 16, v142
	v_and_b32_e32 v57, 0xffff0000, v142
	v_lshlrev_b32_e32 v58, 16, v143
	v_and_b32_e32 v59, 0xffff0000, v143
	v_pk_add_f32 v[46:47], v[46:47], v[54:55]
	v_pk_add_f32 v[44:45], v[44:45], v[52:53]
	v_pk_add_f32 v[52:53], v[42:43], v[58:59]
	v_pk_add_f32 v[42:43], v[40:41], v[56:57]
	v_mul_f32_e32 v40, v45, v45
	v_mul_f32_e32 v41, v47, v47
	v_fmac_f32_e32 v40, v44, v44
	v_fmac_f32_e32 v41, v46, v46
	v_add_f32_e32 v40, v40, v41
	v_mul_f32_e32 v41, v43, v43
	v_mul_f32_e32 v54, v53, v53
	v_fmac_f32_e32 v41, v42, v42
	v_fmac_f32_e32 v54, v52, v52
	v_add_f32_e32 v41, v41, v54
	v_add_f32_e32 v56, v40, v41
	v_cvt_pk_bf16_f32 v40, v44, v45
	v_cvt_pk_bf16_f32 v41, v46, v47
	v_lshlrev_b32_e32 v44, 16, v136
	v_and_b32_e32 v45, 0xffff0000, v136
	v_lshlrev_b32_e32 v46, 16, v137
	v_and_b32_e32 v47, 0xffff0000, v137
	v_cvt_pk_bf16_f32 v42, v42, v43
	v_cvt_pk_bf16_f32 v43, v52, v53
	v_lshlrev_b32_e32 v52, 16, v138
	v_and_b32_e32 v53, 0xffff0000, v138
	v_pk_add_f32 v[38:39], v[38:39], v[46:47]
	v_pk_add_f32 v[36:37], v[36:37], v[44:45]
	v_lshlrev_b32_e32 v54, 16, v139
	v_and_b32_e32 v55, 0xffff0000, v139
	v_pk_add_f32 v[46:47], v[32:33], v[52:53]
	v_mul_f32_e32 v32, v37, v37
	v_mul_f32_e32 v33, v39, v39
	v_pk_add_f32 v[44:45], v[34:35], v[54:55]
	v_fmac_f32_e32 v32, v36, v36
	v_fmac_f32_e32 v33, v38, v38
	v_add_f32_e32 v32, v32, v33
	v_mul_f32_e32 v33, v47, v47
	v_mul_f32_e32 v34, v45, v45
	v_fmac_f32_e32 v33, v46, v46
	v_fmac_f32_e32 v34, v44, v44
	v_add_f32_e32 v33, v33, v34
	v_add_f32_e32 v32, v32, v33
	v_add_f32_e32 v35, v56, v32
	ds_bpermute_b32 v52, v112, v35
	v_add_u32_e32 v48, 0x90, v216
	s_waitcnt lgkmcnt(1)
	v_ashrrev_i32_e32 v49, 31, v48
	v_lshlrev_b64 v[50:51], 11, v[48:49]
	v_lshl_add_u64 v[32:33], s[6:7], 0, v[50:51]
	v_lshl_add_u64 v[50:51], v[214:215], 1, v[32:33]
	s_waitcnt lgkmcnt(0)
	v_add_f32_e32 v32, v35, v52
	ds_bpermute_b32 v33, v113, v32
	global_store_dwordx4 v[50:51], v[40:43], off nt
	v_cvt_pk_bf16_f32 v34, v36, v37
	v_cvt_pk_bf16_f32 v35, v38, v39
	v_cvt_pk_bf16_f32 v36, v46, v47
	v_cvt_pk_bf16_f32 v37, v44, v45
	global_store_dwordx4 v[50:51], v[34:37], off offset:256 nt
	s_and_saveexec_b64 s[0:1], vcc
	s_cbranch_execz .LBB0_980
	v_lshlrev_b64 v[34:35], 6, v[48:49]
	v_lshl_add_u64 v[34:35], s[8:9], 0, v[34:35]
	v_lshl_add_u64 v[34:35], s[22:23], 2, v[34:35]
	s_lshl_b32 s72, s13, 2
	v_lshl_add_u64 v[34:35], v[34:35], 0, s[72:73]
	s_waitcnt lgkmcnt(0)
	v_add_f32_e32 v32, v32, v33
	global_store_dword v[34:35], v32, off
; __device__ __forceinline__ u32x4 pack8(const f32x4 v0, const f32x4 v1) { u32x4 w; w.x = cvt_pk_bf16(v0[0], v0[1]); w.y = cvt_pk_bf16(v0[2], v0[3]); w.z = cvt_pk_bf16(v1[0], v1[1]); w.w = cvt_pk_bf16(v1[2], v1[3]); return w; }
; __device__ __forceinline__ float sumsq8(const f32x4 a, const f32x4 b) { return ((a[0] * a[0] + a[1] * a[1]) + (a[2] * a[2] + a[3] * a[3])) + ((b[0] * b[0] + b[1] * b[1]) + (b[2] * b[2] + b[3] * b[3])); }
; __device__ __forceinline__ void unpack8(const u32x4 w, f32x4& a, f32x4& b) { a = (f32x4){bf_lo(w.x), bf_hi(w.x), bf_lo(w.y), bf_hi(w.y)}; b = (f32x4){bf_lo(w.z), bf_hi(w.z), bf_lo(w.w), bf_hi(w.w)}; }
;     __device__ __forceinline__ void operator()(const f32x4 (&acc)[2][2][4][2], const Unit& u, int wr, int wc, int fr, int fq) const {
;     ...
;         for (int ai = 0; ai < 2; ++ai)
; #pragma unroll
;             for (int m = 0; m < 4; ++m) { const int row = row0 + ai * HALF + m * 16; float part = 0.f;
; #pragma unroll
;                 for (int bj = 0; bj < 2; ++bj) { f32x4 r0, r1; unpack8(rv[ai * 4 + m][bj], r0, r1);
;                     const f32x4 h0 = r0 + acc[ai][bj][m][0], h1 = r1 + acc[ai][bj][m][1]; part += sumsq8(h0, h1);
;                     *(u32x4*)(XBo + (size_t)row * DMODEL + col0 + bj * HALF) = pack8(h0, h1); }
;                 part += __shfl_xor(part, 16); part += __shfl_xor(part, 32);
;                 if (fq == 0) ssq[(size_t)row * 16 + u.pn * 4 + wc] = part; }
.LBB0_980:
	s_or_b64 exec, exec, s[0:1]
	s_waitcnt vmcnt(20)
	v_lshlrev_b32_e32 v36, 16, v128
	v_and_b32_e32 v37, 0xffff0000, v128
	v_lshlrev_b32_e32 v38, 16, v129
	v_and_b32_e32 v39, 0xffff0000, v129
	v_lshlrev_b32_e32 v40, 16, v130
	v_and_b32_e32 v41, 0xffff0000, v130
	v_lshlrev_b32_e32 v42, 16, v131
	v_and_b32_e32 v43, 0xffff0000, v131
	v_pk_add_f32 v[30:31], v[30:31], v[38:39]
	v_pk_add_f32 v[28:29], v[28:29], v[36:37]
	v_pk_add_f32 v[36:37], v[26:27], v[42:43]
	v_pk_add_f32 v[26:27], v[24:25], v[40:41]
	v_mul_f32_e32 v24, v29, v29
	v_mul_f32_e32 v25, v31, v31
	v_fmac_f32_e32 v24, v28, v28
	v_fmac_f32_e32 v25, v30, v30
	v_add_f32_e32 v24, v24, v25
	v_mul_f32_e32 v25, v27, v27
	v_mul_f32_e32 v38, v37, v37
	v_fmac_f32_e32 v25, v26, v26
	v_fmac_f32_e32 v38, v36, v36
	v_add_f32_e32 v25, v25, v38
	v_add_f32_e32 v40, v24, v25
	v_cvt_pk_bf16_f32 v24, v28, v29
	v_cvt_pk_bf16_f32 v25, v30, v31
	v_lshlrev_b32_e32 v28, 16, v116
	v_and_b32_e32 v29, 0xffff0000, v116
	v_lshlrev_b32_e32 v30, 16, v117
	v_and_b32_e32 v31, 0xffff0000, v117
	v_cvt_pk_bf16_f32 v26, v26, v27
	v_cvt_pk_bf16_f32 v27, v36, v37
	v_lshlrev_b32_e32 v36, 16, v118
	v_and_b32_e32 v37, 0xffff0000, v118
	v_pk_add_f32 v[22:23], v[22:23], v[30:31]
	v_pk_add_f32 v[20:21], v[20:21], v[28:29]
	v_lshlrev_b32_e32 v38, 16, v119
	v_and_b32_e32 v39, 0xffff0000, v119
	v_pk_add_f32 v[30:31], v[16:17], v[36:37]
	v_mul_f32_e32 v16, v21, v21
	v_mul_f32_e32 v17, v23, v23
	v_pk_add_f32 v[28:29], v[18:19], v[38:39]
	v_fmac_f32_e32 v16, v20, v20
	v_fmac_f32_e32 v17, v22, v22
	v_add_f32_e32 v16, v16, v17
	v_mul_f32_e32 v17, v31, v31
	v_mul_f32_e32 v18, v29, v29
	v_fmac_f32_e32 v17, v30, v30
	v_fmac_f32_e32 v18, v28, v28
	v_add_f32_e32 v17, v17, v18
	v_add_f32_e32 v16, v16, v17
	v_add_f32_e32 v19, v40, v16
	ds_bpermute_b32 v36, v112, v19
	v_add_u32_e32 v32, 0xa0, v216
	s_waitcnt lgkmcnt(1)
	v_ashrrev_i32_e32 v33, 31, v32
	v_lshlrev_b64 v[34:35], 11, v[32:33]
	v_lshl_add_u64 v[16:17], s[6:7], 0, v[34:35]
	v_lshl_add_u64 v[34:35], v[214:215], 1, v[16:17]
	s_waitcnt lgkmcnt(0)
	v_add_f32_e32 v16, v19, v36
	ds_bpermute_b32 v17, v113, v16
	global_store_dwordx4 v[34:35], v[24:27], off nt
	v_cvt_pk_bf16_f32 v18, v20, v21
	v_cvt_pk_bf16_f32 v19, v22, v23
	v_cvt_pk_bf16_f32 v20, v30, v31
	v_cvt_pk_bf16_f32 v21, v28, v29
	global_store_dwordx4 v[34:35], v[18:21], off offset:256 nt
	s_and_saveexec_b64 s[0:1], vcc
	s_cbranch_execz .LBB0_982
	v_lshlrev_b64 v[18:19], 6, v[32:33]
	v_lshl_add_u64 v[18:19], s[8:9], 0, v[18:19]
	v_lshl_add_u64 v[18:19], s[22:23], 2, v[18:19]
	s_lshl_b32 s72, s13, 2
	v_lshl_add_u64 v[18:19], v[18:19], 0, s[72:73]
	s_waitcnt lgkmcnt(0)
	v_add_f32_e32 v16, v16, v17
	global_store_dword v[18:19], v16, off
.LBB0_982:
	s_or_b64 exec, exec, s[0:1]
	s_waitcnt vmcnt(21)
	v_lshlrev_b32_e32 v20, 16, v132
	v_and_b32_e32 v21, 0xffff0000, v132
	v_lshlrev_b32_e32 v22, 16, v133
	v_and_b32_e32 v23, 0xffff0000, v133
	v_lshlrev_b32_e32 v24, 16, v134
	v_and_b32_e32 v25, 0xffff0000, v134
	v_lshlrev_b32_e32 v26, 16, v135
	v_and_b32_e32 v27, 0xffff0000, v135
	v_pk_add_f32 v[14:15], v[14:15], v[22:23]
	v_pk_add_f32 v[12:13], v[12:13], v[20:21]
	v_pk_add_f32 v[20:21], v[10:11], v[26:27]
	v_pk_add_f32 v[10:11], v[8:9], v[24:25]
	v_mul_f32_e32 v8, v13, v13
	v_mul_f32_e32 v9, v15, v15
	v_fmac_f32_e32 v8, v12, v12
	v_fmac_f32_e32 v9, v14, v14
	v_add_f32_e32 v8, v8, v9
	v_mul_f32_e32 v9, v11, v11
	v_mul_f32_e32 v22, v21, v21
	v_fmac_f32_e32 v9, v10, v10
	v_fmac_f32_e32 v22, v20, v20
	v_add_f32_e32 v9, v9, v22
	v_add_f32_e32 v24, v8, v9
	v_cvt_pk_bf16_f32 v8, v12, v13
	v_cvt_pk_bf16_f32 v9, v14, v15
	v_lshlrev_b32_e32 v12, 16, v120
	v_and_b32_e32 v13, 0xffff0000, v120
	v_lshlrev_b32_e32 v14, 16, v121
	v_and_b32_e32 v15, 0xffff0000, v121
	v_cvt_pk_bf16_f32 v10, v10, v11
	v_cvt_pk_bf16_f32 v11, v20, v21
	v_lshlrev_b32_e32 v20, 16, v122
	v_and_b32_e32 v21, 0xffff0000, v122
	v_pk_add_f32 v[6:7], v[6:7], v[14:15]
	v_pk_add_f32 v[4:5], v[4:5], v[12:13]
	v_lshlrev_b32_e32 v22, 16, v123
	v_and_b32_e32 v23, 0xffff0000, v123
	v_pk_add_f32 v[14:15], v[0:1], v[20:21]
	v_mul_f32_e32 v0, v5, v5
	v_mul_f32_e32 v1, v7, v7
	v_pk_add_f32 v[12:13], v[2:3], v[22:23]
	v_fmac_f32_e32 v0, v4, v4
	v_fmac_f32_e32 v1, v6, v6
	v_add_f32_e32 v0, v0, v1
	v_mul_f32_e32 v1, v15, v15
	v_mul_f32_e32 v2, v13, v13
	v_fmac_f32_e32 v1, v14, v14
	v_fmac_f32_e32 v2, v12, v12
	v_add_f32_e32 v1, v1, v2
	v_add_f32_e32 v0, v0, v1
	v_add_f32_e32 v3, v24, v0
	ds_bpermute_b32 v20, v112, v3
	v_add_u32_e32 v16, 0xb0, v216
	s_waitcnt lgkmcnt(1)
	v_ashrrev_i32_e32 v17, 31, v16
	v_lshlrev_b64 v[18:19], 11, v[16:17]
	v_lshl_add_u64 v[0:1], s[6:7], 0, v[18:19]
	v_lshl_add_u64 v[18:19], v[214:215], 1, v[0:1]
	s_waitcnt lgkmcnt(0)
	v_add_f32_e32 v0, v3, v20
	ds_bpermute_b32 v1, v113, v0
	global_store_dwordx4 v[18:19], v[8:11], off nt
	v_cvt_pk_bf16_f32 v2, v4, v5
	v_cvt_pk_bf16_f32 v3, v6, v7
	v_cvt_pk_bf16_f32 v4, v14, v15
	v_cvt_pk_bf16_f32 v5, v12, v13
	global_store_dwordx4 v[18:19], v[2:5], off offset:256 nt
	s_and_saveexec_b64 s[0:1], vcc
	s_cbranch_execz .LBB0_984
	v_lshlrev_b64 v[2:3], 6, v[16:17]
	v_lshl_add_u64 v[2:3], s[8:9], 0, v[2:3]
	v_lshl_add_u64 v[2:3], s[22:23], 2, v[2:3]
	s_lshl_b32 s72, s13, 2
	v_lshl_add_u64 v[2:3], v[2:3], 0, s[72:73]
	s_waitcnt lgkmcnt(0)
	v_add_f32_e32 v0, v0, v1
	global_store_dword v[2:3], v0, off

; __device__ __forceinline__ u32x4 pack8(const f32x4 v0, const f32x4 v1) { u32x4 w; w.x = cvt_pk_bf16(v0[0], v0[1]); w.y = cvt_pk_bf16(v0[2], v0[3]); w.z = cvt_pk_bf16(v1[0], v1[1]); w.w = cvt_pk_bf16(v1[2], v1[3]); return w; }
;     __device__ __forceinline__ void operator()(const f32x4 (&acc)[2][2][4][2], const Unit& u, int wr, int wc, int fr, int fq) const {
;         const int row0 = u.pm * BM + wr * 64 + fr, col0 = u.pn * BM + wc * 32 + 8 * fq;
; #pragma unroll
;         for (int ai = 0; ai < 2; ++ai)
; #pragma unroll
;           for (int mh = 0; mh < 2; ++mh) {
;             u32x4 rv[2][2], pw[2][2]; f32x4 p[2];
; #pragma unroll
;             for (int mm = 0; mm < 2; ++mm) { const int rowl = row0 + ai * HALF + (2 * mh + mm) * 16; p[mm] = *(const f32x4*)(ssq_in + (size_t)rowl * 16 + 4 * fq);
; #pragma unroll
;                 for (int bj = 0; bj < 2; ++bj) { const size_t off = (size_t)rowl * DMODEL + col0 + bj * HALF; rv[mm][bj] = *(const u32x4*)(Rin + off); pw[mm][bj] = *(const u32x4*)(PP + off); } }
; #pragma unroll
;             for (int mm = 0; mm < 2; ++mm) { const int m = 2 * mh + mm; const int row = row0 + ai * HALF + m * 16; float part = 0.f;
;                 float sr = (p[mm][0] + p[mm][1]) + (p[mm][2] + p[mm][3]); sr += __shfl_xor(sr, 16); sr += __shfl_xor(sr, 32); const float r = __builtin_amdgcn_rsqf(sr * (1.0f / DMODEL) + RMS_EPS);
; #pragma unroll
;                 for (int bj = 0; bj < 2; ++bj) { f32x4 r0, r1, p0, p1; unpack8(rv[mm][bj], r0, r1); unpack8(pw[mm][bj], p0, p1);
;                     f32x4 g0 = acc[ai][bj][m][0] * r, g1 = acc[ai][bj][m][1] * r;
; #pragma unroll
;                     for (int e = 0; e < 4; ++e) { g0[e] = __builtin_amdgcn_rcpf(1.f + __builtin_amdgcn_exp2f(-1.4426950408889634f * g0[e])); g1[e] = __builtin_amdgcn_rcpf(1.f + __builtin_amdgcn_exp2f(-1.4426950408889634f * g1[e])); }
;                     const f32x4 h0 = r0 + g0 * p0, h1 = r1 + g1 * p1; part += sumsq8(h0, h1);
;                     *(u32x4*)(XBo + (size_t)row * DMODEL + col0 + bj * HALF) = pack8(h0, h1); }
;                 part += __shfl_xor(part, 16); part += __shfl_xor(part, 32);
;                 if (fq == 0) ssq_out[(size_t)row * 16 + u.pn * 4 + wc] = part; }
.LBB0_1136:
	v_readfirstlane_b32 s19, v192
	v_and_b32_e32 v247, 15, v192
	s_bfe_u32 s17, s19, 0x20006
	s_lshr_b32 s19, s19, 8
	s_lshl_b32 s19, s19, 6
	s_lshl_b32 s27, s40, 8
	s_add_i32 s19, s19, s27
	v_add_u32_e32 v247, s19, v247
	v_bfe_u32 v252, v192, 4, 2
	s_lshl_b32 s27, s26, 8
	s_lshl_b32 s28, s17, 5
	s_or_b32 s27, s27, s28
	v_lshl_or_b32 v253, v252, 3, s27
	v_lshlrev_b32_e32 v172, 11, v247
	v_lshl_add_u32 v172, v253, 1, v172
	v_lshlrev_b32_e32 v194, 6, v247
	v_lshl_add_u32 v173, v252, 4, v194
	s_lshl_b32 s28, s26, 4
	s_lshl_b32 s29, s17, 2
	s_add_i32 s28, s28, s29
	v_add_u32_e32 v194, s28, v194
	v_cmp_eq_u32_e32 vcc, 0, v252
	v_xor_b32_e32 v236, 16, v241
	v_xor_b32_e32 v237, 32, v241
	v_lshlrev_b32_e32 v236, 2, v236
	v_lshlrev_b32_e32 v237, 2, v237
	v_mov_b32_e32 v250, v172
	v_mov_b32_e32 v251, v173
	global_load_dwordx4 v[128:131], v251, s[10:11]
	global_load_dwordx4 v[132:135], v250, s[6:7]
	global_load_dwordx4 v[140:143], v250, s[2:3]
	global_load_dwordx4 v[136:139], v250, s[6:7] offset:256
	global_load_dwordx4 v[144:147], v250, s[2:3] offset:256
	v_add_u32_e32 v250, 0x8000, v172
	v_add_u32_e32 v251, 0x400, v173
	global_load_dwordx4 v[160:163], v251, s[10:11]
	global_load_dwordx4 v[164:167], v250, s[6:7]
	global_load_dwordx4 v[176:179], v250, s[2:3]
	global_load_dwordx4 v[168:171], v250, s[6:7] offset:256
	global_load_dwordx4 v[180:183], v250, s[2:3] offset:256
	v_add_u32_e32 v250, 0x10000, v172
	v_add_u32_e32 v251, 0x800, v173
	global_load_dwordx4 v[184:187], v251, s[10:11]
	global_load_dwordx4 v[188:191], v250, s[6:7]
	global_load_dwordx4 v[208:211], v250, s[2:3]
	global_load_dwordx4 v[204:207], v250, s[6:7] offset:256
	global_load_dwordx4 v[212:215], v250, s[2:3] offset:256
	s_waitcnt vmcnt(10)
	v_add_f32_e32 v247, v128, v129
	v_add_f32_e32 v252, v130, v131
	v_add_f32_e32 v247, v247, v252
	ds_bpermute_b32 v252, v236, v247
	s_waitcnt lgkmcnt(0)
	v_add_f32_e32 v247, v247, v252
	ds_bpermute_b32 v252, v237, v247
	s_waitcnt lgkmcnt(0)
	v_add_f32_e32 v247, v247, v252
	v_fmamk_f32 v247, v247, 0x3a800000, v193
	v_rsq_f32_e32 v247, v247
	s_nop 0
	v_mul_f32_e32 v253, 0xbfb8aa3b, v247
	v_mul_f32_e32 v124, v124, v253
	v_mul_f32_e32 v125, v125, v253
	v_mul_f32_e32 v126, v126, v253
	v_mul_f32_e32 v127, v127, v253
	v_exp_f32_e32 v124, v124
	v_exp_f32_e32 v125, v125
	v_exp_f32_e32 v126, v126
	v_exp_f32_e32 v127, v127
	v_add_f32_e32 v124, 1.0, v124
	v_add_f32_e32 v125, 1.0, v125
	v_add_f32_e32 v126, 1.0, v126
	v_add_f32_e32 v127, 1.0, v127
	v_rcp_f32_e32 v124, v124
	v_rcp_f32_e32 v125, v125
	v_rcp_f32_e32 v126, v126
	v_rcp_f32_e32 v127, v127
	v_lshlrev_b32_e32 v224, 16, v132
	v_and_b32_e32 v225, 0xffff0000, v132
	v_lshlrev_b32_e32 v226, 16, v133
	v_and_b32_e32 v227, 0xffff0000, v133
	v_lshlrev_b32_e32 v228, 16, v140
	v_and_b32_e32 v229, 0xffff0000, v140
	v_lshlrev_b32_e32 v230, 16, v141
	v_and_b32_e32 v231, 0xffff0000, v141
	v_fma_f32 v124, v124, v228, v224
	v_fma_f32 v125, v125, v229, v225
	v_fma_f32 v126, v126, v230, v226
	v_fma_f32 v127, v127, v231, v227
	v_mul_f32_e32 v232, v125, v125
	v_mul_f32_e32 v233, v127, v127
	v_fmac_f32_e32 v232, v124, v124
	v_fmac_f32_e32 v233, v126, v126
	v_add_f32_e32 v234, v232, v233
	v_mul_f32_e32 v120, v120, v253
	v_mul_f32_e32 v121, v121, v253
	v_mul_f32_e32 v122, v122, v253
	v_mul_f32_e32 v123, v123, v253
	v_exp_f32_e32 v120, v120
	v_exp_f32_e32 v121, v121
	v_exp_f32_e32 v122, v122
	v_exp_f32_e32 v123, v123
	v_add_f32_e32 v120, 1.0, v120
	v_add_f32_e32 v121, 1.0, v121
	v_add_f32_e32 v122, 1.0, v122
	v_add_f32_e32 v123, 1.0, v123
	v_rcp_f32_e32 v120, v120
	v_rcp_f32_e32 v121, v121
	v_rcp_f32_e32 v122, v122
	v_rcp_f32_e32 v123, v123
	v_lshlrev_b32_e32 v224, 16, v134
	v_and_b32_e32 v225, 0xffff0000, v134
	v_lshlrev_b32_e32 v226, 16, v135
	v_and_b32_e32 v227, 0xffff0000, v135
	v_lshlrev_b32_e32 v228, 16, v142
	v_and_b32_e32 v229, 0xffff0000, v142
	v_lshlrev_b32_e32 v230, 16, v143
	v_and_b32_e32 v231, 0xffff0000, v143
	v_fma_f32 v120, v120, v228, v224
	v_fma_f32 v121, v121, v229, v225
	v_fma_f32 v122, v122, v230, v226
	v_fma_f32 v123, v123, v231, v227
	v_mul_f32_e32 v232, v121, v121
	v_mul_f32_e32 v233, v123, v123
	v_fmac_f32_e32 v232, v120, v120
	v_fmac_f32_e32 v233, v122, v122
	v_add_f32_e32 v235, v232, v233
	v_cvt_pk_bf16_f32 v124, v124, v125
	v_cvt_pk_bf16_f32 v125, v126, v127
	v_cvt_pk_bf16_f32 v126, v120, v121
	v_cvt_pk_bf16_f32 v127, v122, v123
	v_mov_b32_e32 v250, v172
	global_store_dwordx4 v250, v[124:127], s[0:1] nt
	v_mul_f32_e32 v116, v116, v253
	v_mul_f32_e32 v117, v117, v253
	v_mul_f32_e32 v118, v118, v253
	v_mul_f32_e32 v119, v119, v253
	v_exp_f32_e32 v116, v116
	v_exp_f32_e32 v117, v117
	v_exp_f32_e32 v118, v118
	v_exp_f32_e32 v119, v119
	v_add_f32_e32 v116, 1.0, v116
	v_add_f32_e32 v117, 1.0, v117
	v_add_f32_e32 v118, 1.0, v118
	v_add_f32_e32 v119, 1.0, v119
	v_rcp_f32_e32 v116, v116
	v_rcp_f32_e32 v117, v117
	v_rcp_f32_e32 v118, v118
	v_rcp_f32_e32 v119, v119
	v_lshlrev_b32_e32 v224, 16, v136
	v_and_b32_e32 v225, 0xffff0000, v136
	v_lshlrev_b32_e32 v226, 16, v137
	v_and_b32_e32 v227, 0xffff0000, v137
	v_lshlrev_b32_e32 v228, 16, v144
	v_and_b32_e32 v229, 0xffff0000, v144
	v_lshlrev_b32_e32 v230, 16, v145
	v_and_b32_e32 v231, 0xffff0000, v145
	v_fma_f32 v116, v116, v228, v224
	v_fma_f32 v117, v117, v229, v225
	v_fma_f32 v118, v118, v230, v226
	v_fma_f32 v119, v119, v231, v227
	v_mul_f32_e32 v232, v117, v117
	v_mul_f32_e32 v233, v119, v119
	v_fmac_f32_e32 v232, v116, v116
	v_fmac_f32_e32 v233, v118, v118
	v_add_f32_e32 v248, v232, v233
	v_mul_f32_e32 v112, v112, v253
	v_mul_f32_e32 v113, v113, v253
	v_mul_f32_e32 v114, v114, v253
	v_mul_f32_e32 v115, v115, v253
	v_exp_f32_e32 v112, v112
	v_exp_f32_e32 v113, v113
	v_exp_f32_e32 v114, v114
	v_exp_f32_e32 v115, v115
	v_add_f32_e32 v112, 1.0, v112
	v_add_f32_e32 v113, 1.0, v113
	v_add_f32_e32 v114, 1.0, v114
	v_add_f32_e32 v115, 1.0, v115
	v_rcp_f32_e32 v112, v112
	v_rcp_f32_e32 v113, v113
	v_rcp_f32_e32 v114, v114
	v_rcp_f32_e32 v115, v115
	v_lshlrev_b32_e32 v224, 16, v138
	v_and_b32_e32 v225, 0xffff0000, v138
	v_lshlrev_b32_e32 v226, 16, v139
	v_and_b32_e32 v227, 0xffff0000, v139
	v_lshlrev_b32_e32 v228, 16, v146
	v_and_b32_e32 v229, 0xffff0000, v146
	v_lshlrev_b32_e32 v230, 16, v147
	v_and_b32_e32 v231, 0xffff0000, v147
	v_fma_f32 v112, v112, v228, v224
	v_fma_f32 v113, v113, v229, v225
	v_fma_f32 v114, v114, v230, v226
	v_fma_f32 v115, v115, v231, v227
	v_mul_f32_e32 v232, v113, v113
	v_mul_f32_e32 v233, v115, v115
	v_fmac_f32_e32 v232, v112, v112
	v_fmac_f32_e32 v233, v114, v114
	v_add_f32_e32 v249, v232, v233
	v_cvt_pk_bf16_f32 v116, v116, v117
	v_cvt_pk_bf16_f32 v117, v118, v119
	v_cvt_pk_bf16_f32 v118, v112, v113
	v_cvt_pk_bf16_f32 v119, v114, v115
	global_store_dwordx4 v250, v[116:119], s[0:1] offset:256 nt
	v_add_f32_e32 v234, v234, v235
	v_add_f32_e32 v248, v248, v249
	v_add_f32_e32 v247, v234, v248
	ds_bpermute_b32 v252, v236, v247
	v_mov_b32_e32 v251, v194
	s_waitcnt lgkmcnt(0)
; __device__ __forceinline__ u32x4 pack8(const f32x4 v0, const f32x4 v1) { u32x4 w; w.x = cvt_pk_bf16(v0[0], v0[1]); w.y = cvt_pk_bf16(v0[2], v0[3]); w.z = cvt_pk_bf16(v1[0], v1[1]); w.w = cvt_pk_bf16(v1[2], v1[3]); return w; }
; __device__ __forceinline__ float sumsq8(const f32x4 a, const f32x4 b) { return ((a[0] * a[0] + a[1] * a[1]) + (a[2] * a[2] + a[3] * a[3])) + ((b[0] * b[0] + b[1] * b[1]) + (b[2] * b[2] + b[3] * b[3])); }
; __device__ __forceinline__ void unpack8(const u32x4 w, f32x4& a, f32x4& b) { a = (f32x4){bf_lo(w.x), bf_hi(w.x), bf_lo(w.y), bf_hi(w.y)}; b = (f32x4){bf_lo(w.z), bf_hi(w.z), bf_lo(w.w), bf_hi(w.w)}; }
;     __device__ __forceinline__ void operator()(const f32x4 (&acc)[2][2][4][2], const Unit& u, int wr, int wc, int fr, int fq) const {
;     ...
;             for (int mm = 0; mm < 2; ++mm) { const int rowl = row0 + ai * HALF + (2 * mh + mm) * 16; p[mm] = *(const f32x4*)(ssq_in + (size_t)rowl * 16 + 4 * fq);
; #pragma unroll
;                 for (int bj = 0; bj < 2; ++bj) { const size_t off = (size_t)rowl * DMODEL + col0 + bj * HALF; rv[mm][bj] = *(const u32x4*)(Rin + off); pw[mm][bj] = *(const u32x4*)(PP + off); } }
; #pragma unroll
;             for (int mm = 0; mm < 2; ++mm) { const int m = 2 * mh + mm; const int row = row0 + ai * HALF + m * 16; float part = 0.f;
;                 float sr = (p[mm][0] + p[mm][1]) + (p[mm][2] + p[mm][3]); sr += __shfl_xor(sr, 16); sr += __shfl_xor(sr, 32); const float r = __builtin_amdgcn_rsqf(sr * (1.0f / DMODEL) + RMS_EPS);
; #pragma unroll
;                 for (int bj = 0; bj < 2; ++bj) { f32x4 r0, r1, p0, p1; unpack8(rv[mm][bj], r0, r1); unpack8(pw[mm][bj], p0, p1);
;                     f32x4 g0 = acc[ai][bj][m][0] * r, g1 = acc[ai][bj][m][1] * r;
; #pragma unroll
;                     for (int e = 0; e < 4; ++e) { g0[e] = __builtin_amdgcn_rcpf(1.f + __builtin_amdgcn_exp2f(-1.4426950408889634f * g0[e])); g1[e] = __builtin_amdgcn_rcpf(1.f + __builtin_amdgcn_exp2f(-1.4426950408889634f * g1[e])); }
;                     const f32x4 h0 = r0 + g0 * p0, h1 = r1 + g1 * p1; part += sumsq8(h0, h1);
;                     *(u32x4*)(XBo + (size_t)row * DMODEL + col0 + bj * HALF) = pack8(h0, h1); }
;                 part += __shfl_xor(part, 16); part += __shfl_xor(part, 32);
;                 if (fq == 0) ssq_out[(size_t)row * 16 + u.pn * 4 + wc] = part; }
	v_add_f32_e32 v247, v247, v252
	ds_bpermute_b32 v252, v237, v247
	s_waitcnt lgkmcnt(0)
	v_add_f32_e32 v247, v247, v252
	s_and_saveexec_b64 s[28:29], vcc
	global_store_dword v251, v247, s[12:13]
	s_or_b64 exec, exec, s[28:29]
	v_add_u32_e32 v250, 0x18000, v172
	v_add_u32_e32 v251, 0xc00, v173
	global_load_dwordx4 v[128:131], v251, s[10:11]
	global_load_dwordx4 v[132:135], v250, s[6:7]
	global_load_dwordx4 v[140:143], v250, s[2:3]
	global_load_dwordx4 v[136:139], v250, s[6:7] offset:256
	global_load_dwordx4 v[144:147], v250, s[2:3] offset:256
	v_add_u32_e32 v250, 0x40000, v172
	v_add_u32_e32 v251, 0x2000, v173
	global_load_dwordx4 v[124:127], v251, s[10:11]
	global_load_dwordx4 v[120:123], v250, s[6:7]
	global_load_dwordx4 v[112:115], v250, s[2:3]
	global_load_dwordx4 v[116:119], v250, s[6:7] offset:256
	global_load_dwordx4 v[216:219], v250, s[2:3] offset:256
	s_waitcnt vmcnt(18)
	v_add_f32_e32 v247, v160, v161
	v_add_f32_e32 v252, v162, v163
	v_add_f32_e32 v247, v247, v252
	ds_bpermute_b32 v252, v236, v247
	s_waitcnt lgkmcnt(0)
	v_add_f32_e32 v247, v247, v252
	ds_bpermute_b32 v252, v237, v247
	s_waitcnt lgkmcnt(0)
	v_add_f32_e32 v247, v247, v252
	v_fmamk_f32 v247, v247, 0x3a800000, v193
	v_rsq_f32_e32 v247, v247
	s_nop 0
	v_mul_f32_e32 v253, 0xbfb8aa3b, v247
	v_mul_f32_e32 v108, v108, v253
	v_mul_f32_e32 v109, v109, v253
	v_mul_f32_e32 v110, v110, v253
	v_mul_f32_e32 v111, v111, v253
	v_exp_f32_e32 v108, v108
	v_exp_f32_e32 v109, v109
	v_exp_f32_e32 v110, v110
	v_exp_f32_e32 v111, v111
	v_add_f32_e32 v108, 1.0, v108
	v_add_f32_e32 v109, 1.0, v109
	v_add_f32_e32 v110, 1.0, v110
	v_add_f32_e32 v111, 1.0, v111
	v_rcp_f32_e32 v108, v108
	v_rcp_f32_e32 v109, v109
	v_rcp_f32_e32 v110, v110
	v_rcp_f32_e32 v111, v111
	v_lshlrev_b32_e32 v224, 16, v164
	v_and_b32_e32 v225, 0xffff0000, v164
	v_lshlrev_b32_e32 v226, 16, v165
	v_and_b32_e32 v227, 0xffff0000, v165
	v_lshlrev_b32_e32 v228, 16, v176
	v_and_b32_e32 v229, 0xffff0000, v176
	v_lshlrev_b32_e32 v230, 16, v177
	v_and_b32_e32 v231, 0xffff0000, v177
	v_fma_f32 v108, v108, v228, v224
	v_fma_f32 v109, v109, v229, v225
	v_fma_f32 v110, v110, v230, v226
	v_fma_f32 v111, v111, v231, v227
	v_mul_f32_e32 v232, v109, v109
	v_mul_f32_e32 v233, v111, v111
	v_fmac_f32_e32 v232, v108, v108
	v_fmac_f32_e32 v233, v110, v110
	v_add_f32_e32 v234, v232, v233
	v_mul_f32_e32 v104, v104, v253
	v_mul_f32_e32 v105, v105, v253
	v_mul_f32_e32 v106, v106, v253
	v_mul_f32_e32 v107, v107, v253
	v_exp_f32_e32 v104, v104
	v_exp_f32_e32 v105, v105
	v_exp_f32_e32 v106, v106
	v_exp_f32_e32 v107, v107
	v_add_f32_e32 v104, 1.0, v104
	v_add_f32_e32 v105, 1.0, v105
	v_add_f32_e32 v106, 1.0, v106
	v_add_f32_e32 v107, 1.0, v107
	v_rcp_f32_e32 v104, v104
	v_rcp_f32_e32 v105, v105
	v_rcp_f32_e32 v106, v106
	v_rcp_f32_e32 v107, v107
	v_lshlrev_b32_e32 v224, 16, v166
	v_and_b32_e32 v225, 0xffff0000, v166
	v_lshlrev_b32_e32 v226, 16, v167
	v_and_b32_e32 v227, 0xffff0000, v167
	v_lshlrev_b32_e32 v228, 16, v178
	v_and_b32_e32 v229, 0xffff0000, v178
	v_lshlrev_b32_e32 v230, 16, v179
	v_and_b32_e32 v231, 0xffff0000, v179
	v_fma_f32 v104, v104, v228, v224
	v_fma_f32 v105, v105, v229, v225
	v_fma_f32 v106, v106, v230, v226
	v_fma_f32 v107, v107, v231, v227
	v_mul_f32_e32 v232, v105, v105
	v_mul_f32_e32 v233, v107, v107
	v_fmac_f32_e32 v232, v104, v104
	v_fmac_f32_e32 v233, v106, v106
	v_add_f32_e32 v235, v232, v233
	v_cvt_pk_bf16_f32 v108, v108, v109
	v_cvt_pk_bf16_f32 v109, v110, v111
	v_cvt_pk_bf16_f32 v110, v104, v105
	v_cvt_pk_bf16_f32 v111, v106, v107
	v_add_u32_e32 v250, 0x8000, v172
	global_store_dwordx4 v250, v[108:111], s[0:1] nt
	v_mul_f32_e32 v100, v100, v253
	v_mul_f32_e32 v101, v101, v253
	v_mul_f32_e32 v102, v102, v253
	v_mul_f32_e32 v103, v103, v253
	v_exp_f32_e32 v100, v100
	v_exp_f32_e32 v101, v101
	v_exp_f32_e32 v102, v102
	v_exp_f32_e32 v103, v103
	v_add_f32_e32 v100, 1.0, v100
	v_add_f32_e32 v101, 1.0, v101
	v_add_f32_e32 v102, 1.0, v102
	v_add_f32_e32 v103, 1.0, v103
	v_rcp_f32_e32 v100, v100
	v_rcp_f32_e32 v101, v101
	v_rcp_f32_e32 v102, v102
	v_rcp_f32_e32 v103, v103
	v_lshlrev_b32_e32 v224, 16, v168
	v_and_b32_e32 v225, 0xffff0000, v168
	v_lshlrev_b32_e32 v226, 16, v169
	v_and_b32_e32 v227, 0xffff0000, v169
	v_lshlrev_b32_e32 v228, 16, v180
	v_and_b32_e32 v229, 0xffff0000, v180
	v_lshlrev_b32_e32 v230, 16, v181
	v_and_b32_e32 v231, 0xffff0000, v181
	v_fma_f32 v100, v100, v228, v224
	v_fma_f32 v101, v101, v229, v225
	v_fma_f32 v102, v102, v230, v226
	v_fma_f32 v103, v103, v231, v227
	v_mul_f32_e32 v232, v101, v101
	v_mul_f32_e32 v233, v103, v103
	v_fmac_f32_e32 v232, v100, v100
	v_fmac_f32_e32 v233, v102, v102
	v_add_f32_e32 v248, v232, v233
	v_mul_f32_e32 v96, v96, v253
	v_mul_f32_e32 v97, v97, v253
	v_mul_f32_e32 v98, v98, v253
	v_mul_f32_e32 v99, v99, v253
	v_exp_f32_e32 v96, v96
	v_exp_f32_e32 v97, v97
	v_exp_f32_e32 v98, v98
	v_exp_f32_e32 v99, v99
	v_add_f32_e32 v96, 1.0, v96
	v_add_f32_e32 v97, 1.0, v97
	v_add_f32_e32 v98, 1.0, v98
	v_add_f32_e32 v99, 1.0, v99
	v_rcp_f32_e32 v96, v96
	v_rcp_f32_e32 v97, v97
	v_rcp_f32_e32 v98, v98
	v_rcp_f32_e32 v99, v99
	v_lshlrev_b32_e32 v224, 16, v170
	v_and_b32_e32 v225, 0xffff0000, v170
	v_lshlrev_b32_e32 v226, 16, v171
	v_and_b32_e32 v227, 0xffff0000, v171
	v_lshlrev_b32_e32 v228, 16, v182
	v_and_b32_e32 v229, 0xffff0000, v182
	v_lshlrev_b32_e32 v230, 16, v183
	v_and_b32_e32 v231, 0xffff0000, v183
	v_fma_f32 v96, v96, v228, v224
	v_fma_f32 v97, v97, v229, v225
	v_fma_f32 v98, v98, v230, v226
	v_fma_f32 v99, v99, v231, v227
	v_mul_f32_e32 v232, v97, v97
	v_mul_f32_e32 v233, v99, v99
	v_fmac_f32_e32 v232, v96, v96
	v_fmac_f32_e32 v233, v98, v98
	v_add_f32_e32 v249, v232, v233
	v_cvt_pk_bf16_f32 v100, v100, v101
	v_cvt_pk_bf16_f32 v101, v102, v103
	v_cvt_pk_bf16_f32 v102, v96, v97
	v_cvt_pk_bf16_f32 v103, v98, v99
	global_store_dwordx4 v250, v[100:103], s[0:1] offset:256 nt
	v_add_f32_e32 v234, v234, v235
	v_add_f32_e32 v248, v248, v249
	v_add_f32_e32 v247, v234, v248
	ds_bpermute_b32 v252, v236, v247
	v_add_u32_e32 v251, 0x400, v194
	s_waitcnt lgkmcnt(0)
; __device__ __forceinline__ u32x4 pack8(const f32x4 v0, const f32x4 v1) { u32x4 w; w.x = cvt_pk_bf16(v0[0], v0[1]); w.y = cvt_pk_bf16(v0[2], v0[3]); w.z = cvt_pk_bf16(v1[0], v1[1]); w.w = cvt_pk_bf16(v1[2], v1[3]); return w; }
; __device__ __forceinline__ float sumsq8(const f32x4 a, const f32x4 b) { return ((a[0] * a[0] + a[1] * a[1]) + (a[2] * a[2] + a[3] * a[3])) + ((b[0] * b[0] + b[1] * b[1]) + (b[2] * b[2] + b[3] * b[3])); }
; __device__ __forceinline__ void unpack8(const u32x4 w, f32x4& a, f32x4& b) { a = (f32x4){bf_lo(w.x), bf_hi(w.x), bf_lo(w.y), bf_hi(w.y)}; b = (f32x4){bf_lo(w.z), bf_hi(w.z), bf_lo(w.w), bf_hi(w.w)}; }
;     __device__ __forceinline__ void operator()(const f32x4 (&acc)[2][2][4][2], const Unit& u, int wr, int wc, int fr, int fq) const {
;     ...
;             for (int mm = 0; mm < 2; ++mm) { const int rowl = row0 + ai * HALF + (2 * mh + mm) * 16; p[mm] = *(const f32x4*)(ssq_in + (size_t)rowl * 16 + 4 * fq);
; #pragma unroll
;                 for (int bj = 0; bj < 2; ++bj) { const size_t off = (size_t)rowl * DMODEL + col0 + bj * HALF; rv[mm][bj] = *(const u32x4*)(Rin + off); pw[mm][bj] = *(const u32x4*)(PP + off); } }
; #pragma unroll
;             for (int mm = 0; mm < 2; ++mm) { const int m = 2 * mh + mm; const int row = row0 + ai * HALF + m * 16; float part = 0.f;
;                 float sr = (p[mm][0] + p[mm][1]) + (p[mm][2] + p[mm][3]); sr += __shfl_xor(sr, 16); sr += __shfl_xor(sr, 32); const float r = __builtin_amdgcn_rsqf(sr * (1.0f / DMODEL) + RMS_EPS);
; #pragma unroll
;                 for (int bj = 0; bj < 2; ++bj) { f32x4 r0, r1, p0, p1; unpack8(rv[mm][bj], r0, r1); unpack8(pw[mm][bj], p0, p1);
;                     f32x4 g0 = acc[ai][bj][m][0] * r, g1 = acc[ai][bj][m][1] * r;
; #pragma unroll
;                     for (int e = 0; e < 4; ++e) { g0[e] = __builtin_amdgcn_rcpf(1.f + __builtin_amdgcn_exp2f(-1.4426950408889634f * g0[e])); g1[e] = __builtin_amdgcn_rcpf(1.f + __builtin_amdgcn_exp2f(-1.4426950408889634f * g1[e])); }
;                     const f32x4 h0 = r0 + g0 * p0, h1 = r1 + g1 * p1; part += sumsq8(h0, h1);
;                     *(u32x4*)(XBo + (size_t)row * DMODEL + col0 + bj * HALF) = pack8(h0, h1); }
;                 part += __shfl_xor(part, 16); part += __shfl_xor(part, 32);
;                 if (fq == 0) ssq_out[(size_t)row * 16 + u.pn * 4 + wc] = part; }
	v_add_f32_e32 v247, v247, v252
	ds_bpermute_b32 v252, v237, v247
	s_waitcnt lgkmcnt(0)
	v_add_f32_e32 v247, v247, v252
	s_and_saveexec_b64 s[28:29], vcc
	global_store_dword v251, v247, s[12:13]
	s_or_b64 exec, exec, s[28:29]
	v_add_u32_e32 v250, 0x48000, v172
	v_add_u32_e32 v251, 0x2400, v173
	global_load_dwordx4 v[160:163], v251, s[10:11]
	global_load_dwordx4 v[164:167], v250, s[6:7]
	global_load_dwordx4 v[176:179], v250, s[2:3]
	global_load_dwordx4 v[168:171], v250, s[6:7] offset:256
	global_load_dwordx4 v[180:183], v250, s[2:3] offset:256
	v_add_u32_e32 v250, 0x50000, v172
	v_add_u32_e32 v251, 0x2800, v173
	global_load_dwordx4 v[108:111], v251, s[10:11]
	global_load_dwordx4 v[104:107], v250, s[6:7]
	global_load_dwordx4 v[96:99], v250, s[2:3]
	global_load_dwordx4 v[100:103], v250, s[6:7] offset:256
	global_load_dwordx4 v[220:223], v250, s[2:3] offset:256
	s_waitcnt vmcnt(26)
	v_add_f32_e32 v247, v184, v185
	v_add_f32_e32 v252, v186, v187
	v_add_f32_e32 v247, v247, v252
	ds_bpermute_b32 v252, v236, v247
	s_waitcnt lgkmcnt(0)
	v_add_f32_e32 v247, v247, v252
	ds_bpermute_b32 v252, v237, v247
	s_waitcnt lgkmcnt(0)
	v_add_f32_e32 v247, v247, v252
	v_fmamk_f32 v247, v247, 0x3a800000, v193
	v_rsq_f32_e32 v247, v247
	s_nop 0
	v_mul_f32_e32 v253, 0xbfb8aa3b, v247
	v_mul_f32_e32 v92, v92, v253
	v_mul_f32_e32 v93, v93, v253
	v_mul_f32_e32 v94, v94, v253
	v_mul_f32_e32 v95, v95, v253
	v_exp_f32_e32 v92, v92
	v_exp_f32_e32 v93, v93
	v_exp_f32_e32 v94, v94
	v_exp_f32_e32 v95, v95
	v_add_f32_e32 v92, 1.0, v92
	v_add_f32_e32 v93, 1.0, v93
	v_add_f32_e32 v94, 1.0, v94
	v_add_f32_e32 v95, 1.0, v95
	v_rcp_f32_e32 v92, v92
	v_rcp_f32_e32 v93, v93
	v_rcp_f32_e32 v94, v94
	v_rcp_f32_e32 v95, v95
	v_lshlrev_b32_e32 v224, 16, v188
	v_and_b32_e32 v225, 0xffff0000, v188
	v_lshlrev_b32_e32 v226, 16, v189
	v_and_b32_e32 v227, 0xffff0000, v189
	v_lshlrev_b32_e32 v228, 16, v208
	v_and_b32_e32 v229, 0xffff0000, v208
	v_lshlrev_b32_e32 v230, 16, v209
	v_and_b32_e32 v231, 0xffff0000, v209
	v_fma_f32 v92, v92, v228, v224
	v_fma_f32 v93, v93, v229, v225
	v_fma_f32 v94, v94, v230, v226
	v_fma_f32 v95, v95, v231, v227
	v_mul_f32_e32 v232, v93, v93
	v_mul_f32_e32 v233, v95, v95
	v_fmac_f32_e32 v232, v92, v92
	v_fmac_f32_e32 v233, v94, v94
	v_add_f32_e32 v234, v232, v233
	v_mul_f32_e32 v88, v88, v253
	v_mul_f32_e32 v89, v89, v253
	v_mul_f32_e32 v90, v90, v253
	v_mul_f32_e32 v91, v91, v253
	v_exp_f32_e32 v88, v88
	v_exp_f32_e32 v89, v89
	v_exp_f32_e32 v90, v90
	v_exp_f32_e32 v91, v91
	v_add_f32_e32 v88, 1.0, v88
	v_add_f32_e32 v89, 1.0, v89
	v_add_f32_e32 v90, 1.0, v90
	v_add_f32_e32 v91, 1.0, v91
	v_rcp_f32_e32 v88, v88
	v_rcp_f32_e32 v89, v89
	v_rcp_f32_e32 v90, v90
	v_rcp_f32_e32 v91, v91
	v_lshlrev_b32_e32 v224, 16, v190
	v_and_b32_e32 v225, 0xffff0000, v190
	v_lshlrev_b32_e32 v226, 16, v191
	v_and_b32_e32 v227, 0xffff0000, v191
	v_lshlrev_b32_e32 v228, 16, v210
	v_and_b32_e32 v229, 0xffff0000, v210
	v_lshlrev_b32_e32 v230, 16, v211
	v_and_b32_e32 v231, 0xffff0000, v211
	v_fma_f32 v88, v88, v228, v224
	v_fma_f32 v89, v89, v229, v225
	v_fma_f32 v90, v90, v230, v226
	v_fma_f32 v91, v91, v231, v227
	v_mul_f32_e32 v232, v89, v89
	v_mul_f32_e32 v233, v91, v91
	v_fmac_f32_e32 v232, v88, v88
	v_fmac_f32_e32 v233, v90, v90
	v_add_f32_e32 v235, v232, v233
	v_cvt_pk_bf16_f32 v92, v92, v93
	v_cvt_pk_bf16_f32 v93, v94, v95
	v_cvt_pk_bf16_f32 v94, v88, v89
	v_cvt_pk_bf16_f32 v95, v90, v91
	v_add_u32_e32 v250, 0x10000, v172
	global_store_dwordx4 v250, v[92:95], s[0:1] nt
	v_mul_f32_e32 v84, v84, v253
	v_mul_f32_e32 v85, v85, v253
	v_mul_f32_e32 v86, v86, v253
	v_mul_f32_e32 v87, v87, v253
	v_exp_f32_e32 v84, v84
	v_exp_f32_e32 v85, v85
	v_exp_f32_e32 v86, v86
	v_exp_f32_e32 v87, v87
	v_add_f32_e32 v84, 1.0, v84
	v_add_f32_e32 v85, 1.0, v85
	v_add_f32_e32 v86, 1.0, v86
	v_add_f32_e32 v87, 1.0, v87
	v_rcp_f32_e32 v84, v84
	v_rcp_f32_e32 v85, v85
	v_rcp_f32_e32 v86, v86
	v_rcp_f32_e32 v87, v87
	v_lshlrev_b32_e32 v224, 16, v204
	v_and_b32_e32 v225, 0xffff0000, v204
	v_lshlrev_b32_e32 v226, 16, v205
	v_and_b32_e32 v227, 0xffff0000, v205
	v_lshlrev_b32_e32 v228, 16, v212
	v_and_b32_e32 v229, 0xffff0000, v212
	v_lshlrev_b32_e32 v230, 16, v213
	v_and_b32_e32 v231, 0xffff0000, v213
	v_fma_f32 v84, v84, v228, v224
	v_fma_f32 v85, v85, v229, v225
	v_fma_f32 v86, v86, v230, v226
	v_fma_f32 v87, v87, v231, v227
	v_mul_f32_e32 v232, v85, v85
	v_mul_f32_e32 v233, v87, v87
	v_fmac_f32_e32 v232, v84, v84
	v_fmac_f32_e32 v233, v86, v86
	v_add_f32_e32 v248, v232, v233
	v_mul_f32_e32 v80, v80, v253
	v_mul_f32_e32 v81, v81, v253
	v_mul_f32_e32 v82, v82, v253
	v_mul_f32_e32 v83, v83, v253
	v_exp_f32_e32 v80, v80
	v_exp_f32_e32 v81, v81
	v_exp_f32_e32 v82, v82
	v_exp_f32_e32 v83, v83
	v_add_f32_e32 v80, 1.0, v80
	v_add_f32_e32 v81, 1.0, v81
	v_add_f32_e32 v82, 1.0, v82
	v_add_f32_e32 v83, 1.0, v83
	v_rcp_f32_e32 v80, v80
	v_rcp_f32_e32 v81, v81
	v_rcp_f32_e32 v82, v82
	v_rcp_f32_e32 v83, v83
	v_lshlrev_b32_e32 v224, 16, v206
	v_and_b32_e32 v225, 0xffff0000, v206
	v_lshlrev_b32_e32 v226, 16, v207
	v_and_b32_e32 v227, 0xffff0000, v207
	v_lshlrev_b32_e32 v228, 16, v214
	v_and_b32_e32 v229, 0xffff0000, v214
	v_lshlrev_b32_e32 v230, 16, v215
	v_and_b32_e32 v231, 0xffff0000, v215
	v_fma_f32 v80, v80, v228, v224
	v_fma_f32 v81, v81, v229, v225
	v_fma_f32 v82, v82, v230, v226
	v_fma_f32 v83, v83, v231, v227
	v_mul_f32_e32 v232, v81, v81
	v_mul_f32_e32 v233, v83, v83
	v_fmac_f32_e32 v232, v80, v80
	v_fmac_f32_e32 v233, v82, v82
	v_add_f32_e32 v249, v232, v233
	v_cvt_pk_bf16_f32 v84, v84, v85
	v_cvt_pk_bf16_f32 v85, v86, v87
	v_cvt_pk_bf16_f32 v86, v80, v81
	v_cvt_pk_bf16_f32 v87, v82, v83
	global_store_dwordx4 v250, v[84:87], s[0:1] offset:256 nt
	v_add_f32_e32 v234, v234, v235
	v_add_f32_e32 v248, v248, v249
	v_add_f32_e32 v247, v234, v248
	ds_bpermute_b32 v252, v236, v247
	v_add_u32_e32 v251, 0x800, v194
	s_waitcnt lgkmcnt(0)
; __device__ __forceinline__ u32x4 pack8(const f32x4 v0, const f32x4 v1) { u32x4 w; w.x = cvt_pk_bf16(v0[0], v0[1]); w.y = cvt_pk_bf16(v0[2], v0[3]); w.z = cvt_pk_bf16(v1[0], v1[1]); w.w = cvt_pk_bf16(v1[2], v1[3]); return w; }
; __device__ __forceinline__ float sumsq8(const f32x4 a, const f32x4 b) { return ((a[0] * a[0] + a[1] * a[1]) + (a[2] * a[2] + a[3] * a[3])) + ((b[0] * b[0] + b[1] * b[1]) + (b[2] * b[2] + b[3] * b[3])); }
; __device__ __forceinline__ void unpack8(const u32x4 w, f32x4& a, f32x4& b) { a = (f32x4){bf_lo(w.x), bf_hi(w.x), bf_lo(w.y), bf_hi(w.y)}; b = (f32x4){bf_lo(w.z), bf_hi(w.z), bf_lo(w.w), bf_hi(w.w)}; }
;     __device__ __forceinline__ void operator()(const f32x4 (&acc)[2][2][4][2], const Unit& u, int wr, int wc, int fr, int fq) const {
;     ...
;             for (int mm = 0; mm < 2; ++mm) { const int rowl = row0 + ai * HALF + (2 * mh + mm) * 16; p[mm] = *(const f32x4*)(ssq_in + (size_t)rowl * 16 + 4 * fq);
; #pragma unroll
;                 for (int bj = 0; bj < 2; ++bj) { const size_t off = (size_t)rowl * DMODEL + col0 + bj * HALF; rv[mm][bj] = *(const u32x4*)(Rin + off); pw[mm][bj] = *(const u32x4*)(PP + off); } }
; #pragma unroll
;             for (int mm = 0; mm < 2; ++mm) { const int m = 2 * mh + mm; const int row = row0 + ai * HALF + m * 16; float part = 0.f;
;                 float sr = (p[mm][0] + p[mm][1]) + (p[mm][2] + p[mm][3]); sr += __shfl_xor(sr, 16); sr += __shfl_xor(sr, 32); const float r = __builtin_amdgcn_rsqf(sr * (1.0f / DMODEL) + RMS_EPS);
; #pragma unroll
;                 for (int bj = 0; bj < 2; ++bj) { f32x4 r0, r1, p0, p1; unpack8(rv[mm][bj], r0, r1); unpack8(pw[mm][bj], p0, p1);
;                     f32x4 g0 = acc[ai][bj][m][0] * r, g1 = acc[ai][bj][m][1] * r;
; #pragma unroll
;                     for (int e = 0; e < 4; ++e) { g0[e] = __builtin_amdgcn_rcpf(1.f + __builtin_amdgcn_exp2f(-1.4426950408889634f * g0[e])); g1[e] = __builtin_amdgcn_rcpf(1.f + __builtin_amdgcn_exp2f(-1.4426950408889634f * g1[e])); }
;                     const f32x4 h0 = r0 + g0 * p0, h1 = r1 + g1 * p1; part += sumsq8(h0, h1);
;                     *(u32x4*)(XBo + (size_t)row * DMODEL + col0 + bj * HALF) = pack8(h0, h1); }
;                 part += __shfl_xor(part, 16); part += __shfl_xor(part, 32);
;                 if (fq == 0) ssq_out[(size_t)row * 16 + u.pn * 4 + wc] = part; }
	v_add_f32_e32 v247, v247, v252
	ds_bpermute_b32 v252, v237, v247
	s_waitcnt lgkmcnt(0)
	v_add_f32_e32 v247, v247, v252
	s_and_saveexec_b64 s[28:29], vcc
	global_store_dword v251, v247, s[12:13]
	s_or_b64 exec, exec, s[28:29]
	v_add_u32_e32 v250, 0x58000, v172
	v_add_u32_e32 v251, 0x2c00, v173
	global_load_dwordx4 v[184:187], v251, s[10:11]
	global_load_dwordx4 v[188:191], v250, s[6:7]
	global_load_dwordx4 v[208:211], v250, s[2:3]
	global_load_dwordx4 v[204:207], v250, s[6:7] offset:256
	global_load_dwordx4 v[212:215], v250, s[2:3] offset:256
	s_waitcnt vmcnt(26)
	v_add_f32_e32 v247, v128, v129
	v_add_f32_e32 v252, v130, v131
	v_add_f32_e32 v247, v247, v252
	ds_bpermute_b32 v252, v236, v247
	s_waitcnt lgkmcnt(0)
	v_add_f32_e32 v247, v247, v252
	ds_bpermute_b32 v252, v237, v247
	s_waitcnt lgkmcnt(0)
	v_add_f32_e32 v247, v247, v252
	v_fmamk_f32 v247, v247, 0x3a800000, v193
	v_rsq_f32_e32 v247, v247
	s_nop 0
	v_mul_f32_e32 v253, 0xbfb8aa3b, v247
	v_mul_f32_e32 v76, v76, v253
	v_mul_f32_e32 v77, v77, v253
	v_mul_f32_e32 v78, v78, v253
	v_mul_f32_e32 v79, v79, v253
	v_exp_f32_e32 v76, v76
	v_exp_f32_e32 v77, v77
	v_exp_f32_e32 v78, v78
	v_exp_f32_e32 v79, v79
	v_add_f32_e32 v76, 1.0, v76
	v_add_f32_e32 v77, 1.0, v77
	v_add_f32_e32 v78, 1.0, v78
	v_add_f32_e32 v79, 1.0, v79
	v_rcp_f32_e32 v76, v76
	v_rcp_f32_e32 v77, v77
	v_rcp_f32_e32 v78, v78
	v_rcp_f32_e32 v79, v79
	v_lshlrev_b32_e32 v224, 16, v132
	v_and_b32_e32 v225, 0xffff0000, v132
	v_lshlrev_b32_e32 v226, 16, v133
	v_and_b32_e32 v227, 0xffff0000, v133
	v_lshlrev_b32_e32 v228, 16, v140
	v_and_b32_e32 v229, 0xffff0000, v140
	v_lshlrev_b32_e32 v230, 16, v141
	v_and_b32_e32 v231, 0xffff0000, v141
	v_fma_f32 v76, v76, v228, v224
	v_fma_f32 v77, v77, v229, v225
	v_fma_f32 v78, v78, v230, v226
	v_fma_f32 v79, v79, v231, v227
	v_mul_f32_e32 v232, v77, v77
	v_mul_f32_e32 v233, v79, v79
	v_fmac_f32_e32 v232, v76, v76
	v_fmac_f32_e32 v233, v78, v78
	v_add_f32_e32 v234, v232, v233
	v_mul_f32_e32 v72, v72, v253
	v_mul_f32_e32 v73, v73, v253
	v_mul_f32_e32 v74, v74, v253
	v_mul_f32_e32 v75, v75, v253
	v_exp_f32_e32 v72, v72
	v_exp_f32_e32 v73, v73
	v_exp_f32_e32 v74, v74
	v_exp_f32_e32 v75, v75
	v_add_f32_e32 v72, 1.0, v72
	v_add_f32_e32 v73, 1.0, v73
	v_add_f32_e32 v74, 1.0, v74
	v_add_f32_e32 v75, 1.0, v75
	v_rcp_f32_e32 v72, v72
	v_rcp_f32_e32 v73, v73
	v_rcp_f32_e32 v74, v74
	v_rcp_f32_e32 v75, v75
	v_lshlrev_b32_e32 v224, 16, v134
	v_and_b32_e32 v225, 0xffff0000, v134
	v_lshlrev_b32_e32 v226, 16, v135
	v_and_b32_e32 v227, 0xffff0000, v135
	v_lshlrev_b32_e32 v228, 16, v142
	v_and_b32_e32 v229, 0xffff0000, v142
	v_lshlrev_b32_e32 v230, 16, v143
	v_and_b32_e32 v231, 0xffff0000, v143
	v_fma_f32 v72, v72, v228, v224
	v_fma_f32 v73, v73, v229, v225
	v_fma_f32 v74, v74, v230, v226
	v_fma_f32 v75, v75, v231, v227
	v_mul_f32_e32 v232, v73, v73
	v_mul_f32_e32 v233, v75, v75
	v_fmac_f32_e32 v232, v72, v72
	v_fmac_f32_e32 v233, v74, v74
	v_add_f32_e32 v235, v232, v233
	v_cvt_pk_bf16_f32 v76, v76, v77
	v_cvt_pk_bf16_f32 v77, v78, v79
	v_cvt_pk_bf16_f32 v78, v72, v73
	v_cvt_pk_bf16_f32 v79, v74, v75
	v_add_u32_e32 v250, 0x18000, v172
	global_store_dwordx4 v250, v[76:79], s[0:1] nt
	v_mul_f32_e32 v68, v68, v253
	v_mul_f32_e32 v69, v69, v253
	v_mul_f32_e32 v70, v70, v253
	v_mul_f32_e32 v71, v71, v253
	v_exp_f32_e32 v68, v68
	v_exp_f32_e32 v69, v69
	v_exp_f32_e32 v70, v70
	v_exp_f32_e32 v71, v71
	v_add_f32_e32 v68, 1.0, v68
	v_add_f32_e32 v69, 1.0, v69
	v_add_f32_e32 v70, 1.0, v70
	v_add_f32_e32 v71, 1.0, v71
	v_rcp_f32_e32 v68, v68
	v_rcp_f32_e32 v69, v69
	v_rcp_f32_e32 v70, v70
	v_rcp_f32_e32 v71, v71
	v_lshlrev_b32_e32 v224, 16, v136
	v_and_b32_e32 v225, 0xffff0000, v136
	v_lshlrev_b32_e32 v226, 16, v137
	v_and_b32_e32 v227, 0xffff0000, v137
	v_lshlrev_b32_e32 v228, 16, v144
	v_and_b32_e32 v229, 0xffff0000, v144
	v_lshlrev_b32_e32 v230, 16, v145
	v_and_b32_e32 v231, 0xffff0000, v145
	v_fma_f32 v68, v68, v228, v224
	v_fma_f32 v69, v69, v229, v225
	v_fma_f32 v70, v70, v230, v226
	v_fma_f32 v71, v71, v231, v227
	v_mul_f32_e32 v232, v69, v69
	v_mul_f32_e32 v233, v71, v71
	v_fmac_f32_e32 v232, v68, v68
	v_fmac_f32_e32 v233, v70, v70
	v_add_f32_e32 v248, v232, v233
	v_mul_f32_e32 v64, v64, v253
	v_mul_f32_e32 v65, v65, v253
	v_mul_f32_e32 v66, v66, v253
	v_mul_f32_e32 v67, v67, v253
	v_exp_f32_e32 v64, v64
	v_exp_f32_e32 v65, v65
	v_exp_f32_e32 v66, v66
	v_exp_f32_e32 v67, v67
	v_add_f32_e32 v64, 1.0, v64
	v_add_f32_e32 v65, 1.0, v65
	v_add_f32_e32 v66, 1.0, v66
	v_add_f32_e32 v67, 1.0, v67
	v_rcp_f32_e32 v64, v64
	v_rcp_f32_e32 v65, v65
	v_rcp_f32_e32 v66, v66
	v_rcp_f32_e32 v67, v67
	v_lshlrev_b32_e32 v224, 16, v138
	v_and_b32_e32 v225, 0xffff0000, v138
	v_lshlrev_b32_e32 v226, 16, v139
	v_and_b32_e32 v227, 0xffff0000, v139
	v_lshlrev_b32_e32 v228, 16, v146
	v_and_b32_e32 v229, 0xffff0000, v146
	v_lshlrev_b32_e32 v230, 16, v147
	v_and_b32_e32 v231, 0xffff0000, v147
	v_fma_f32 v64, v64, v228, v224
	v_fma_f32 v65, v65, v229, v225
	v_fma_f32 v66, v66, v230, v226
	v_fma_f32 v67, v67, v231, v227
	v_mul_f32_e32 v232, v65, v65
	v_mul_f32_e32 v233, v67, v67
	v_fmac_f32_e32 v232, v64, v64
	v_fmac_f32_e32 v233, v66, v66
	v_add_f32_e32 v249, v232, v233
	v_cvt_pk_bf16_f32 v68, v68, v69
	v_cvt_pk_bf16_f32 v69, v70, v71
	v_cvt_pk_bf16_f32 v70, v64, v65
	v_cvt_pk_bf16_f32 v71, v66, v67
	global_store_dwordx4 v250, v[68:71], s[0:1] offset:256 nt
	v_add_f32_e32 v234, v234, v235
	v_add_f32_e32 v248, v248, v249
	v_add_f32_e32 v247, v234, v248
	ds_bpermute_b32 v252, v236, v247
	v_add_u32_e32 v251, 0xc00, v194
	s_waitcnt lgkmcnt(0)
	v_add_f32_e32 v247, v247, v252
	ds_bpermute_b32 v252, v237, v247
	s_waitcnt lgkmcnt(0)
; __device__ __forceinline__ u32x4 pack8(const f32x4 v0, const f32x4 v1) { u32x4 w; w.x = cvt_pk_bf16(v0[0], v0[1]); w.y = cvt_pk_bf16(v0[2], v0[3]); w.z = cvt_pk_bf16(v1[0], v1[1]); w.w = cvt_pk_bf16(v1[2], v1[3]); return w; }
; __device__ __forceinline__ float sumsq8(const f32x4 a, const f32x4 b) { return ((a[0] * a[0] + a[1] * a[1]) + (a[2] * a[2] + a[3] * a[3])) + ((b[0] * b[0] + b[1] * b[1]) + (b[2] * b[2] + b[3] * b[3])); }
; __device__ __forceinline__ void unpack8(const u32x4 w, f32x4& a, f32x4& b) { a = (f32x4){bf_lo(w.x), bf_hi(w.x), bf_lo(w.y), bf_hi(w.y)}; b = (f32x4){bf_lo(w.z), bf_hi(w.z), bf_lo(w.w), bf_hi(w.w)}; }
;     __device__ __forceinline__ void operator()(const f32x4 (&acc)[2][2][4][2], const Unit& u, int wr, int wc, int fr, int fq) const {
;     ...
;             for (int mm = 0; mm < 2; ++mm) { const int rowl = row0 + ai * HALF + (2 * mh + mm) * 16; p[mm] = *(const f32x4*)(ssq_in + (size_t)rowl * 16 + 4 * fq);
; #pragma unroll
;                 for (int bj = 0; bj < 2; ++bj) { const size_t off = (size_t)rowl * DMODEL + col0 + bj * HALF; rv[mm][bj] = *(const u32x4*)(Rin + off); pw[mm][bj] = *(const u32x4*)(PP + off); } }
; #pragma unroll
;             for (int mm = 0; mm < 2; ++mm) { const int m = 2 * mh + mm; const int row = row0 + ai * HALF + m * 16; float part = 0.f;
;                 float sr = (p[mm][0] + p[mm][1]) + (p[mm][2] + p[mm][3]); sr += __shfl_xor(sr, 16); sr += __shfl_xor(sr, 32); const float r = __builtin_amdgcn_rsqf(sr * (1.0f / DMODEL) + RMS_EPS);
; #pragma unroll
;                 for (int bj = 0; bj < 2; ++bj) { f32x4 r0, r1, p0, p1; unpack8(rv[mm][bj], r0, r1); unpack8(pw[mm][bj], p0, p1);
;                     f32x4 g0 = acc[ai][bj][m][0] * r, g1 = acc[ai][bj][m][1] * r;
; #pragma unroll
;                     for (int e = 0; e < 4; ++e) { g0[e] = __builtin_amdgcn_rcpf(1.f + __builtin_amdgcn_exp2f(-1.4426950408889634f * g0[e])); g1[e] = __builtin_amdgcn_rcpf(1.f + __builtin_amdgcn_exp2f(-1.4426950408889634f * g1[e])); }
;                     const f32x4 h0 = r0 + g0 * p0, h1 = r1 + g1 * p1; part += sumsq8(h0, h1);
;                     *(u32x4*)(XBo + (size_t)row * DMODEL + col0 + bj * HALF) = pack8(h0, h1); }
;                 part += __shfl_xor(part, 16); part += __shfl_xor(part, 32);
;                 if (fq == 0) ssq_out[(size_t)row * 16 + u.pn * 4 + wc] = part; }
	v_add_f32_e32 v247, v247, v252
	s_and_saveexec_b64 s[28:29], vcc
	global_store_dword v251, v247, s[12:13]
	s_or_b64 exec, exec, s[28:29]
	s_waitcnt vmcnt(24)
	v_add_f32_e32 v247, v124, v125
	v_add_f32_e32 v252, v126, v127
	v_add_f32_e32 v247, v247, v252
	ds_bpermute_b32 v252, v236, v247
	s_waitcnt lgkmcnt(0)
	v_add_f32_e32 v247, v247, v252
	ds_bpermute_b32 v252, v237, v247
	s_waitcnt lgkmcnt(0)
	v_add_f32_e32 v247, v247, v252
	v_fmamk_f32 v247, v247, 0x3a800000, v193
	v_rsq_f32_e32 v247, v247
	s_nop 0
	v_mul_f32_e32 v253, 0xbfb8aa3b, v247
	v_mul_f32_e32 v60, v60, v253
	v_mul_f32_e32 v61, v61, v253
	v_mul_f32_e32 v62, v62, v253
	v_mul_f32_e32 v63, v63, v253
	v_exp_f32_e32 v60, v60
	v_exp_f32_e32 v61, v61
	v_exp_f32_e32 v62, v62
	v_exp_f32_e32 v63, v63
	v_add_f32_e32 v60, 1.0, v60
	v_add_f32_e32 v61, 1.0, v61
	v_add_f32_e32 v62, 1.0, v62
	v_add_f32_e32 v63, 1.0, v63
	v_rcp_f32_e32 v60, v60
	v_rcp_f32_e32 v61, v61
	v_rcp_f32_e32 v62, v62
	v_rcp_f32_e32 v63, v63
	v_lshlrev_b32_e32 v224, 16, v120
	v_and_b32_e32 v225, 0xffff0000, v120
	v_lshlrev_b32_e32 v226, 16, v121
	v_and_b32_e32 v227, 0xffff0000, v121
	v_lshlrev_b32_e32 v228, 16, v112
	v_and_b32_e32 v229, 0xffff0000, v112
	v_lshlrev_b32_e32 v230, 16, v113
	v_and_b32_e32 v231, 0xffff0000, v113
	v_fma_f32 v60, v60, v228, v224
	v_fma_f32 v61, v61, v229, v225
	v_fma_f32 v62, v62, v230, v226
	v_fma_f32 v63, v63, v231, v227
	v_mul_f32_e32 v232, v61, v61
	v_mul_f32_e32 v233, v63, v63
	v_fmac_f32_e32 v232, v60, v60
	v_fmac_f32_e32 v233, v62, v62
	v_add_f32_e32 v234, v232, v233
	v_mul_f32_e32 v56, v56, v253
	v_mul_f32_e32 v57, v57, v253
	v_mul_f32_e32 v58, v58, v253
	v_mul_f32_e32 v59, v59, v253
	v_exp_f32_e32 v56, v56
	v_exp_f32_e32 v57, v57
	v_exp_f32_e32 v58, v58
	v_exp_f32_e32 v59, v59
	v_add_f32_e32 v56, 1.0, v56
	v_add_f32_e32 v57, 1.0, v57
	v_add_f32_e32 v58, 1.0, v58
	v_add_f32_e32 v59, 1.0, v59
	v_rcp_f32_e32 v56, v56
	v_rcp_f32_e32 v57, v57
	v_rcp_f32_e32 v58, v58
	v_rcp_f32_e32 v59, v59
	v_lshlrev_b32_e32 v224, 16, v122
	v_and_b32_e32 v225, 0xffff0000, v122
	v_lshlrev_b32_e32 v226, 16, v123
	v_and_b32_e32 v227, 0xffff0000, v123
	v_lshlrev_b32_e32 v228, 16, v114
	v_and_b32_e32 v229, 0xffff0000, v114
	v_lshlrev_b32_e32 v230, 16, v115
	v_and_b32_e32 v231, 0xffff0000, v115
	v_fma_f32 v56, v56, v228, v224
	v_fma_f32 v57, v57, v229, v225
	v_fma_f32 v58, v58, v230, v226
	v_fma_f32 v59, v59, v231, v227
	v_mul_f32_e32 v232, v57, v57
	v_mul_f32_e32 v233, v59, v59
	v_fmac_f32_e32 v232, v56, v56
	v_fmac_f32_e32 v233, v58, v58
	v_add_f32_e32 v235, v232, v233
	v_cvt_pk_bf16_f32 v60, v60, v61
	v_cvt_pk_bf16_f32 v61, v62, v63
	v_cvt_pk_bf16_f32 v62, v56, v57
	v_cvt_pk_bf16_f32 v63, v58, v59
	v_add_u32_e32 v250, 0x40000, v172
	global_store_dwordx4 v250, v[60:63], s[0:1] nt
	v_mul_f32_e32 v52, v52, v253
	v_mul_f32_e32 v53, v53, v253
	v_mul_f32_e32 v54, v54, v253
	v_mul_f32_e32 v55, v55, v253
	v_exp_f32_e32 v52, v52
	v_exp_f32_e32 v53, v53
	v_exp_f32_e32 v54, v54
	v_exp_f32_e32 v55, v55
	v_add_f32_e32 v52, 1.0, v52
	v_add_f32_e32 v53, 1.0, v53
	v_add_f32_e32 v54, 1.0, v54
	v_add_f32_e32 v55, 1.0, v55
	v_rcp_f32_e32 v52, v52
	v_rcp_f32_e32 v53, v53
	v_rcp_f32_e32 v54, v54
	v_rcp_f32_e32 v55, v55
	v_lshlrev_b32_e32 v224, 16, v116
	v_and_b32_e32 v225, 0xffff0000, v116
	v_lshlrev_b32_e32 v226, 16, v117
	v_and_b32_e32 v227, 0xffff0000, v117
	v_lshlrev_b32_e32 v228, 16, v216
	v_and_b32_e32 v229, 0xffff0000, v216
	v_lshlrev_b32_e32 v230, 16, v217
	v_and_b32_e32 v231, 0xffff0000, v217
	v_fma_f32 v52, v52, v228, v224
	v_fma_f32 v53, v53, v229, v225
	v_fma_f32 v54, v54, v230, v226
	v_fma_f32 v55, v55, v231, v227
	v_mul_f32_e32 v232, v53, v53
	v_mul_f32_e32 v233, v55, v55
	v_fmac_f32_e32 v232, v52, v52
	v_fmac_f32_e32 v233, v54, v54
	v_add_f32_e32 v248, v232, v233
	v_mul_f32_e32 v48, v48, v253
	v_mul_f32_e32 v49, v49, v253
	v_mul_f32_e32 v50, v50, v253
	v_mul_f32_e32 v51, v51, v253
	v_exp_f32_e32 v48, v48
	v_exp_f32_e32 v49, v49
	v_exp_f32_e32 v50, v50
	v_exp_f32_e32 v51, v51
	v_add_f32_e32 v48, 1.0, v48
	v_add_f32_e32 v49, 1.0, v49
	v_add_f32_e32 v50, 1.0, v50
	v_add_f32_e32 v51, 1.0, v51
	v_rcp_f32_e32 v48, v48
	v_rcp_f32_e32 v49, v49
	v_rcp_f32_e32 v50, v50
	v_rcp_f32_e32 v51, v51
	v_lshlrev_b32_e32 v224, 16, v118
	v_and_b32_e32 v225, 0xffff0000, v118
	v_lshlrev_b32_e32 v226, 16, v119
	v_and_b32_e32 v227, 0xffff0000, v119
	v_lshlrev_b32_e32 v228, 16, v218
	v_and_b32_e32 v229, 0xffff0000, v218
	v_lshlrev_b32_e32 v230, 16, v219
	v_and_b32_e32 v231, 0xffff0000, v219
	v_fma_f32 v48, v48, v228, v224
	v_fma_f32 v49, v49, v229, v225
	v_fma_f32 v50, v50, v230, v226
	v_fma_f32 v51, v51, v231, v227
	v_mul_f32_e32 v232, v49, v49
	v_mul_f32_e32 v233, v51, v51
	v_fmac_f32_e32 v232, v48, v48
	v_fmac_f32_e32 v233, v50, v50
	v_add_f32_e32 v249, v232, v233
	v_cvt_pk_bf16_f32 v52, v52, v53
	v_cvt_pk_bf16_f32 v53, v54, v55
	v_cvt_pk_bf16_f32 v54, v48, v49
	v_cvt_pk_bf16_f32 v55, v50, v51
	global_store_dwordx4 v250, v[52:55], s[0:1] offset:256 nt
	v_add_f32_e32 v234, v234, v235
	v_add_f32_e32 v248, v248, v249
	v_add_f32_e32 v247, v234, v248
	ds_bpermute_b32 v252, v236, v247
	v_add_u32_e32 v251, 0x2000, v194
	s_waitcnt lgkmcnt(0)
	v_add_f32_e32 v247, v247, v252
	ds_bpermute_b32 v252, v237, v247
	s_waitcnt lgkmcnt(0)
	v_add_f32_e32 v247, v247, v252
	s_and_saveexec_b64 s[28:29], vcc
	global_store_dword v251, v247, s[12:13]
	s_or_b64 exec, exec, s[28:29]
	s_waitcnt vmcnt(19)
	v_add_f32_e32 v247, v160, v161
	v_add_f32_e32 v252, v162, v163
	v_add_f32_e32 v247, v247, v252
	ds_bpermute_b32 v252, v236, v247
	s_waitcnt lgkmcnt(0)
	v_add_f32_e32 v247, v247, v252
	ds_bpermute_b32 v252, v237, v247
	s_waitcnt lgkmcnt(0)
; __device__ __forceinline__ u32x4 pack8(const f32x4 v0, const f32x4 v1) { u32x4 w; w.x = cvt_pk_bf16(v0[0], v0[1]); w.y = cvt_pk_bf16(v0[2], v0[3]); w.z = cvt_pk_bf16(v1[0], v1[1]); w.w = cvt_pk_bf16(v1[2], v1[3]); return w; }
; __device__ __forceinline__ float sumsq8(const f32x4 a, const f32x4 b) { return ((a[0] * a[0] + a[1] * a[1]) + (a[2] * a[2] + a[3] * a[3])) + ((b[0] * b[0] + b[1] * b[1]) + (b[2] * b[2] + b[3] * b[3])); }
; __device__ __forceinline__ void unpack8(const u32x4 w, f32x4& a, f32x4& b) { a = (f32x4){bf_lo(w.x), bf_hi(w.x), bf_lo(w.y), bf_hi(w.y)}; b = (f32x4){bf_lo(w.z), bf_hi(w.z), bf_lo(w.w), bf_hi(w.w)}; }
;     __device__ __forceinline__ void operator()(const f32x4 (&acc)[2][2][4][2], const Unit& u, int wr, int wc, int fr, int fq) const {
;     ...
;             for (int mm = 0; mm < 2; ++mm) { const int rowl = row0 + ai * HALF + (2 * mh + mm) * 16; p[mm] = *(const f32x4*)(ssq_in + (size_t)rowl * 16 + 4 * fq);
; #pragma unroll
;                 for (int bj = 0; bj < 2; ++bj) { const size_t off = (size_t)rowl * DMODEL + col0 + bj * HALF; rv[mm][bj] = *(const u32x4*)(Rin + off); pw[mm][bj] = *(const u32x4*)(PP + off); } }
; #pragma unroll
;             for (int mm = 0; mm < 2; ++mm) { const int m = 2 * mh + mm; const int row = row0 + ai * HALF + m * 16; float part = 0.f;
;                 float sr = (p[mm][0] + p[mm][1]) + (p[mm][2] + p[mm][3]); sr += __shfl_xor(sr, 16); sr += __shfl_xor(sr, 32); const float r = __builtin_amdgcn_rsqf(sr * (1.0f / DMODEL) + RMS_EPS);
; #pragma unroll
;                 for (int bj = 0; bj < 2; ++bj) { f32x4 r0, r1, p0, p1; unpack8(rv[mm][bj], r0, r1); unpack8(pw[mm][bj], p0, p1);
;                     f32x4 g0 = acc[ai][bj][m][0] * r, g1 = acc[ai][bj][m][1] * r;
; #pragma unroll
;                     for (int e = 0; e < 4; ++e) { g0[e] = __builtin_amdgcn_rcpf(1.f + __builtin_amdgcn_exp2f(-1.4426950408889634f * g0[e])); g1[e] = __builtin_amdgcn_rcpf(1.f + __builtin_amdgcn_exp2f(-1.4426950408889634f * g1[e])); }
;                     const f32x4 h0 = r0 + g0 * p0, h1 = r1 + g1 * p1; part += sumsq8(h0, h1);
;                     *(u32x4*)(XBo + (size_t)row * DMODEL + col0 + bj * HALF) = pack8(h0, h1); }
;                 part += __shfl_xor(part, 16); part += __shfl_xor(part, 32);
;                 if (fq == 0) ssq_out[(size_t)row * 16 + u.pn * 4 + wc] = part; }
	v_add_f32_e32 v247, v247, v252
	v_fmamk_f32 v247, v247, 0x3a800000, v193
	v_rsq_f32_e32 v247, v247
	s_nop 0
	v_mul_f32_e32 v253, 0xbfb8aa3b, v247
	v_mul_f32_e32 v44, v44, v253
	v_mul_f32_e32 v45, v45, v253
	v_mul_f32_e32 v46, v46, v253
	v_mul_f32_e32 v47, v47, v253
	v_exp_f32_e32 v44, v44
	v_exp_f32_e32 v45, v45
	v_exp_f32_e32 v46, v46
	v_exp_f32_e32 v47, v47
	v_add_f32_e32 v44, 1.0, v44
	v_add_f32_e32 v45, 1.0, v45
	v_add_f32_e32 v46, 1.0, v46
	v_add_f32_e32 v47, 1.0, v47
	v_rcp_f32_e32 v44, v44
	v_rcp_f32_e32 v45, v45
	v_rcp_f32_e32 v46, v46
	v_rcp_f32_e32 v47, v47
	v_lshlrev_b32_e32 v224, 16, v164
	v_and_b32_e32 v225, 0xffff0000, v164
	v_lshlrev_b32_e32 v226, 16, v165
	v_and_b32_e32 v227, 0xffff0000, v165
	v_lshlrev_b32_e32 v228, 16, v176
	v_and_b32_e32 v229, 0xffff0000, v176
	v_lshlrev_b32_e32 v230, 16, v177
	v_and_b32_e32 v231, 0xffff0000, v177
	v_fma_f32 v44, v44, v228, v224
	v_fma_f32 v45, v45, v229, v225
	v_fma_f32 v46, v46, v230, v226
	v_fma_f32 v47, v47, v231, v227
	v_mul_f32_e32 v232, v45, v45
	v_mul_f32_e32 v233, v47, v47
	v_fmac_f32_e32 v232, v44, v44
	v_fmac_f32_e32 v233, v46, v46
	v_add_f32_e32 v234, v232, v233
	v_mul_f32_e32 v40, v40, v253
	v_mul_f32_e32 v41, v41, v253
	v_mul_f32_e32 v42, v42, v253
	v_mul_f32_e32 v43, v43, v253
	v_exp_f32_e32 v40, v40
	v_exp_f32_e32 v41, v41
	v_exp_f32_e32 v42, v42
	v_exp_f32_e32 v43, v43
	v_add_f32_e32 v40, 1.0, v40
	v_add_f32_e32 v41, 1.0, v41
	v_add_f32_e32 v42, 1.0, v42
	v_add_f32_e32 v43, 1.0, v43
	v_rcp_f32_e32 v40, v40
	v_rcp_f32_e32 v41, v41
	v_rcp_f32_e32 v42, v42
	v_rcp_f32_e32 v43, v43
	v_lshlrev_b32_e32 v224, 16, v166
	v_and_b32_e32 v225, 0xffff0000, v166
	v_lshlrev_b32_e32 v226, 16, v167
	v_and_b32_e32 v227, 0xffff0000, v167
	v_lshlrev_b32_e32 v228, 16, v178
	v_and_b32_e32 v229, 0xffff0000, v178
	v_lshlrev_b32_e32 v230, 16, v179
	v_and_b32_e32 v231, 0xffff0000, v179
	v_fma_f32 v40, v40, v228, v224
	v_fma_f32 v41, v41, v229, v225
	v_fma_f32 v42, v42, v230, v226
	v_fma_f32 v43, v43, v231, v227
	v_mul_f32_e32 v232, v41, v41
	v_mul_f32_e32 v233, v43, v43
	v_fmac_f32_e32 v232, v40, v40
	v_fmac_f32_e32 v233, v42, v42
	v_add_f32_e32 v235, v232, v233
	v_cvt_pk_bf16_f32 v44, v44, v45
	v_cvt_pk_bf16_f32 v45, v46, v47
	v_cvt_pk_bf16_f32 v46, v40, v41
	v_cvt_pk_bf16_f32 v47, v42, v43
	v_add_u32_e32 v250, 0x48000, v172
	global_store_dwordx4 v250, v[44:47], s[0:1] nt
	v_mul_f32_e32 v36, v36, v253
	v_mul_f32_e32 v37, v37, v253
	v_mul_f32_e32 v38, v38, v253
	v_mul_f32_e32 v39, v39, v253
	v_exp_f32_e32 v36, v36
	v_exp_f32_e32 v37, v37
	v_exp_f32_e32 v38, v38
	v_exp_f32_e32 v39, v39
	v_add_f32_e32 v36, 1.0, v36
	v_add_f32_e32 v37, 1.0, v37
	v_add_f32_e32 v38, 1.0, v38
	v_add_f32_e32 v39, 1.0, v39
	v_rcp_f32_e32 v36, v36
	v_rcp_f32_e32 v37, v37
	v_rcp_f32_e32 v38, v38
	v_rcp_f32_e32 v39, v39
	v_lshlrev_b32_e32 v224, 16, v168
	v_and_b32_e32 v225, 0xffff0000, v168
	v_lshlrev_b32_e32 v226, 16, v169
	v_and_b32_e32 v227, 0xffff0000, v169
	v_lshlrev_b32_e32 v228, 16, v180
	v_and_b32_e32 v229, 0xffff0000, v180
	v_lshlrev_b32_e32 v230, 16, v181
	v_and_b32_e32 v231, 0xffff0000, v181
	v_fma_f32 v36, v36, v228, v224
	v_fma_f32 v37, v37, v229, v225
	v_fma_f32 v38, v38, v230, v226
	v_fma_f32 v39, v39, v231, v227
	v_mul_f32_e32 v232, v37, v37
	v_mul_f32_e32 v233, v39, v39
	v_fmac_f32_e32 v232, v36, v36
	v_fmac_f32_e32 v233, v38, v38
	v_add_f32_e32 v248, v232, v233
	v_mul_f32_e32 v32, v32, v253
	v_mul_f32_e32 v33, v33, v253
	v_mul_f32_e32 v34, v34, v253
	v_mul_f32_e32 v35, v35, v253
	v_exp_f32_e32 v32, v32
	v_exp_f32_e32 v33, v33
	v_exp_f32_e32 v34, v34
	v_exp_f32_e32 v35, v35
	v_add_f32_e32 v32, 1.0, v32
	v_add_f32_e32 v33, 1.0, v33
	v_add_f32_e32 v34, 1.0, v34
	v_add_f32_e32 v35, 1.0, v35
	v_rcp_f32_e32 v32, v32
	v_rcp_f32_e32 v33, v33
	v_rcp_f32_e32 v34, v34
	v_rcp_f32_e32 v35, v35
	v_lshlrev_b32_e32 v224, 16, v170
	v_and_b32_e32 v225, 0xffff0000, v170
	v_lshlrev_b32_e32 v226, 16, v171
	v_and_b32_e32 v227, 0xffff0000, v171
	v_lshlrev_b32_e32 v228, 16, v182
	v_and_b32_e32 v229, 0xffff0000, v182
	v_lshlrev_b32_e32 v230, 16, v183
	v_and_b32_e32 v231, 0xffff0000, v183
	v_fma_f32 v32, v32, v228, v224
	v_fma_f32 v33, v33, v229, v225
	v_fma_f32 v34, v34, v230, v226
	v_fma_f32 v35, v35, v231, v227
	v_mul_f32_e32 v232, v33, v33
	v_mul_f32_e32 v233, v35, v35
	v_fmac_f32_e32 v232, v32, v32
	v_fmac_f32_e32 v233, v34, v34
	v_add_f32_e32 v249, v232, v233
	v_cvt_pk_bf16_f32 v36, v36, v37
	v_cvt_pk_bf16_f32 v37, v38, v39
	v_cvt_pk_bf16_f32 v38, v32, v33
	v_cvt_pk_bf16_f32 v39, v34, v35
	global_store_dwordx4 v250, v[36:39], s[0:1] offset:256 nt
	v_add_f32_e32 v234, v234, v235
	v_add_f32_e32 v248, v248, v249
	v_add_f32_e32 v247, v234, v248
	ds_bpermute_b32 v252, v236, v247
	v_add_u32_e32 v251, 0x2400, v194
	s_waitcnt lgkmcnt(0)
	v_add_f32_e32 v247, v247, v252
	ds_bpermute_b32 v252, v237, v247
	s_waitcnt lgkmcnt(0)
	v_add_f32_e32 v247, v247, v252
	s_and_saveexec_b64 s[28:29], vcc
	global_store_dword v251, v247, s[12:13]
	s_or_b64 exec, exec, s[28:29]
	s_waitcnt vmcnt(17)
	v_add_f32_e32 v247, v108, v109
	v_add_f32_e32 v252, v110, v111
	v_add_f32_e32 v247, v247, v252
	ds_bpermute_b32 v252, v236, v247
	s_waitcnt lgkmcnt(0)
	v_add_f32_e32 v247, v247, v252
	ds_bpermute_b32 v252, v237, v247
	s_waitcnt lgkmcnt(0)
; __device__ __forceinline__ u32x4 pack8(const f32x4 v0, const f32x4 v1) { u32x4 w; w.x = cvt_pk_bf16(v0[0], v0[1]); w.y = cvt_pk_bf16(v0[2], v0[3]); w.z = cvt_pk_bf16(v1[0], v1[1]); w.w = cvt_pk_bf16(v1[2], v1[3]); return w; }
; __device__ __forceinline__ float sumsq8(const f32x4 a, const f32x4 b) { return ((a[0] * a[0] + a[1] * a[1]) + (a[2] * a[2] + a[3] * a[3])) + ((b[0] * b[0] + b[1] * b[1]) + (b[2] * b[2] + b[3] * b[3])); }
; __device__ __forceinline__ void unpack8(const u32x4 w, f32x4& a, f32x4& b) { a = (f32x4){bf_lo(w.x), bf_hi(w.x), bf_lo(w.y), bf_hi(w.y)}; b = (f32x4){bf_lo(w.z), bf_hi(w.z), bf_lo(w.w), bf_hi(w.w)}; }
;     __device__ __forceinline__ void operator()(const f32x4 (&acc)[2][2][4][2], const Unit& u, int wr, int wc, int fr, int fq) const {
;     ...
;             for (int mm = 0; mm < 2; ++mm) { const int rowl = row0 + ai * HALF + (2 * mh + mm) * 16; p[mm] = *(const f32x4*)(ssq_in + (size_t)rowl * 16 + 4 * fq);
; #pragma unroll
;                 for (int bj = 0; bj < 2; ++bj) { const size_t off = (size_t)rowl * DMODEL + col0 + bj * HALF; rv[mm][bj] = *(const u32x4*)(Rin + off); pw[mm][bj] = *(const u32x4*)(PP + off); } }
; #pragma unroll
;             for (int mm = 0; mm < 2; ++mm) { const int m = 2 * mh + mm; const int row = row0 + ai * HALF + m * 16; float part = 0.f;
;                 float sr = (p[mm][0] + p[mm][1]) + (p[mm][2] + p[mm][3]); sr += __shfl_xor(sr, 16); sr += __shfl_xor(sr, 32); const float r = __builtin_amdgcn_rsqf(sr * (1.0f / DMODEL) + RMS_EPS);
; #pragma unroll
;                 for (int bj = 0; bj < 2; ++bj) { f32x4 r0, r1, p0, p1; unpack8(rv[mm][bj], r0, r1); unpack8(pw[mm][bj], p0, p1);
;                     f32x4 g0 = acc[ai][bj][m][0] * r, g1 = acc[ai][bj][m][1] * r;
; #pragma unroll
;                     for (int e = 0; e < 4; ++e) { g0[e] = __builtin_amdgcn_rcpf(1.f + __builtin_amdgcn_exp2f(-1.4426950408889634f * g0[e])); g1[e] = __builtin_amdgcn_rcpf(1.f + __builtin_amdgcn_exp2f(-1.4426950408889634f * g1[e])); }
;                     const f32x4 h0 = r0 + g0 * p0, h1 = r1 + g1 * p1; part += sumsq8(h0, h1);
;                     *(u32x4*)(XBo + (size_t)row * DMODEL + col0 + bj * HALF) = pack8(h0, h1); }
;                 part += __shfl_xor(part, 16); part += __shfl_xor(part, 32);
;                 if (fq == 0) ssq_out[(size_t)row * 16 + u.pn * 4 + wc] = part; }
	v_add_f32_e32 v247, v247, v252
	v_fmamk_f32 v247, v247, 0x3a800000, v193
	v_rsq_f32_e32 v247, v247
	s_nop 0
	v_mul_f32_e32 v253, 0xbfb8aa3b, v247
	v_mul_f32_e32 v28, v28, v253
	v_mul_f32_e32 v29, v29, v253
	v_mul_f32_e32 v30, v30, v253
	v_mul_f32_e32 v31, v31, v253
	v_exp_f32_e32 v28, v28
	v_exp_f32_e32 v29, v29
	v_exp_f32_e32 v30, v30
	v_exp_f32_e32 v31, v31
	v_add_f32_e32 v28, 1.0, v28
	v_add_f32_e32 v29, 1.0, v29
	v_add_f32_e32 v30, 1.0, v30
	v_add_f32_e32 v31, 1.0, v31
	v_rcp_f32_e32 v28, v28
	v_rcp_f32_e32 v29, v29
	v_rcp_f32_e32 v30, v30
	v_rcp_f32_e32 v31, v31
	v_lshlrev_b32_e32 v224, 16, v104
	v_and_b32_e32 v225, 0xffff0000, v104
	v_lshlrev_b32_e32 v226, 16, v105
	v_and_b32_e32 v227, 0xffff0000, v105
	v_lshlrev_b32_e32 v228, 16, v96
	v_and_b32_e32 v229, 0xffff0000, v96
	v_lshlrev_b32_e32 v230, 16, v97
	v_and_b32_e32 v231, 0xffff0000, v97
	v_fma_f32 v28, v28, v228, v224
	v_fma_f32 v29, v29, v229, v225
	v_fma_f32 v30, v30, v230, v226
	v_fma_f32 v31, v31, v231, v227
	v_mul_f32_e32 v232, v29, v29
	v_mul_f32_e32 v233, v31, v31
	v_fmac_f32_e32 v232, v28, v28
	v_fmac_f32_e32 v233, v30, v30
	v_add_f32_e32 v234, v232, v233
	v_mul_f32_e32 v24, v24, v253
	v_mul_f32_e32 v25, v25, v253
	v_mul_f32_e32 v26, v26, v253
	v_mul_f32_e32 v27, v27, v253
	v_exp_f32_e32 v24, v24
	v_exp_f32_e32 v25, v25
	v_exp_f32_e32 v26, v26
	v_exp_f32_e32 v27, v27
	v_add_f32_e32 v24, 1.0, v24
	v_add_f32_e32 v25, 1.0, v25
	v_add_f32_e32 v26, 1.0, v26
	v_add_f32_e32 v27, 1.0, v27
	v_rcp_f32_e32 v24, v24
	v_rcp_f32_e32 v25, v25
	v_rcp_f32_e32 v26, v26
	v_rcp_f32_e32 v27, v27
	v_lshlrev_b32_e32 v224, 16, v106
	v_and_b32_e32 v225, 0xffff0000, v106
	v_lshlrev_b32_e32 v226, 16, v107
	v_and_b32_e32 v227, 0xffff0000, v107
	v_lshlrev_b32_e32 v228, 16, v98
	v_and_b32_e32 v229, 0xffff0000, v98
	v_lshlrev_b32_e32 v230, 16, v99
	v_and_b32_e32 v231, 0xffff0000, v99
	v_fma_f32 v24, v24, v228, v224
	v_fma_f32 v25, v25, v229, v225
	v_fma_f32 v26, v26, v230, v226
	v_fma_f32 v27, v27, v231, v227
	v_mul_f32_e32 v232, v25, v25
	v_mul_f32_e32 v233, v27, v27
	v_fmac_f32_e32 v232, v24, v24
	v_fmac_f32_e32 v233, v26, v26
	v_add_f32_e32 v235, v232, v233
	v_cvt_pk_bf16_f32 v28, v28, v29
	v_cvt_pk_bf16_f32 v29, v30, v31
	v_cvt_pk_bf16_f32 v30, v24, v25
	v_cvt_pk_bf16_f32 v31, v26, v27
	v_add_u32_e32 v250, 0x50000, v172
	global_store_dwordx4 v250, v[28:31], s[0:1] nt
	v_mul_f32_e32 v20, v20, v253
	v_mul_f32_e32 v21, v21, v253
	v_mul_f32_e32 v22, v22, v253
	v_mul_f32_e32 v23, v23, v253
	v_exp_f32_e32 v20, v20
	v_exp_f32_e32 v21, v21
	v_exp_f32_e32 v22, v22
	v_exp_f32_e32 v23, v23
	v_add_f32_e32 v20, 1.0, v20
	v_add_f32_e32 v21, 1.0, v21
	v_add_f32_e32 v22, 1.0, v22
	v_add_f32_e32 v23, 1.0, v23
	v_rcp_f32_e32 v20, v20
	v_rcp_f32_e32 v21, v21
	v_rcp_f32_e32 v22, v22
	v_rcp_f32_e32 v23, v23
	v_lshlrev_b32_e32 v224, 16, v100
	v_and_b32_e32 v225, 0xffff0000, v100
	v_lshlrev_b32_e32 v226, 16, v101
	v_and_b32_e32 v227, 0xffff0000, v101
	v_lshlrev_b32_e32 v228, 16, v220
	v_and_b32_e32 v229, 0xffff0000, v220
	v_lshlrev_b32_e32 v230, 16, v221
	v_and_b32_e32 v231, 0xffff0000, v221
	v_fma_f32 v20, v20, v228, v224
	v_fma_f32 v21, v21, v229, v225
	v_fma_f32 v22, v22, v230, v226
	v_fma_f32 v23, v23, v231, v227
	v_mul_f32_e32 v232, v21, v21
	v_mul_f32_e32 v233, v23, v23
	v_fmac_f32_e32 v232, v20, v20
	v_fmac_f32_e32 v233, v22, v22
	v_add_f32_e32 v248, v232, v233
	v_mul_f32_e32 v16, v16, v253
	v_mul_f32_e32 v17, v17, v253
	v_mul_f32_e32 v18, v18, v253
	v_mul_f32_e32 v19, v19, v253
	v_exp_f32_e32 v16, v16
	v_exp_f32_e32 v17, v17
	v_exp_f32_e32 v18, v18
	v_exp_f32_e32 v19, v19
	v_add_f32_e32 v16, 1.0, v16
	v_add_f32_e32 v17, 1.0, v17
	v_add_f32_e32 v18, 1.0, v18
	v_add_f32_e32 v19, 1.0, v19
	v_rcp_f32_e32 v16, v16
	v_rcp_f32_e32 v17, v17
	v_rcp_f32_e32 v18, v18
	v_rcp_f32_e32 v19, v19
	v_lshlrev_b32_e32 v224, 16, v102
	v_and_b32_e32 v225, 0xffff0000, v102
	v_lshlrev_b32_e32 v226, 16, v103
	v_and_b32_e32 v227, 0xffff0000, v103
	v_lshlrev_b32_e32 v228, 16, v222
	v_and_b32_e32 v229, 0xffff0000, v222
	v_lshlrev_b32_e32 v230, 16, v223
	v_and_b32_e32 v231, 0xffff0000, v223
	v_fma_f32 v16, v16, v228, v224
	v_fma_f32 v17, v17, v229, v225
	v_fma_f32 v18, v18, v230, v226
	v_fma_f32 v19, v19, v231, v227
	v_mul_f32_e32 v232, v17, v17
	v_mul_f32_e32 v233, v19, v19
	v_fmac_f32_e32 v232, v16, v16
	v_fmac_f32_e32 v233, v18, v18
	v_add_f32_e32 v249, v232, v233
	v_cvt_pk_bf16_f32 v20, v20, v21
	v_cvt_pk_bf16_f32 v21, v22, v23
	v_cvt_pk_bf16_f32 v22, v16, v17
	v_cvt_pk_bf16_f32 v23, v18, v19
	global_store_dwordx4 v250, v[20:23], s[0:1] offset:256 nt
	v_add_f32_e32 v234, v234, v235
	v_add_f32_e32 v248, v248, v249
	v_add_f32_e32 v247, v234, v248
	ds_bpermute_b32 v252, v236, v247
	v_add_u32_e32 v251, 0x2800, v194
	s_waitcnt lgkmcnt(0)
	v_add_f32_e32 v247, v247, v252
	ds_bpermute_b32 v252, v237, v247
	s_waitcnt lgkmcnt(0)
	v_add_f32_e32 v247, v247, v252
	s_and_saveexec_b64 s[28:29], vcc
	global_store_dword v251, v247, s[12:13]
	s_or_b64 exec, exec, s[28:29]
	s_waitcnt vmcnt(12)
	v_add_f32_e32 v247, v184, v185
	v_add_f32_e32 v252, v186, v187
	v_add_f32_e32 v247, v247, v252
	ds_bpermute_b32 v252, v236, v247
	s_waitcnt lgkmcnt(0)
; __device__ __forceinline__ u32x4 pack8(const f32x4 v0, const f32x4 v1) { u32x4 w; w.x = cvt_pk_bf16(v0[0], v0[1]); w.y = cvt_pk_bf16(v0[2], v0[3]); w.z = cvt_pk_bf16(v1[0], v1[1]); w.w = cvt_pk_bf16(v1[2], v1[3]); return w; }
; __device__ __forceinline__ float sumsq8(const f32x4 a, const f32x4 b) { return ((a[0] * a[0] + a[1] * a[1]) + (a[2] * a[2] + a[3] * a[3])) + ((b[0] * b[0] + b[1] * b[1]) + (b[2] * b[2] + b[3] * b[3])); }
; __device__ __forceinline__ void unpack8(const u32x4 w, f32x4& a, f32x4& b) { a = (f32x4){bf_lo(w.x), bf_hi(w.x), bf_lo(w.y), bf_hi(w.y)}; b = (f32x4){bf_lo(w.z), bf_hi(w.z), bf_lo(w.w), bf_hi(w.w)}; }
;     __device__ __forceinline__ void operator()(const f32x4 (&acc)[2][2][4][2], const Unit& u, int wr, int wc, int fr, int fq) const {
;     ...
;             for (int mm = 0; mm < 2; ++mm) { const int rowl = row0 + ai * HALF + (2 * mh + mm) * 16; p[mm] = *(const f32x4*)(ssq_in + (size_t)rowl * 16 + 4 * fq);
; #pragma unroll
;                 for (int bj = 0; bj < 2; ++bj) { const size_t off = (size_t)rowl * DMODEL + col0 + bj * HALF; rv[mm][bj] = *(const u32x4*)(Rin + off); pw[mm][bj] = *(const u32x4*)(PP + off); } }
; #pragma unroll
;             for (int mm = 0; mm < 2; ++mm) { const int m = 2 * mh + mm; const int row = row0 + ai * HALF + m * 16; float part = 0.f;
;                 float sr = (p[mm][0] + p[mm][1]) + (p[mm][2] + p[mm][3]); sr += __shfl_xor(sr, 16); sr += __shfl_xor(sr, 32); const float r = __builtin_amdgcn_rsqf(sr * (1.0f / DMODEL) + RMS_EPS);
; #pragma unroll
;                 for (int bj = 0; bj < 2; ++bj) { f32x4 r0, r1, p0, p1; unpack8(rv[mm][bj], r0, r1); unpack8(pw[mm][bj], p0, p1);
;                     f32x4 g0 = acc[ai][bj][m][0] * r, g1 = acc[ai][bj][m][1] * r;
; #pragma unroll
;                     for (int e = 0; e < 4; ++e) { g0[e] = __builtin_amdgcn_rcpf(1.f + __builtin_amdgcn_exp2f(-1.4426950408889634f * g0[e])); g1[e] = __builtin_amdgcn_rcpf(1.f + __builtin_amdgcn_exp2f(-1.4426950408889634f * g1[e])); }
;                     const f32x4 h0 = r0 + g0 * p0, h1 = r1 + g1 * p1; part += sumsq8(h0, h1);
;                     *(u32x4*)(XBo + (size_t)row * DMODEL + col0 + bj * HALF) = pack8(h0, h1); }
;                 part += __shfl_xor(part, 16); part += __shfl_xor(part, 32);
;                 if (fq == 0) ssq_out[(size_t)row * 16 + u.pn * 4 + wc] = part; }
	v_add_f32_e32 v247, v247, v252
	ds_bpermute_b32 v252, v237, v247
	s_waitcnt lgkmcnt(0)
	v_add_f32_e32 v247, v247, v252
	v_fmamk_f32 v247, v247, 0x3a800000, v193
	v_rsq_f32_e32 v247, v247
	s_nop 0
	v_mul_f32_e32 v253, 0xbfb8aa3b, v247
	v_mul_f32_e32 v12, v12, v253
	v_mul_f32_e32 v13, v13, v253
	v_mul_f32_e32 v14, v14, v253
	v_mul_f32_e32 v15, v15, v253
	v_exp_f32_e32 v12, v12
	v_exp_f32_e32 v13, v13
	v_exp_f32_e32 v14, v14
	v_exp_f32_e32 v15, v15
	v_add_f32_e32 v12, 1.0, v12
	v_add_f32_e32 v13, 1.0, v13
	v_add_f32_e32 v14, 1.0, v14
	v_add_f32_e32 v15, 1.0, v15
	v_rcp_f32_e32 v12, v12
	v_rcp_f32_e32 v13, v13
	v_rcp_f32_e32 v14, v14
	v_rcp_f32_e32 v15, v15
	v_lshlrev_b32_e32 v224, 16, v188
	v_and_b32_e32 v225, 0xffff0000, v188
	v_lshlrev_b32_e32 v226, 16, v189
	v_and_b32_e32 v227, 0xffff0000, v189
	v_lshlrev_b32_e32 v228, 16, v208
	v_and_b32_e32 v229, 0xffff0000, v208
	v_lshlrev_b32_e32 v230, 16, v209
	v_and_b32_e32 v231, 0xffff0000, v209
	v_fma_f32 v12, v12, v228, v224
	v_fma_f32 v13, v13, v229, v225
	v_fma_f32 v14, v14, v230, v226
	v_fma_f32 v15, v15, v231, v227
	v_mul_f32_e32 v232, v13, v13
	v_mul_f32_e32 v233, v15, v15
	v_fmac_f32_e32 v232, v12, v12
	v_fmac_f32_e32 v233, v14, v14
	v_add_f32_e32 v234, v232, v233
	v_mul_f32_e32 v8, v8, v253
	v_mul_f32_e32 v9, v9, v253
	v_mul_f32_e32 v10, v10, v253
	v_mul_f32_e32 v11, v11, v253
	v_exp_f32_e32 v8, v8
	v_exp_f32_e32 v9, v9
	v_exp_f32_e32 v10, v10
	v_exp_f32_e32 v11, v11
	v_add_f32_e32 v8, 1.0, v8
	v_add_f32_e32 v9, 1.0, v9
	v_add_f32_e32 v10, 1.0, v10
	v_add_f32_e32 v11, 1.0, v11
	v_rcp_f32_e32 v8, v8
	v_rcp_f32_e32 v9, v9
	v_rcp_f32_e32 v10, v10
	v_rcp_f32_e32 v11, v11
	v_lshlrev_b32_e32 v224, 16, v190
	v_and_b32_e32 v225, 0xffff0000, v190
	v_lshlrev_b32_e32 v226, 16, v191
	v_and_b32_e32 v227, 0xffff0000, v191
	v_lshlrev_b32_e32 v228, 16, v210
	v_and_b32_e32 v229, 0xffff0000, v210
	v_lshlrev_b32_e32 v230, 16, v211
	v_and_b32_e32 v231, 0xffff0000, v211
	v_fma_f32 v8, v8, v228, v224
	v_fma_f32 v9, v9, v229, v225
	v_fma_f32 v10, v10, v230, v226
	v_fma_f32 v11, v11, v231, v227
	v_mul_f32_e32 v232, v9, v9
	v_mul_f32_e32 v233, v11, v11
	v_fmac_f32_e32 v232, v8, v8
	v_fmac_f32_e32 v233, v10, v10
	v_add_f32_e32 v235, v232, v233
	v_cvt_pk_bf16_f32 v12, v12, v13
	v_cvt_pk_bf16_f32 v13, v14, v15
	v_cvt_pk_bf16_f32 v14, v8, v9
	v_cvt_pk_bf16_f32 v15, v10, v11
	v_add_u32_e32 v250, 0x58000, v172
	global_store_dwordx4 v250, v[12:15], s[0:1] nt
	v_mul_f32_e32 v4, v4, v253
	v_mul_f32_e32 v5, v5, v253
	v_mul_f32_e32 v6, v6, v253
	v_mul_f32_e32 v7, v7, v253
	v_exp_f32_e32 v4, v4
	v_exp_f32_e32 v5, v5
	v_exp_f32_e32 v6, v6
	v_exp_f32_e32 v7, v7
	v_add_f32_e32 v4, 1.0, v4
	v_add_f32_e32 v5, 1.0, v5
	v_add_f32_e32 v6, 1.0, v6
	v_add_f32_e32 v7, 1.0, v7
	v_rcp_f32_e32 v4, v4
	v_rcp_f32_e32 v5, v5
	v_rcp_f32_e32 v6, v6
	v_rcp_f32_e32 v7, v7
	v_lshlrev_b32_e32 v224, 16, v204
	v_and_b32_e32 v225, 0xffff0000, v204
	v_lshlrev_b32_e32 v226, 16, v205
	v_and_b32_e32 v227, 0xffff0000, v205
	v_lshlrev_b32_e32 v228, 16, v212
	v_and_b32_e32 v229, 0xffff0000, v212
	v_lshlrev_b32_e32 v230, 16, v213
	v_and_b32_e32 v231, 0xffff0000, v213
	v_fma_f32 v4, v4, v228, v224
	v_fma_f32 v5, v5, v229, v225
	v_fma_f32 v6, v6, v230, v226
	v_fma_f32 v7, v7, v231, v227
	v_mul_f32_e32 v232, v5, v5
	v_mul_f32_e32 v233, v7, v7
	v_fmac_f32_e32 v232, v4, v4
	v_fmac_f32_e32 v233, v6, v6
	v_add_f32_e32 v248, v232, v233
	v_mul_f32_e32 v0, v0, v253
	v_mul_f32_e32 v1, v1, v253
	v_mul_f32_e32 v2, v2, v253
	v_mul_f32_e32 v3, v3, v253
	v_exp_f32_e32 v0, v0
	v_exp_f32_e32 v1, v1
	v_exp_f32_e32 v2, v2
	v_exp_f32_e32 v3, v3
	v_add_f32_e32 v0, 1.0, v0
	v_add_f32_e32 v1, 1.0, v1
	v_add_f32_e32 v2, 1.0, v2
	v_add_f32_e32 v3, 1.0, v3
	v_rcp_f32_e32 v0, v0
	v_rcp_f32_e32 v1, v1
	v_rcp_f32_e32 v2, v2
	v_rcp_f32_e32 v3, v3
	v_lshlrev_b32_e32 v224, 16, v206
	v_and_b32_e32 v225, 0xffff0000, v206
	v_lshlrev_b32_e32 v226, 16, v207
	v_and_b32_e32 v227, 0xffff0000, v207
	v_lshlrev_b32_e32 v228, 16, v214
	v_and_b32_e32 v229, 0xffff0000, v214
	v_lshlrev_b32_e32 v230, 16, v215
	v_and_b32_e32 v231, 0xffff0000, v215
	v_fma_f32 v0, v0, v228, v224
	v_fma_f32 v1, v1, v229, v225
	v_fma_f32 v2, v2, v230, v226
	v_fma_f32 v3, v3, v231, v227
	v_mul_f32_e32 v232, v1, v1
	v_mul_f32_e32 v233, v3, v3
	v_fmac_f32_e32 v232, v0, v0
	v_fmac_f32_e32 v233, v2, v2
	v_add_f32_e32 v249, v232, v233
	v_cvt_pk_bf16_f32 v4, v4, v5
	v_cvt_pk_bf16_f32 v5, v6, v7
	v_cvt_pk_bf16_f32 v6, v0, v1
	v_cvt_pk_bf16_f32 v7, v2, v3
	global_store_dwordx4 v250, v[4:7], s[0:1] offset:256 nt
	v_add_f32_e32 v234, v234, v235
	v_add_f32_e32 v248, v248, v249
	v_add_f32_e32 v247, v234, v248
	ds_bpermute_b32 v252, v236, v247
	v_add_u32_e32 v251, 0x2c00, v194
	s_waitcnt lgkmcnt(0)
	v_add_f32_e32 v247, v247, v252
	ds_bpermute_b32 v252, v237, v247
	s_waitcnt lgkmcnt(0)
	v_add_f32_e32 v247, v247, v252
	s_and_saveexec_b64 s[28:29], vcc
	global_store_dword v251, v247, s[12:13]
	s_or_b64 exec, exec, s[28:29]
	s_mov_b64 s[62:63], -1
	s_andn2_b64 vcc, exec, s[20:21]
	s_mov_b64 s[20:21], -1
	s_cbranch_vccnz .LBB0_1123
	s_andn2_b64 vcc, exec, s[8:9]
	s_cbranch_vccnz .LBB0_1122
	s_barrier
	s_branch .LBB0_1122
